# v26 + code placement (9.3): 25 four-byte s_nop pads so that every 32-MFMA segment of the ten GEMM K-loops starts at an address = 0 mod 8
# speedup vs baseline: 1.0060x; 1.0044x over previous
; #define PG8_STAGE(bufoff, gbase, voff) do { _Pragma("unroll") for (int _i = 0; _i < 2; ++_i) \
;         __builtin_amdgcn_global_load_lds((const unsigned*)((const char*)(gbase) + (voff)[_i]), (LAS unsigned*)(lds + (bufoff) + ldsw + _i * 8192), 16, 0, 0); } while (0)
; #define PG8_LDA(dst, b, h) do { _Pragma("unroll") for (int m = 0; m < 4; ++m) _Pragma("unroll") for (int k = 0; k < 2; ++k) dst[m][k] = *(const LAS bf16x8*)(lds + PG8_SA(b, h) + aoff + m * 2048 + k * 1024); } while (0)
; #define PG8_LDB(dst, b, h) do { _Pragma("unroll") for (int n = 0; n < 2; ++n) _Pragma("unroll") for (int k = 0; k < 2; ++k) dst[n][k] = *(const LAS bf16x8*)(lds + PG8_SB(b, h) + boff + n * 2048 + k * 1024); } while (0)
; #define PG8_MMA(ai, bj, At, Bt) do { __builtin_amdgcn_s_setprio(1); _Pragma("unroll") for (int m = 0; m < 4; ++m) _Pragma("unroll") for (int n = 0; n < 2; ++n) _Pragma("unroll") for (int k = 0; k < 2; ++k) \
;         acc[ai][bj][m][n] = __builtin_amdgcn_mfma_f32_16x16x32_bf16(Bt[n][k], At[m][k], acc[ai][bj][m][n], 0, 0, 0); __builtin_amdgcn_s_setprio(0); } while (0)
; #define PG8_WAIT_V(n) asm volatile("s_waitcnt vmcnt(" #n ")" ::: "memory")
; #define PG8_WAIT_L(n) asm volatile("s_waitcnt lgkmcnt(" #n ")" ::: "memory")
; #define PG8_BAR __builtin_amdgcn_s_barrier()
; #define PG8_SCHED __builtin_amdgcn_sched_barrier(0)
; template <class Epi, class Sched>
; __device__ __forceinline__ void gemm_phase(int wv, LAS unsigned char* lds, const Gemm g, const Sched& S, const Epi& E) {
;     ...
;         for (int t = 0; t < nt; t += 2) {
;             const bool last = (t == nt - 2);
;             const char* a1 = cA + (size_t)(t + 1) * kstep;
;             const char* a2 = last ? nA : cA + (size_t)(t + 2) * kstep; const char* b2 = last ? nB : cB + (size_t)(t + 2) * kstep;
;             const char* a3 = a2 + kstep; const char* b3 = b2 + kstep;
;             PG8_LDB(B0, 0, 0); PG8_LDB(B1, 0, 1); PG8_SCHED; PG8_LDA(At, 0, 0); PG8_STAGE(PG8_SA(1, 1), a1 + hstep, voffA);
;             PG8_WAIT_V(8); PG8_WAIT_L(0); PG8_BAR; PG8_MMA(0, 0, At, B0); PG8_MMA(0, 1, At, B1); PG8_BAR; PG8_SCHED;
;             PG8_LDA(At, 0, 1); PG8_STAGE(PG8_SB(0, 0), b2, voffB); PG8_STAGE(PG8_SB(0, 1), b2 + hstepB, voffB); PG8_STAGE(PG8_SA(0, 0), a2, voffA);
;             PG8_WAIT_V(8); PG8_WAIT_L(0); PG8_BAR; PG8_MMA(1, 0, At, B0); PG8_MMA(1, 1, At, B1); PG8_BAR; PG8_SCHED;
.LBB0_178:
	s_add_u32 s20, s18, 0xfffc0080
	s_addc_u32 s21, s19, -1
	s_add_i32 s47, 0, 0x10000
	s_cmp_eq_u32 s46, 12
	s_cselect_b32 s23, s11, s21
	s_cselect_b32 s22, s41, s20
	s_cselect_b32 s21, s13, s45
	s_cselect_b32 s20, s42, s43
	s_add_i32 s50, 0, 0x14000
	v_add_u32_e32 v154, s47, v143
	v_add_u32_e32 v170, s50, v143
	ds_read_b128 v[138:141], v154
	ds_read_b128 v[146:149], v154 offset:1024
	ds_read_b128 v[150:153], v154 offset:2048
	ds_read_b128 v[154:157], v154 offset:3072
	ds_read_b128 v[158:161], v170
	ds_read_b128 v[162:165], v170 offset:1024
	ds_read_b128 v[166:169], v170 offset:2048
	ds_read_b128 v[170:173], v170 offset:3072
	v_lshl_add_u64 v[186:187], s[18:19], 0, v[134:135]
	s_add_i32 m0, s29, 0xc000
	ds_read_b128 v[174:177], v145
	ds_read_b128 v[178:181], v145 offset:1024
	ds_read_b128 v[182:185], v145 offset:2048
	ds_read_b128 v[198:201], v145 offset:3072
	ds_read_b128 v[202:205], v145 offset:4096
	ds_read_b128 v[206:209], v145 offset:5120
	ds_read_b128 v[210:213], v145 offset:6144
	ds_read_b128 v[214:217], v145 offset:7168
	global_load_lds_dwordx4 v[186:187], off
	v_lshl_add_u64 v[186:187], s[18:19], 0, v[136:137]
	s_add_i32 m0, s29, 0xe000
	s_nop 0
	global_load_lds_dwordx4 v[186:187], off
	s_waitcnt vmcnt(8)
	s_waitcnt lgkmcnt(0)
	s_barrier
	s_setprio 1
	s_waitcnt lgkmcnt(0)
	v_mfma_f32_16x16x32_bf16 v[124:127], v[138:141], v[174:177], v[124:127]
	v_mfma_f32_16x16x32_bf16 v[120:123], v[150:153], v[174:177], v[120:123]
	v_mfma_f32_16x16x32_bf16 v[108:111], v[138:141], v[182:185], v[108:111]
	v_mfma_f32_16x16x32_bf16 v[100:103], v[150:153], v[182:185], v[100:103]
	v_mfma_f32_16x16x32_bf16 v[92:95], v[138:141], v[202:205], v[92:95]
	v_mfma_f32_16x16x32_bf16 v[84:87], v[150:153], v[202:205], v[84:87]
	v_mfma_f32_16x16x32_bf16 v[76:79], v[138:141], v[210:213], v[76:79]
	v_mfma_f32_16x16x32_bf16 v[68:71], v[150:153], v[210:213], v[68:71]
	v_mfma_f32_16x16x32_bf16 v[124:127], v[146:149], v[178:181], v[124:127]
	v_mfma_f32_16x16x32_bf16 v[120:123], v[154:157], v[178:181], v[120:123]
	v_mfma_f32_16x16x32_bf16 v[108:111], v[146:149], v[198:201], v[108:111]
	v_mfma_f32_16x16x32_bf16 v[100:103], v[154:157], v[198:201], v[100:103]
	v_mfma_f32_16x16x32_bf16 v[92:95], v[146:149], v[206:209], v[92:95]
	v_mfma_f32_16x16x32_bf16 v[84:87], v[154:157], v[206:209], v[84:87]
	v_mfma_f32_16x16x32_bf16 v[76:79], v[146:149], v[214:217], v[76:79]
	v_mfma_f32_16x16x32_bf16 v[68:71], v[154:157], v[214:217], v[68:71]
	s_setprio 0
	s_setprio 1
	v_mfma_f32_16x16x32_bf16 v[116:119], v[158:161], v[174:177], v[116:119]
	v_mfma_f32_16x16x32_bf16 v[112:115], v[166:169], v[174:177], v[112:115]
	v_mfma_f32_16x16x32_bf16 v[104:107], v[158:161], v[182:185], v[104:107]
	v_mfma_f32_16x16x32_bf16 v[96:99], v[166:169], v[182:185], v[96:99]
	v_mfma_f32_16x16x32_bf16 v[88:91], v[158:161], v[202:205], v[88:91]
	v_mfma_f32_16x16x32_bf16 v[80:83], v[166:169], v[202:205], v[80:83]
	v_mfma_f32_16x16x32_bf16 v[72:75], v[158:161], v[210:213], v[72:75]
	v_mfma_f32_16x16x32_bf16 v[64:67], v[166:169], v[210:213], v[64:67]
	v_mfma_f32_16x16x32_bf16 v[116:119], v[162:165], v[178:181], v[116:119]
	v_mfma_f32_16x16x32_bf16 v[112:115], v[170:173], v[178:181], v[112:115]
	v_mfma_f32_16x16x32_bf16 v[104:107], v[162:165], v[198:201], v[104:107]
	v_mfma_f32_16x16x32_bf16 v[96:99], v[170:173], v[198:201], v[96:99]
	v_mfma_f32_16x16x32_bf16 v[88:91], v[162:165], v[206:209], v[88:91]
	v_mfma_f32_16x16x32_bf16 v[80:83], v[170:173], v[206:209], v[80:83]
	v_mfma_f32_16x16x32_bf16 v[72:75], v[162:165], v[214:217], v[72:75]
	v_mfma_f32_16x16x32_bf16 v[64:67], v[170:173], v[214:217], v[64:67]
	s_setprio 0
	s_barrier
	s_add_i32 s47, s47, s28
	v_lshl_add_u64 v[186:187], s[20:21], 0, v[188:189]
	s_mov_b32 m0, s47
	ds_read_b128 v[174:177], v145 offset:16384
	ds_read_b128 v[178:181], v145 offset:17408
	ds_read_b128 v[182:185], v145 offset:18432
	ds_read_b128 v[198:201], v145 offset:19456
	ds_read_b128 v[202:205], v145 offset:20480
	ds_read_b128 v[206:209], v145 offset:21504
	ds_read_b128 v[210:213], v145 offset:22528
	ds_read_b128 v[214:217], v145 offset:23552
	global_load_lds_dwordx4 v[186:187], off
	s_add_i32 m0, s47, 0x2000
	s_add_u32 s48, s20, 0x40000
	v_lshl_add_u64 v[218:219], s[20:21], 0, v[128:129]
	s_addc_u32 s49, s21, 0
	s_add_i32 s47, s50, s28
	global_load_lds_dwordx4 v[218:219], off
	v_lshl_add_u64 v[220:221], s[48:49], 0, v[188:189]
	s_mov_b32 m0, s47
	v_lshl_add_u64 v[222:223], s[22:23], 0, v[130:131]
	global_load_lds_dwordx4 v[220:221], off
	v_lshl_add_u64 v[220:221], s[48:49], 0, v[128:129]
	s_add_i32 m0, s47, 0x2000
	s_nop 0
	global_load_lds_dwordx4 v[220:221], off
	v_lshl_add_u64 v[220:221], s[22:23], 0, v[132:133]
	s_mov_b32 m0, s29
	s_nop 0
	global_load_lds_dwordx4 v[220:221], off
	s_mov_b32 m0, s30
	s_nop 0
	global_load_lds_dwordx4 v[222:223], off
	s_nop 0
	s_waitcnt vmcnt(8)
	s_waitcnt lgkmcnt(0)
	s_barrier
; #define PG8_STAGE(bufoff, gbase, voff) do { _Pragma("unroll") for (int _i = 0; _i < 2; ++_i) \
;         __builtin_amdgcn_global_load_lds((const unsigned*)((const char*)(gbase) + (voff)[_i]), (LAS unsigned*)(lds + (bufoff) + ldsw + _i * 8192), 16, 0, 0); } while (0)
; #define PG8_LDA(dst, b, h) do { _Pragma("unroll") for (int m = 0; m < 4; ++m) _Pragma("unroll") for (int k = 0; k < 2; ++k) dst[m][k] = *(const LAS bf16x8*)(lds + PG8_SA(b, h) + aoff + m * 2048 + k * 1024); } while (0)
; #define PG8_LDB(dst, b, h) do { _Pragma("unroll") for (int n = 0; n < 2; ++n) _Pragma("unroll") for (int k = 0; k < 2; ++k) dst[n][k] = *(const LAS bf16x8*)(lds + PG8_SB(b, h) + boff + n * 2048 + k * 1024); } while (0)
; #define PG8_MMA(ai, bj, At, Bt) do { __builtin_amdgcn_s_setprio(1); _Pragma("unroll") for (int m = 0; m < 4; ++m) _Pragma("unroll") for (int n = 0; n < 2; ++n) _Pragma("unroll") for (int k = 0; k < 2; ++k) \
;         acc[ai][bj][m][n] = __builtin_amdgcn_mfma_f32_16x16x32_bf16(Bt[n][k], At[m][k], acc[ai][bj][m][n], 0, 0, 0); __builtin_amdgcn_s_setprio(0); } while (0)
; #define PG8_WAIT_V(n) asm volatile("s_waitcnt vmcnt(" #n ")" ::: "memory")
; #define PG8_WAIT_L(n) asm volatile("s_waitcnt lgkmcnt(" #n ")" ::: "memory")
; #define PG8_BAR __builtin_amdgcn_s_barrier()
; #define PG8_SCHED __builtin_amdgcn_sched_barrier(0)
; template <class Epi, class Sched>
; __device__ __forceinline__ void gemm_phase(int wv, LAS unsigned char* lds, const Gemm g, const Sched& S, const Epi& E) {
;     ...
;             PG8_WAIT_V(8); PG8_WAIT_L(0); PG8_BAR; PG8_MMA(1, 0, At, B0); PG8_MMA(1, 1, At, B1); PG8_BAR; PG8_SCHED;
;             PG8_LDB(B0, 1, 0); PG8_LDB(B1, 1, 1); PG8_SCHED; PG8_LDA(At, 1, 0); PG8_STAGE(PG8_SA(0, 1), a2 + hstep, voffA);
;             PG8_WAIT_V(8); PG8_WAIT_L(0); PG8_BAR; PG8_MMA(0, 0, At, B0); PG8_MMA(0, 1, At, B1); PG8_BAR; PG8_SCHED;
	s_setprio 1
	s_waitcnt lgkmcnt(0)
	v_mfma_f32_16x16x32_bf16 v[60:63], v[138:141], v[174:177], v[60:63]
	v_mfma_f32_16x16x32_bf16 v[52:55], v[150:153], v[174:177], v[52:55]
	v_mfma_f32_16x16x32_bf16 v[44:47], v[138:141], v[182:185], v[44:47]
	v_mfma_f32_16x16x32_bf16 v[36:39], v[150:153], v[182:185], v[36:39]
	v_mfma_f32_16x16x32_bf16 v[28:31], v[138:141], v[202:205], v[28:31]
	v_mfma_f32_16x16x32_bf16 v[20:23], v[150:153], v[202:205], v[20:23]
	v_mfma_f32_16x16x32_bf16 v[12:15], v[138:141], v[210:213], v[12:15]
	v_mfma_f32_16x16x32_bf16 v[4:7], v[150:153], v[210:213], v[4:7]
	v_mfma_f32_16x16x32_bf16 v[60:63], v[146:149], v[178:181], v[60:63]
	v_mfma_f32_16x16x32_bf16 v[52:55], v[154:157], v[178:181], v[52:55]
	v_mfma_f32_16x16x32_bf16 v[44:47], v[146:149], v[198:201], v[44:47]
	v_mfma_f32_16x16x32_bf16 v[36:39], v[154:157], v[198:201], v[36:39]
	v_mfma_f32_16x16x32_bf16 v[28:31], v[146:149], v[206:209], v[28:31]
	v_mfma_f32_16x16x32_bf16 v[20:23], v[154:157], v[206:209], v[20:23]
	v_mfma_f32_16x16x32_bf16 v[12:15], v[146:149], v[214:217], v[12:15]
	v_mfma_f32_16x16x32_bf16 v[4:7], v[154:157], v[214:217], v[4:7]
	s_setprio 0
	s_setprio 1
	v_mfma_f32_16x16x32_bf16 v[56:59], v[158:161], v[174:177], v[56:59]
	v_mfma_f32_16x16x32_bf16 v[48:51], v[166:169], v[174:177], v[48:51]
	v_mfma_f32_16x16x32_bf16 v[40:43], v[158:161], v[182:185], v[40:43]
	v_mfma_f32_16x16x32_bf16 v[32:35], v[166:169], v[182:185], v[32:35]
	v_mfma_f32_16x16x32_bf16 v[24:27], v[158:161], v[202:205], v[24:27]
	v_mfma_f32_16x16x32_bf16 v[16:19], v[166:169], v[202:205], v[16:19]
	v_mfma_f32_16x16x32_bf16 v[8:11], v[158:161], v[210:213], v[8:11]
	v_mfma_f32_16x16x32_bf16 v[0:3], v[166:169], v[210:213], v[0:3]
	v_mfma_f32_16x16x32_bf16 v[56:59], v[162:165], v[178:181], v[56:59]
	v_mfma_f32_16x16x32_bf16 v[48:51], v[170:173], v[178:181], v[48:51]
	v_mfma_f32_16x16x32_bf16 v[40:43], v[162:165], v[198:201], v[40:43]
	v_mfma_f32_16x16x32_bf16 v[32:35], v[170:173], v[198:201], v[32:35]
	v_mfma_f32_16x16x32_bf16 v[24:27], v[162:165], v[206:209], v[24:27]
	v_mfma_f32_16x16x32_bf16 v[16:19], v[170:173], v[206:209], v[16:19]
	v_mfma_f32_16x16x32_bf16 v[8:11], v[162:165], v[214:217], v[8:11]
	v_mfma_f32_16x16x32_bf16 v[0:3], v[170:173], v[214:217], v[0:3]
	s_setprio 0
	s_barrier
	s_add_i32 s47, 0, 0x18000
	s_add_i32 s48, 0, 0x1c000
	v_add_u32_e32 v154, s47, v143
	v_add_u32_e32 v170, s48, v143
	ds_read_b128 v[138:141], v154
	ds_read_b128 v[146:149], v154 offset:1024
	ds_read_b128 v[150:153], v154 offset:2048
	ds_read_b128 v[154:157], v154 offset:3072
	ds_read_b128 v[158:161], v170
	ds_read_b128 v[162:165], v170 offset:1024
	ds_read_b128 v[166:169], v170 offset:2048
	ds_read_b128 v[170:173], v170 offset:3072
	s_add_u32 s22, s22, 0x40000
	s_addc_u32 s23, s23, 0
	s_mov_b32 m0, s31
	v_lshl_add_u64 v[228:229], s[22:23], 0, v[132:133]
	ds_read_b128 v[174:177], v145 offset:32768
	ds_read_b128 v[178:181], v145 offset:33792
	ds_read_b128 v[182:185], v145 offset:34816
	ds_read_b128 v[198:201], v145 offset:35840
	ds_read_b128 v[202:205], v145 offset:36864
	ds_read_b128 v[206:209], v145 offset:37888
	ds_read_b128 v[210:213], v145 offset:38912
	ds_read_b128 v[214:217], v145 offset:39936
	global_load_lds_dwordx4 v[228:229], off
	v_lshl_add_u64 v[228:229], s[22:23], 0, v[130:131]
	s_mov_b32 m0, s36
	s_nop 0
	global_load_lds_dwordx4 v[228:229], off
	s_nop 0
	s_waitcnt vmcnt(8)
	s_waitcnt lgkmcnt(0)
	s_barrier
	s_setprio 1
	s_waitcnt lgkmcnt(0)
	v_mfma_f32_16x16x32_bf16 v[124:127], v[138:141], v[174:177], v[124:127]
	v_mfma_f32_16x16x32_bf16 v[120:123], v[150:153], v[174:177], v[120:123]
	v_mfma_f32_16x16x32_bf16 v[108:111], v[138:141], v[182:185], v[108:111]
	v_mfma_f32_16x16x32_bf16 v[100:103], v[150:153], v[182:185], v[100:103]
	v_mfma_f32_16x16x32_bf16 v[92:95], v[138:141], v[202:205], v[92:95]
	v_mfma_f32_16x16x32_bf16 v[84:87], v[150:153], v[202:205], v[84:87]
	v_mfma_f32_16x16x32_bf16 v[76:79], v[138:141], v[210:213], v[76:79]
	v_mfma_f32_16x16x32_bf16 v[68:71], v[150:153], v[210:213], v[68:71]
	v_mfma_f32_16x16x32_bf16 v[124:127], v[146:149], v[178:181], v[124:127]
	v_mfma_f32_16x16x32_bf16 v[120:123], v[154:157], v[178:181], v[120:123]
	v_mfma_f32_16x16x32_bf16 v[108:111], v[146:149], v[198:201], v[108:111]
	v_mfma_f32_16x16x32_bf16 v[100:103], v[154:157], v[198:201], v[100:103]
	v_mfma_f32_16x16x32_bf16 v[92:95], v[146:149], v[206:209], v[92:95]
	v_mfma_f32_16x16x32_bf16 v[84:87], v[154:157], v[206:209], v[84:87]
	v_mfma_f32_16x16x32_bf16 v[76:79], v[146:149], v[214:217], v[76:79]
	v_mfma_f32_16x16x32_bf16 v[68:71], v[154:157], v[214:217], v[68:71]
	s_setprio 0
	s_setprio 1
	v_mfma_f32_16x16x32_bf16 v[116:119], v[158:161], v[174:177], v[116:119]
	v_mfma_f32_16x16x32_bf16 v[112:115], v[166:169], v[174:177], v[112:115]
	v_mfma_f32_16x16x32_bf16 v[104:107], v[158:161], v[182:185], v[104:107]
	v_mfma_f32_16x16x32_bf16 v[96:99], v[166:169], v[182:185], v[96:99]
	v_mfma_f32_16x16x32_bf16 v[88:91], v[158:161], v[202:205], v[88:91]
	v_mfma_f32_16x16x32_bf16 v[80:83], v[166:169], v[202:205], v[80:83]
	v_mfma_f32_16x16x32_bf16 v[72:75], v[158:161], v[210:213], v[72:75]
	v_mfma_f32_16x16x32_bf16 v[64:67], v[166:169], v[210:213], v[64:67]
	v_mfma_f32_16x16x32_bf16 v[116:119], v[162:165], v[178:181], v[116:119]
	v_mfma_f32_16x16x32_bf16 v[112:115], v[170:173], v[178:181], v[112:115]
	v_mfma_f32_16x16x32_bf16 v[104:107], v[162:165], v[198:201], v[104:107]
	v_mfma_f32_16x16x32_bf16 v[96:99], v[170:173], v[198:201], v[96:99]
	v_mfma_f32_16x16x32_bf16 v[88:91], v[162:165], v[206:209], v[88:91]
	v_mfma_f32_16x16x32_bf16 v[80:83], v[170:173], v[206:209], v[80:83]
	v_mfma_f32_16x16x32_bf16 v[72:75], v[162:165], v[214:217], v[72:75]
	v_mfma_f32_16x16x32_bf16 v[64:67], v[170:173], v[214:217], v[64:67]
	s_setprio 0
	s_barrier
; #define PG8_STAGE(bufoff, gbase, voff) do { _Pragma("unroll") for (int _i = 0; _i < 2; ++_i) \
;         __builtin_amdgcn_global_load_lds((const unsigned*)((const char*)(gbase) + (voff)[_i]), (LAS unsigned*)(lds + (bufoff) + ldsw + _i * 8192), 16, 0, 0); } while (0)
; #define PG8_LDA(dst, b, h) do { _Pragma("unroll") for (int m = 0; m < 4; ++m) _Pragma("unroll") for (int k = 0; k < 2; ++k) dst[m][k] = *(const LAS bf16x8*)(lds + PG8_SA(b, h) + aoff + m * 2048 + k * 1024); } while (0)
; #define PG8_MMA(ai, bj, At, Bt) do { __builtin_amdgcn_s_setprio(1); _Pragma("unroll") for (int m = 0; m < 4; ++m) _Pragma("unroll") for (int n = 0; n < 2; ++n) _Pragma("unroll") for (int k = 0; k < 2; ++k) \
;         acc[ai][bj][m][n] = __builtin_amdgcn_mfma_f32_16x16x32_bf16(Bt[n][k], At[m][k], acc[ai][bj][m][n], 0, 0, 0); __builtin_amdgcn_s_setprio(0); } while (0)
; #define PG8_WAIT_V(n) asm volatile("s_waitcnt vmcnt(" #n ")" ::: "memory")
; #define PG8_WAIT_L(n) asm volatile("s_waitcnt lgkmcnt(" #n ")" ::: "memory")
; #define PG8_BAR __builtin_amdgcn_s_barrier()
; #define PG8_SCHED __builtin_amdgcn_sched_barrier(0)
; template <class Epi, class Sched>
; __device__ __forceinline__ void gemm_phase(int wv, LAS unsigned char* lds, const Gemm g, const Sched& S, const Epi& E) {
;     ...
;             PG8_LDA(At, 1, 1); PG8_STAGE(PG8_SB(1, 0), b3, voffB); PG8_STAGE(PG8_SB(1, 1), b3 + hstepB, voffB); PG8_STAGE(PG8_SA(1, 0), a3, voffA);
;             PG8_WAIT_V(8); PG8_WAIT_L(0); PG8_BAR; PG8_MMA(1, 0, At, B0); PG8_MMA(1, 1, At, B1); PG8_BAR; PG8_SCHED;
;         }
;         if (wr == 0) PG8_BAR;
	s_add_i32 s22, s47, s28
	v_lshl_add_u64 v[186:187], v[186:187], 0, s[74:75]
	s_mov_b32 m0, s22
	ds_read_b128 v[174:177], v145 offset:49152
	ds_read_b128 v[178:181], v145 offset:50176
	ds_read_b128 v[182:185], v145 offset:51200
	ds_read_b128 v[198:201], v145 offset:52224
	ds_read_b128 v[202:205], v145 offset:53248
	ds_read_b128 v[206:209], v145 offset:54272
	ds_read_b128 v[210:213], v145 offset:55296
	ds_read_b128 v[214:217], v145 offset:56320
	global_load_lds_dwordx4 v[186:187], off
	s_add_i32 m0, s22, 0x2000
	s_add_u32 s20, s20, 0x40080
	v_lshl_add_u64 v[186:187], v[218:219], 0, s[74:75]
	s_addc_u32 s21, s21, 0
	s_add_i32 s22, s48, s28
	global_load_lds_dwordx4 v[186:187], off
	v_lshl_add_u64 v[186:187], s[20:21], 0, v[188:189]
	s_mov_b32 m0, s22
	s_nop 0
	global_load_lds_dwordx4 v[186:187], off
	v_lshl_add_u64 v[186:187], s[20:21], 0, v[128:129]
	s_add_i32 m0, s22, 0x2000
	s_nop 0
	global_load_lds_dwordx4 v[186:187], off
	v_lshl_add_u64 v[186:187], v[220:221], 0, s[74:75]
	s_mov_b32 m0, s37
	s_nop 0
	global_load_lds_dwordx4 v[186:187], off
	v_lshl_add_u64 v[186:187], v[222:223], 0, s[74:75]
	s_mov_b32 m0, s38
	s_nop 0
	global_load_lds_dwordx4 v[186:187], off
	s_waitcnt vmcnt(8)
	s_waitcnt lgkmcnt(0)
	s_barrier
	s_setprio 1
	s_waitcnt lgkmcnt(0)
	v_mfma_f32_16x16x32_bf16 v[60:63], v[138:141], v[174:177], v[60:63]
	v_mfma_f32_16x16x32_bf16 v[52:55], v[150:153], v[174:177], v[52:55]
	v_mfma_f32_16x16x32_bf16 v[44:47], v[138:141], v[182:185], v[44:47]
	v_mfma_f32_16x16x32_bf16 v[36:39], v[150:153], v[182:185], v[36:39]
	v_mfma_f32_16x16x32_bf16 v[28:31], v[138:141], v[202:205], v[28:31]
	v_mfma_f32_16x16x32_bf16 v[20:23], v[150:153], v[202:205], v[20:23]
	v_mfma_f32_16x16x32_bf16 v[12:15], v[138:141], v[210:213], v[12:15]
	v_mfma_f32_16x16x32_bf16 v[4:7], v[150:153], v[210:213], v[4:7]
	v_mfma_f32_16x16x32_bf16 v[60:63], v[146:149], v[178:181], v[60:63]
	v_mfma_f32_16x16x32_bf16 v[52:55], v[154:157], v[178:181], v[52:55]
	v_mfma_f32_16x16x32_bf16 v[44:47], v[146:149], v[198:201], v[44:47]
	v_mfma_f32_16x16x32_bf16 v[36:39], v[154:157], v[198:201], v[36:39]
	v_mfma_f32_16x16x32_bf16 v[28:31], v[146:149], v[206:209], v[28:31]
	v_mfma_f32_16x16x32_bf16 v[20:23], v[154:157], v[206:209], v[20:23]
	v_mfma_f32_16x16x32_bf16 v[12:15], v[146:149], v[214:217], v[12:15]
	v_mfma_f32_16x16x32_bf16 v[4:7], v[154:157], v[214:217], v[4:7]
	s_setprio 0
	s_setprio 1
	v_mfma_f32_16x16x32_bf16 v[56:59], v[158:161], v[174:177], v[56:59]
	v_mfma_f32_16x16x32_bf16 v[48:51], v[166:169], v[174:177], v[48:51]
	v_mfma_f32_16x16x32_bf16 v[40:43], v[158:161], v[182:185], v[40:43]
	v_mfma_f32_16x16x32_bf16 v[32:35], v[166:169], v[182:185], v[32:35]
	v_mfma_f32_16x16x32_bf16 v[24:27], v[158:161], v[202:205], v[24:27]
	v_mfma_f32_16x16x32_bf16 v[16:19], v[166:169], v[202:205], v[16:19]
	v_mfma_f32_16x16x32_bf16 v[8:11], v[158:161], v[210:213], v[8:11]
	v_mfma_f32_16x16x32_bf16 v[0:3], v[166:169], v[210:213], v[0:3]
	v_mfma_f32_16x16x32_bf16 v[56:59], v[162:165], v[178:181], v[56:59]
	v_mfma_f32_16x16x32_bf16 v[48:51], v[170:173], v[178:181], v[48:51]
	v_mfma_f32_16x16x32_bf16 v[40:43], v[162:165], v[198:201], v[40:43]
	v_mfma_f32_16x16x32_bf16 v[32:35], v[170:173], v[198:201], v[32:35]
	v_mfma_f32_16x16x32_bf16 v[24:27], v[162:165], v[206:209], v[24:27]
	v_mfma_f32_16x16x32_bf16 v[16:19], v[170:173], v[206:209], v[16:19]
	v_mfma_f32_16x16x32_bf16 v[8:11], v[162:165], v[214:217], v[8:11]
	v_mfma_f32_16x16x32_bf16 v[0:3], v[170:173], v[214:217], v[0:3]
	s_setprio 0
	s_barrier
	s_add_i32 s46, s46, 2
	s_add_u32 s18, s18, 0x100
	s_addc_u32 s19, s19, 0
	s_add_u32 s43, s43, 0x100
	s_addc_u32 s45, s45, 0
	s_cmp_gt_u32 s46, 13
	s_cbranch_scc0 .LBB0_178
	s_and_b64 vcc, exec, s[8:9]
	s_cbranch_vccz .LBB0_181
	s_barrier

; #define PG8_STAGE(bufoff, gbase, voff) do { _Pragma("unroll") for (int _i = 0; _i < 2; ++_i) \
;         __builtin_amdgcn_global_load_lds((const unsigned*)((const char*)(gbase) + (voff)[_i]), (LAS unsigned*)(lds + (bufoff) + ldsw + _i * 8192), 16, 0, 0); } while (0)
; #define PG8_LDA(dst, b, h) do { _Pragma("unroll") for (int m = 0; m < 4; ++m) _Pragma("unroll") for (int k = 0; k < 2; ++k) dst[m][k] = *(const LAS bf16x8*)(lds + PG8_SA(b, h) + aoff + m * 2048 + k * 1024); } while (0)
; #define PG8_LDB(dst, b, h) do { _Pragma("unroll") for (int n = 0; n < 2; ++n) _Pragma("unroll") for (int k = 0; k < 2; ++k) dst[n][k] = *(const LAS bf16x8*)(lds + PG8_SB(b, h) + boff + n * 2048 + k * 1024); } while (0)
; #define PG8_MMA(ai, bj, At, Bt) do { __builtin_amdgcn_s_setprio(1); _Pragma("unroll") for (int m = 0; m < 4; ++m) _Pragma("unroll") for (int n = 0; n < 2; ++n) _Pragma("unroll") for (int k = 0; k < 2; ++k) \
;         acc[ai][bj][m][n] = __builtin_amdgcn_mfma_f32_16x16x32_bf16(Bt[n][k], At[m][k], acc[ai][bj][m][n], 0, 0, 0); __builtin_amdgcn_s_setprio(0); } while (0)
; #define PG8_WAIT_V(n) asm volatile("s_waitcnt vmcnt(" #n ")" ::: "memory")
; #define PG8_WAIT_L(n) asm volatile("s_waitcnt lgkmcnt(" #n ")" ::: "memory")
; #define PG8_BAR __builtin_amdgcn_s_barrier()
; #define PG8_SCHED __builtin_amdgcn_sched_barrier(0)
; template <class Epi, class Sched>
; __device__ __forceinline__ void gemm_phase(int wv, LAS unsigned char* lds, const Gemm g, const Sched& S, const Epi& E) {
;     ...
;         for (int t = 0; t < nt; t += 2) {
;             const bool last = (t == nt - 2);
;             const char* a1 = cA + (size_t)(t + 1) * kstep;
;             const char* a2 = last ? nA : cA + (size_t)(t + 2) * kstep; const char* b2 = last ? nB : cB + (size_t)(t + 2) * kstep;
;             const char* a3 = a2 + kstep; const char* b3 = b2 + kstep;
;             PG8_LDB(B0, 0, 0); PG8_LDB(B1, 0, 1); PG8_SCHED; PG8_LDA(At, 0, 0); PG8_STAGE(PG8_SA(1, 1), a1 + hstep, voffA);
;             PG8_WAIT_V(8); PG8_WAIT_L(0); PG8_BAR; PG8_MMA(0, 0, At, B0); PG8_MMA(0, 1, At, B1); PG8_BAR; PG8_SCHED;
;             PG8_LDA(At, 0, 1); PG8_STAGE(PG8_SB(0, 0), b2, voffB); PG8_STAGE(PG8_SB(0, 1), b2 + hstepB, voffB); PG8_STAGE(PG8_SA(0, 0), a2, voffA);
;             PG8_WAIT_V(8); PG8_WAIT_L(0); PG8_BAR; PG8_MMA(1, 0, At, B0); PG8_MMA(1, 1, At, B1); PG8_BAR; PG8_SCHED;
.LBB0_255:
	s_add_u32 s20, s18, 0x100
	s_addc_u32 s21, s19, 0
	s_add_i32 s49, 0, 0x10000
	s_cmp_eq_u32 s48, 40
	s_cselect_b32 s25, s5, s21
	s_cselect_b32 s24, s4, s20
	s_cselect_b32 s23, s17, s47
	s_cselect_b32 s22, s16, s46
	s_add_i32 s50, 0, 0x14000
	v_add_u32_e32 v124, s49, v240
	v_add_u32_e32 v156, s50, v240
	ds_read_b128 v[112:115], v124
	ds_read_b128 v[116:119], v124 offset:1024
	ds_read_b128 v[120:123], v124 offset:2048
	ds_read_b128 v[124:127], v124 offset:3072
	ds_read_b128 v[128:131], v156
	ds_read_b128 v[140:143], v156 offset:1024
	ds_read_b128 v[152:155], v156 offset:2048
	ds_read_b128 v[156:159], v156 offset:3072
	v_lshl_add_u64 v[212:213], s[18:19], 0, v[204:205]
	s_add_i32 m0, s31, 0xc000
	ds_read_b128 v[160:163], v244
	ds_read_b128 v[164:167], v244 offset:1024
	ds_read_b128 v[168:171], v244 offset:2048
	ds_read_b128 v[172:175], v244 offset:3072
	ds_read_b128 v[176:179], v244 offset:4096
	ds_read_b128 v[180:183], v244 offset:5120
	ds_read_b128 v[184:187], v244 offset:6144
	ds_read_b128 v[208:211], v244 offset:7168
	global_load_lds_dwordx4 v[212:213], off
	v_lshl_add_u64 v[212:213], s[18:19], 0, v[206:207]
	s_add_i32 m0, s31, 0xe000
	s_nop 0
	global_load_lds_dwordx4 v[212:213], off
	s_nop 0
	s_waitcnt vmcnt(8)
	s_waitcnt lgkmcnt(0)
	s_barrier
	s_setprio 1
	s_waitcnt lgkmcnt(0)
	v_mfma_f32_16x16x32_bf16 v[148:151], v[112:115], v[160:163], v[148:151]
	v_mfma_f32_16x16x32_bf16 v[144:147], v[120:123], v[160:163], v[144:147]
	v_mfma_f32_16x16x32_bf16 v[108:111], v[112:115], v[168:171], v[108:111]
	v_mfma_f32_16x16x32_bf16 v[104:107], v[120:123], v[168:171], v[104:107]
	v_mfma_f32_16x16x32_bf16 v[92:95], v[112:115], v[176:179], v[92:95]
	v_mfma_f32_16x16x32_bf16 v[88:91], v[120:123], v[176:179], v[88:91]
	v_mfma_f32_16x16x32_bf16 v[76:79], v[112:115], v[184:187], v[76:79]
	v_mfma_f32_16x16x32_bf16 v[72:75], v[120:123], v[184:187], v[72:75]
	v_mfma_f32_16x16x32_bf16 v[148:151], v[116:119], v[164:167], v[148:151]
	v_mfma_f32_16x16x32_bf16 v[144:147], v[124:127], v[164:167], v[144:147]
	v_mfma_f32_16x16x32_bf16 v[108:111], v[116:119], v[172:175], v[108:111]
	v_mfma_f32_16x16x32_bf16 v[104:107], v[124:127], v[172:175], v[104:107]
	v_mfma_f32_16x16x32_bf16 v[92:95], v[116:119], v[180:183], v[92:95]
	v_mfma_f32_16x16x32_bf16 v[88:91], v[124:127], v[180:183], v[88:91]
	v_mfma_f32_16x16x32_bf16 v[76:79], v[116:119], v[208:211], v[76:79]
	v_mfma_f32_16x16x32_bf16 v[72:75], v[124:127], v[208:211], v[72:75]
	s_setprio 0
	s_setprio 1
	v_mfma_f32_16x16x32_bf16 v[136:139], v[128:131], v[160:163], v[136:139]
	v_mfma_f32_16x16x32_bf16 v[132:135], v[152:155], v[160:163], v[132:135]
	v_mfma_f32_16x16x32_bf16 v[100:103], v[128:131], v[168:171], v[100:103]
	v_mfma_f32_16x16x32_bf16 v[96:99], v[152:155], v[168:171], v[96:99]
	v_mfma_f32_16x16x32_bf16 v[84:87], v[128:131], v[176:179], v[84:87]
	v_mfma_f32_16x16x32_bf16 v[80:83], v[152:155], v[176:179], v[80:83]
	v_mfma_f32_16x16x32_bf16 v[68:71], v[128:131], v[184:187], v[68:71]
	v_mfma_f32_16x16x32_bf16 v[64:67], v[152:155], v[184:187], v[64:67]
	v_mfma_f32_16x16x32_bf16 v[136:139], v[140:143], v[164:167], v[136:139]
	v_mfma_f32_16x16x32_bf16 v[132:135], v[156:159], v[164:167], v[132:135]
	v_mfma_f32_16x16x32_bf16 v[100:103], v[140:143], v[172:175], v[100:103]
	v_mfma_f32_16x16x32_bf16 v[96:99], v[156:159], v[172:175], v[96:99]
	v_mfma_f32_16x16x32_bf16 v[84:87], v[140:143], v[180:183], v[84:87]
	v_mfma_f32_16x16x32_bf16 v[80:83], v[156:159], v[180:183], v[80:83]
	v_mfma_f32_16x16x32_bf16 v[68:71], v[140:143], v[208:211], v[68:71]
	v_mfma_f32_16x16x32_bf16 v[64:67], v[156:159], v[208:211], v[64:67]
	s_setprio 0
	s_barrier
	s_add_i32 s18, s49, s30
	v_lshl_add_u64 v[212:213], s[22:23], 0, v[188:189]
	s_mov_b32 m0, s18
	ds_read_b128 v[160:163], v244 offset:16384
	ds_read_b128 v[164:167], v244 offset:17408
	ds_read_b128 v[168:171], v244 offset:18432
	ds_read_b128 v[172:175], v244 offset:19456
	ds_read_b128 v[176:179], v244 offset:20480
	ds_read_b128 v[180:183], v244 offset:21504
	ds_read_b128 v[184:187], v244 offset:22528
	ds_read_b128 v[208:211], v244 offset:23552
	global_load_lds_dwordx4 v[212:213], off
	s_add_i32 m0, s18, 0x2000
	s_add_u32 s18, s22, 0xb000
	v_lshl_add_u64 v[214:215], s[22:23], 0, v[198:199]
	s_addc_u32 s19, s23, 0
	s_add_i32 s49, s50, s30
	global_load_lds_dwordx4 v[214:215], off
	v_lshl_add_u64 v[216:217], s[18:19], 0, v[188:189]
	s_mov_b32 m0, s49
	v_lshl_add_u64 v[218:219], s[24:25], 0, v[200:201]
	global_load_lds_dwordx4 v[216:217], off
	v_lshl_add_u64 v[216:217], s[18:19], 0, v[198:199]
	s_add_i32 m0, s49, 0x2000
	s_nop 0
	global_load_lds_dwordx4 v[216:217], off
	v_lshl_add_u64 v[216:217], s[24:25], 0, v[202:203]
	s_mov_b32 m0, s31
	s_nop 0
	global_load_lds_dwordx4 v[216:217], off
	s_mov_b32 m0, s36
	s_nop 0
	global_load_lds_dwordx4 v[218:219], off
	s_nop 0
	s_waitcnt vmcnt(8)
	s_waitcnt lgkmcnt(0)
	s_barrier
; #define PG8_STAGE(bufoff, gbase, voff) do { _Pragma("unroll") for (int _i = 0; _i < 2; ++_i) \
;         __builtin_amdgcn_global_load_lds((const unsigned*)((const char*)(gbase) + (voff)[_i]), (LAS unsigned*)(lds + (bufoff) + ldsw + _i * 8192), 16, 0, 0); } while (0)
; #define PG8_LDA(dst, b, h) do { _Pragma("unroll") for (int m = 0; m < 4; ++m) _Pragma("unroll") for (int k = 0; k < 2; ++k) dst[m][k] = *(const LAS bf16x8*)(lds + PG8_SA(b, h) + aoff + m * 2048 + k * 1024); } while (0)
; #define PG8_LDB(dst, b, h) do { _Pragma("unroll") for (int n = 0; n < 2; ++n) _Pragma("unroll") for (int k = 0; k < 2; ++k) dst[n][k] = *(const LAS bf16x8*)(lds + PG8_SB(b, h) + boff + n * 2048 + k * 1024); } while (0)
; #define PG8_MMA(ai, bj, At, Bt) do { __builtin_amdgcn_s_setprio(1); _Pragma("unroll") for (int m = 0; m < 4; ++m) _Pragma("unroll") for (int n = 0; n < 2; ++n) _Pragma("unroll") for (int k = 0; k < 2; ++k) \
;         acc[ai][bj][m][n] = __builtin_amdgcn_mfma_f32_16x16x32_bf16(Bt[n][k], At[m][k], acc[ai][bj][m][n], 0, 0, 0); __builtin_amdgcn_s_setprio(0); } while (0)
; #define PG8_WAIT_V(n) asm volatile("s_waitcnt vmcnt(" #n ")" ::: "memory")
; #define PG8_WAIT_L(n) asm volatile("s_waitcnt lgkmcnt(" #n ")" ::: "memory")
; #define PG8_BAR __builtin_amdgcn_s_barrier()
; #define PG8_SCHED __builtin_amdgcn_sched_barrier(0)
; template <class Epi, class Sched>
; __device__ __forceinline__ void gemm_phase(int wv, LAS unsigned char* lds, const Gemm g, const Sched& S, const Epi& E) {
;     ...
;             PG8_WAIT_V(8); PG8_WAIT_L(0); PG8_BAR; PG8_MMA(1, 0, At, B0); PG8_MMA(1, 1, At, B1); PG8_BAR; PG8_SCHED;
;             PG8_LDB(B0, 1, 0); PG8_LDB(B1, 1, 1); PG8_SCHED; PG8_LDA(At, 1, 0); PG8_STAGE(PG8_SA(0, 1), a2 + hstep, voffA);
;             PG8_WAIT_V(8); PG8_WAIT_L(0); PG8_BAR; PG8_MMA(0, 0, At, B0); PG8_MMA(0, 1, At, B1); PG8_BAR; PG8_SCHED;
	s_setprio 1
	s_waitcnt lgkmcnt(0)
	v_mfma_f32_16x16x32_bf16 v[60:63], v[112:115], v[160:163], v[60:63]
	v_mfma_f32_16x16x32_bf16 v[56:59], v[120:123], v[160:163], v[56:59]
	v_mfma_f32_16x16x32_bf16 v[44:47], v[112:115], v[168:171], v[44:47]
	v_mfma_f32_16x16x32_bf16 v[40:43], v[120:123], v[168:171], v[40:43]
	v_mfma_f32_16x16x32_bf16 v[28:31], v[112:115], v[176:179], v[28:31]
	v_mfma_f32_16x16x32_bf16 v[24:27], v[120:123], v[176:179], v[24:27]
	v_mfma_f32_16x16x32_bf16 v[12:15], v[112:115], v[184:187], v[12:15]
	v_mfma_f32_16x16x32_bf16 v[8:11], v[120:123], v[184:187], v[8:11]
	v_mfma_f32_16x16x32_bf16 v[60:63], v[116:119], v[164:167], v[60:63]
	v_mfma_f32_16x16x32_bf16 v[56:59], v[124:127], v[164:167], v[56:59]
	v_mfma_f32_16x16x32_bf16 v[44:47], v[116:119], v[172:175], v[44:47]
	v_mfma_f32_16x16x32_bf16 v[40:43], v[124:127], v[172:175], v[40:43]
	v_mfma_f32_16x16x32_bf16 v[28:31], v[116:119], v[180:183], v[28:31]
	v_mfma_f32_16x16x32_bf16 v[24:27], v[124:127], v[180:183], v[24:27]
	v_mfma_f32_16x16x32_bf16 v[12:15], v[116:119], v[208:211], v[12:15]
	v_mfma_f32_16x16x32_bf16 v[8:11], v[124:127], v[208:211], v[8:11]
	s_setprio 0
	s_setprio 1
	v_mfma_f32_16x16x32_bf16 v[52:55], v[128:131], v[160:163], v[52:55]
	v_mfma_f32_16x16x32_bf16 v[48:51], v[152:155], v[160:163], v[48:51]
	v_mfma_f32_16x16x32_bf16 v[36:39], v[128:131], v[168:171], v[36:39]
	v_mfma_f32_16x16x32_bf16 v[32:35], v[152:155], v[168:171], v[32:35]
	v_mfma_f32_16x16x32_bf16 v[20:23], v[128:131], v[176:179], v[20:23]
	v_mfma_f32_16x16x32_bf16 v[16:19], v[152:155], v[176:179], v[16:19]
	v_mfma_f32_16x16x32_bf16 v[4:7], v[128:131], v[184:187], v[4:7]
	v_mfma_f32_16x16x32_bf16 v[0:3], v[152:155], v[184:187], v[0:3]
	v_mfma_f32_16x16x32_bf16 v[52:55], v[140:143], v[164:167], v[52:55]
	v_mfma_f32_16x16x32_bf16 v[48:51], v[156:159], v[164:167], v[48:51]
	v_mfma_f32_16x16x32_bf16 v[36:39], v[140:143], v[172:175], v[36:39]
	v_mfma_f32_16x16x32_bf16 v[32:35], v[156:159], v[172:175], v[32:35]
	v_mfma_f32_16x16x32_bf16 v[20:23], v[140:143], v[180:183], v[20:23]
	v_mfma_f32_16x16x32_bf16 v[16:19], v[156:159], v[180:183], v[16:19]
	v_mfma_f32_16x16x32_bf16 v[4:7], v[140:143], v[208:211], v[4:7]
	v_mfma_f32_16x16x32_bf16 v[0:3], v[156:159], v[208:211], v[0:3]
	s_setprio 0
	s_barrier
	s_add_i32 s49, 0, 0x18000
	s_add_i32 s50, 0, 0x1c000
	v_add_u32_e32 v124, s49, v240
	v_add_u32_e32 v156, s50, v240
	ds_read_b128 v[112:115], v124
	ds_read_b128 v[116:119], v124 offset:1024
	ds_read_b128 v[120:123], v124 offset:2048
	ds_read_b128 v[124:127], v124 offset:3072
	ds_read_b128 v[128:131], v156
	ds_read_b128 v[140:143], v156 offset:1024
	ds_read_b128 v[152:155], v156 offset:2048
	ds_read_b128 v[156:159], v156 offset:3072
	s_add_u32 s18, s24, 0xb0000
	s_addc_u32 s19, s25, 0
	s_mov_b32 m0, s37
	v_lshl_add_u64 v[220:221], s[18:19], 0, v[202:203]
	ds_read_b128 v[160:163], v244 offset:32768
	ds_read_b128 v[164:167], v244 offset:33792
	ds_read_b128 v[168:171], v244 offset:34816
	ds_read_b128 v[172:175], v244 offset:35840
	ds_read_b128 v[176:179], v244 offset:36864
	ds_read_b128 v[180:183], v244 offset:37888
	ds_read_b128 v[184:187], v244 offset:38912
	ds_read_b128 v[208:211], v244 offset:39936
	global_load_lds_dwordx4 v[220:221], off
	v_lshl_add_u64 v[220:221], s[18:19], 0, v[200:201]
	s_mov_b32 m0, s38
	s_nop 0
	global_load_lds_dwordx4 v[220:221], off
	s_nop 0
	s_waitcnt vmcnt(8)
	s_waitcnt lgkmcnt(0)
	s_barrier
	s_setprio 1
	s_waitcnt lgkmcnt(0)
	v_mfma_f32_16x16x32_bf16 v[148:151], v[112:115], v[160:163], v[148:151]
	v_mfma_f32_16x16x32_bf16 v[144:147], v[120:123], v[160:163], v[144:147]
	v_mfma_f32_16x16x32_bf16 v[108:111], v[112:115], v[168:171], v[108:111]
	v_mfma_f32_16x16x32_bf16 v[104:107], v[120:123], v[168:171], v[104:107]
	v_mfma_f32_16x16x32_bf16 v[92:95], v[112:115], v[176:179], v[92:95]
	v_mfma_f32_16x16x32_bf16 v[88:91], v[120:123], v[176:179], v[88:91]
	v_mfma_f32_16x16x32_bf16 v[76:79], v[112:115], v[184:187], v[76:79]
	v_mfma_f32_16x16x32_bf16 v[72:75], v[120:123], v[184:187], v[72:75]
	v_mfma_f32_16x16x32_bf16 v[148:151], v[116:119], v[164:167], v[148:151]
	v_mfma_f32_16x16x32_bf16 v[144:147], v[124:127], v[164:167], v[144:147]
	v_mfma_f32_16x16x32_bf16 v[108:111], v[116:119], v[172:175], v[108:111]
	v_mfma_f32_16x16x32_bf16 v[104:107], v[124:127], v[172:175], v[104:107]
	v_mfma_f32_16x16x32_bf16 v[92:95], v[116:119], v[180:183], v[92:95]
	v_mfma_f32_16x16x32_bf16 v[88:91], v[124:127], v[180:183], v[88:91]
	v_mfma_f32_16x16x32_bf16 v[76:79], v[116:119], v[208:211], v[76:79]
	v_mfma_f32_16x16x32_bf16 v[72:75], v[124:127], v[208:211], v[72:75]
	s_setprio 0
	s_setprio 1
	v_mfma_f32_16x16x32_bf16 v[136:139], v[128:131], v[160:163], v[136:139]
	v_mfma_f32_16x16x32_bf16 v[132:135], v[152:155], v[160:163], v[132:135]
	v_mfma_f32_16x16x32_bf16 v[100:103], v[128:131], v[168:171], v[100:103]
	v_mfma_f32_16x16x32_bf16 v[96:99], v[152:155], v[168:171], v[96:99]
	v_mfma_f32_16x16x32_bf16 v[84:87], v[128:131], v[176:179], v[84:87]
	v_mfma_f32_16x16x32_bf16 v[80:83], v[152:155], v[176:179], v[80:83]
	v_mfma_f32_16x16x32_bf16 v[68:71], v[128:131], v[184:187], v[68:71]
	v_mfma_f32_16x16x32_bf16 v[64:67], v[152:155], v[184:187], v[64:67]
	v_mfma_f32_16x16x32_bf16 v[136:139], v[140:143], v[164:167], v[136:139]
	v_mfma_f32_16x16x32_bf16 v[132:135], v[156:159], v[164:167], v[132:135]
	v_mfma_f32_16x16x32_bf16 v[100:103], v[140:143], v[172:175], v[100:103]
	v_mfma_f32_16x16x32_bf16 v[96:99], v[156:159], v[172:175], v[96:99]
	v_mfma_f32_16x16x32_bf16 v[84:87], v[140:143], v[180:183], v[84:87]
	v_mfma_f32_16x16x32_bf16 v[80:83], v[156:159], v[180:183], v[80:83]
	v_mfma_f32_16x16x32_bf16 v[68:71], v[140:143], v[208:211], v[68:71]
	v_mfma_f32_16x16x32_bf16 v[64:67], v[156:159], v[208:211], v[64:67]
	s_setprio 0
	s_barrier
; #define PG8_STAGE(bufoff, gbase, voff) do { _Pragma("unroll") for (int _i = 0; _i < 2; ++_i) \
;         __builtin_amdgcn_global_load_lds((const unsigned*)((const char*)(gbase) + (voff)[_i]), (LAS unsigned*)(lds + (bufoff) + ldsw + _i * 8192), 16, 0, 0); } while (0)
; #define PG8_LDA(dst, b, h) do { _Pragma("unroll") for (int m = 0; m < 4; ++m) _Pragma("unroll") for (int k = 0; k < 2; ++k) dst[m][k] = *(const LAS bf16x8*)(lds + PG8_SA(b, h) + aoff + m * 2048 + k * 1024); } while (0)
; #define PG8_MMA(ai, bj, At, Bt) do { __builtin_amdgcn_s_setprio(1); _Pragma("unroll") for (int m = 0; m < 4; ++m) _Pragma("unroll") for (int n = 0; n < 2; ++n) _Pragma("unroll") for (int k = 0; k < 2; ++k) \
;         acc[ai][bj][m][n] = __builtin_amdgcn_mfma_f32_16x16x32_bf16(Bt[n][k], At[m][k], acc[ai][bj][m][n], 0, 0, 0); __builtin_amdgcn_s_setprio(0); } while (0)
; #define PG8_WAIT_V(n) asm volatile("s_waitcnt vmcnt(" #n ")" ::: "memory")
; #define PG8_WAIT_L(n) asm volatile("s_waitcnt lgkmcnt(" #n ")" ::: "memory")
; #define PG8_BAR __builtin_amdgcn_s_barrier()
; #define PG8_SCHED __builtin_amdgcn_sched_barrier(0)
; template <class Epi, class Sched>
; __device__ __forceinline__ void gemm_phase(int wv, LAS unsigned char* lds, const Gemm g, const Sched& S, const Epi& E) {
;     ...
;             PG8_LDA(At, 1, 1); PG8_STAGE(PG8_SB(1, 0), b3, voffB); PG8_STAGE(PG8_SB(1, 1), b3 + hstepB, voffB); PG8_STAGE(PG8_SA(1, 0), a3, voffA);
;             PG8_WAIT_V(8); PG8_WAIT_L(0); PG8_BAR; PG8_MMA(1, 0, At, B0); PG8_MMA(1, 1, At, B1); PG8_BAR; PG8_SCHED;
;         }
;         if (wr == 0) PG8_BAR;
	s_add_i32 s18, s49, s30
	v_lshl_add_u64 v[212:213], v[212:213], 0, s[74:75]
	s_mov_b32 m0, s18
	ds_read_b128 v[160:163], v244 offset:49152
	ds_read_b128 v[164:167], v244 offset:50176
	ds_read_b128 v[168:171], v244 offset:51200
	ds_read_b128 v[172:175], v244 offset:52224
	ds_read_b128 v[176:179], v244 offset:53248
	ds_read_b128 v[180:183], v244 offset:54272
	ds_read_b128 v[184:187], v244 offset:55296
	ds_read_b128 v[208:211], v244 offset:56320
	global_load_lds_dwordx4 v[212:213], off
	s_add_i32 m0, s18, 0x2000
	s_add_u32 s18, s22, 0xb080
	v_lshl_add_u64 v[212:213], v[214:215], 0, s[74:75]
	s_addc_u32 s19, s23, 0
	s_add_i32 s22, s50, s30
	global_load_lds_dwordx4 v[212:213], off
	v_lshl_add_u64 v[212:213], s[18:19], 0, v[188:189]
	s_mov_b32 m0, s22
	s_nop 0
	global_load_lds_dwordx4 v[212:213], off
	v_lshl_add_u64 v[212:213], s[18:19], 0, v[198:199]
	s_add_i32 m0, s22, 0x2000
	s_nop 0
	global_load_lds_dwordx4 v[212:213], off
	v_lshl_add_u64 v[212:213], v[216:217], 0, s[74:75]
	s_mov_b32 m0, s39
	s_nop 0
	global_load_lds_dwordx4 v[212:213], off
	v_lshl_add_u64 v[212:213], v[218:219], 0, s[74:75]
	s_mov_b32 m0, s40
	s_nop 0
	global_load_lds_dwordx4 v[212:213], off
	s_waitcnt vmcnt(8)
	s_waitcnt lgkmcnt(0)
	s_barrier
	s_setprio 1
	s_waitcnt lgkmcnt(0)
	v_mfma_f32_16x16x32_bf16 v[60:63], v[112:115], v[160:163], v[60:63]
	v_mfma_f32_16x16x32_bf16 v[56:59], v[120:123], v[160:163], v[56:59]
	v_mfma_f32_16x16x32_bf16 v[44:47], v[112:115], v[168:171], v[44:47]
	v_mfma_f32_16x16x32_bf16 v[40:43], v[120:123], v[168:171], v[40:43]
	v_mfma_f32_16x16x32_bf16 v[28:31], v[112:115], v[176:179], v[28:31]
	v_mfma_f32_16x16x32_bf16 v[24:27], v[120:123], v[176:179], v[24:27]
	v_mfma_f32_16x16x32_bf16 v[12:15], v[112:115], v[184:187], v[12:15]
	v_mfma_f32_16x16x32_bf16 v[8:11], v[120:123], v[184:187], v[8:11]
	v_mfma_f32_16x16x32_bf16 v[60:63], v[116:119], v[164:167], v[60:63]
	v_mfma_f32_16x16x32_bf16 v[56:59], v[124:127], v[164:167], v[56:59]
	v_mfma_f32_16x16x32_bf16 v[44:47], v[116:119], v[172:175], v[44:47]
	v_mfma_f32_16x16x32_bf16 v[40:43], v[124:127], v[172:175], v[40:43]
	v_mfma_f32_16x16x32_bf16 v[28:31], v[116:119], v[180:183], v[28:31]
	v_mfma_f32_16x16x32_bf16 v[24:27], v[124:127], v[180:183], v[24:27]
	v_mfma_f32_16x16x32_bf16 v[12:15], v[116:119], v[208:211], v[12:15]
	v_mfma_f32_16x16x32_bf16 v[8:11], v[124:127], v[208:211], v[8:11]
	s_setprio 0
	s_setprio 1
	v_mfma_f32_16x16x32_bf16 v[52:55], v[128:131], v[160:163], v[52:55]
	v_mfma_f32_16x16x32_bf16 v[48:51], v[152:155], v[160:163], v[48:51]
	v_mfma_f32_16x16x32_bf16 v[36:39], v[128:131], v[168:171], v[36:39]
	v_mfma_f32_16x16x32_bf16 v[32:35], v[152:155], v[168:171], v[32:35]
	v_mfma_f32_16x16x32_bf16 v[20:23], v[128:131], v[176:179], v[20:23]
	v_mfma_f32_16x16x32_bf16 v[16:19], v[152:155], v[176:179], v[16:19]
	v_mfma_f32_16x16x32_bf16 v[4:7], v[128:131], v[184:187], v[4:7]
	v_mfma_f32_16x16x32_bf16 v[0:3], v[152:155], v[184:187], v[0:3]
	v_mfma_f32_16x16x32_bf16 v[52:55], v[140:143], v[164:167], v[52:55]
	v_mfma_f32_16x16x32_bf16 v[48:51], v[156:159], v[164:167], v[48:51]
	v_mfma_f32_16x16x32_bf16 v[36:39], v[140:143], v[172:175], v[36:39]
	v_mfma_f32_16x16x32_bf16 v[32:35], v[156:159], v[172:175], v[32:35]
	v_mfma_f32_16x16x32_bf16 v[20:23], v[140:143], v[180:183], v[20:23]
	v_mfma_f32_16x16x32_bf16 v[16:19], v[156:159], v[180:183], v[16:19]
	v_mfma_f32_16x16x32_bf16 v[4:7], v[140:143], v[208:211], v[4:7]
	v_mfma_f32_16x16x32_bf16 v[0:3], v[156:159], v[208:211], v[0:3]
	s_setprio 0
	s_barrier
	s_add_i32 s48, s48, 2
	s_add_u32 s46, s46, 0x100
	s_addc_u32 s47, s47, 0
	s_cmp_gt_u32 s48, 41
	s_mov_b64 s[18:19], s[20:21]
	s_cbranch_scc0 .LBB0_255
	s_and_b64 vcc, exec, s[14:15]
	s_cbranch_vccz .LBB0_258
	s_barrier

; #define PG8_STAGE(bufoff, gbase, voff) do { _Pragma("unroll") for (int _i = 0; _i < 2; ++_i) \
;         __builtin_amdgcn_global_load_lds((const unsigned*)((const char*)(gbase) + (voff)[_i]), (LAS unsigned*)(lds + (bufoff) + ldsw + _i * 8192), 16, 0, 0); } while (0)
; #define PG8_LDA(dst, b, h) do { _Pragma("unroll") for (int m = 0; m < 4; ++m) _Pragma("unroll") for (int k = 0; k < 2; ++k) dst[m][k] = *(const LAS bf16x8*)(lds + PG8_SA(b, h) + aoff + m * 2048 + k * 1024); } while (0)
; #define PG8_LDB(dst, b, h) do { _Pragma("unroll") for (int n = 0; n < 2; ++n) _Pragma("unroll") for (int k = 0; k < 2; ++k) dst[n][k] = *(const LAS bf16x8*)(lds + PG8_SB(b, h) + boff + n * 2048 + k * 1024); } while (0)
; #define PG8_MMA(ai, bj, At, Bt) do { __builtin_amdgcn_s_setprio(1); _Pragma("unroll") for (int m = 0; m < 4; ++m) _Pragma("unroll") for (int n = 0; n < 2; ++n) _Pragma("unroll") for (int k = 0; k < 2; ++k) \
;         acc[ai][bj][m][n] = __builtin_amdgcn_mfma_f32_16x16x32_bf16(Bt[n][k], At[m][k], acc[ai][bj][m][n], 0, 0, 0); __builtin_amdgcn_s_setprio(0); } while (0)
; #define PG8_WAIT_V(n) asm volatile("s_waitcnt vmcnt(" #n ")" ::: "memory")
; #define PG8_WAIT_L(n) asm volatile("s_waitcnt lgkmcnt(" #n ")" ::: "memory")
; #define PG8_BAR __builtin_amdgcn_s_barrier()
; #define PG8_SCHED __builtin_amdgcn_sched_barrier(0)
; template <class Epi, class Sched>
; __device__ __forceinline__ void gemm_phase(int wv, LAS unsigned char* lds, const Gemm g, const Sched& S, const Epi& E) {
;     ...
;         for (int t = 0; t < nt; t += 2) {
;             const bool last = (t == nt - 2);
;             const char* a1 = cA + (size_t)(t + 1) * kstep;
;             const char* a2 = last ? nA : cA + (size_t)(t + 2) * kstep; const char* b2 = last ? nB : cB + (size_t)(t + 2) * kstep;
;             const char* a3 = a2 + kstep; const char* b3 = b2 + kstep;
;             PG8_LDB(B0, 0, 0); PG8_LDB(B1, 0, 1); PG8_SCHED; PG8_LDA(At, 0, 0); PG8_STAGE(PG8_SA(1, 1), a1 + hstep, voffA);
;             PG8_WAIT_V(8); PG8_WAIT_L(0); PG8_BAR; PG8_MMA(0, 0, At, B0); PG8_MMA(0, 1, At, B1); PG8_BAR; PG8_SCHED;
;             PG8_LDA(At, 0, 1); PG8_STAGE(PG8_SB(0, 0), b2, voffB); PG8_STAGE(PG8_SB(0, 1), b2 + hstepB, voffB); PG8_STAGE(PG8_SA(0, 0), a2, voffA);
;             PG8_WAIT_V(8); PG8_WAIT_L(0); PG8_BAR; PG8_MMA(1, 0, At, B0); PG8_MMA(1, 1, At, B1); PG8_BAR; PG8_SCHED;
.LBB0_344:
	s_add_u32 s18, s2, 0xfffc0080
	s_addc_u32 s19, s3, -1
	s_add_i32 s47, 0, 0x10000
	s_cmp_eq_u32 s46, 12
	s_cselect_b32 s21, s11, s19
	s_cselect_b32 s20, s41, s18
	s_cselect_b32 s19, s13, s45
	s_cselect_b32 s18, s42, s43
	s_add_i32 s50, 0, 0x14000
	v_add_u32_e32 v156, s47, v145
	v_add_u32_e32 v172, s50, v145
	ds_read_b128 v[140:143], v156
	ds_read_b128 v[148:151], v156 offset:1024
	ds_read_b128 v[152:155], v156 offset:2048
	ds_read_b128 v[156:159], v156 offset:3072
	ds_read_b128 v[160:163], v172
	ds_read_b128 v[164:167], v172 offset:1024
	ds_read_b128 v[168:171], v172 offset:2048
	ds_read_b128 v[172:175], v172 offset:3072
	v_lshl_add_u64 v[218:219], s[2:3], 0, v[136:137]
	s_add_i32 m0, s27, 0xc000
	ds_read_b128 v[176:179], v147
	ds_read_b128 v[180:183], v147 offset:1024
	ds_read_b128 v[184:187], v147 offset:2048
	ds_read_b128 v[198:201], v147 offset:3072
	ds_read_b128 v[202:205], v147 offset:4096
	ds_read_b128 v[206:209], v147 offset:5120
	ds_read_b128 v[210:213], v147 offset:6144
	ds_read_b128 v[214:217], v147 offset:7168
	global_load_lds_dwordx4 v[218:219], off
	v_lshl_add_u64 v[218:219], s[2:3], 0, v[138:139]
	s_add_i32 m0, s27, 0xe000
	s_nop 0
	global_load_lds_dwordx4 v[218:219], off
	s_nop 0
	s_waitcnt vmcnt(8)
	s_waitcnt lgkmcnt(0)
	s_barrier
	s_setprio 1
	s_waitcnt lgkmcnt(0)
	v_mfma_f32_16x16x32_bf16 v[124:127], v[140:143], v[176:179], v[124:127]
	v_mfma_f32_16x16x32_bf16 v[120:123], v[152:155], v[176:179], v[120:123]
	v_mfma_f32_16x16x32_bf16 v[108:111], v[140:143], v[184:187], v[108:111]
	v_mfma_f32_16x16x32_bf16 v[104:107], v[152:155], v[184:187], v[104:107]
	v_mfma_f32_16x16x32_bf16 v[92:95], v[140:143], v[202:205], v[92:95]
	v_mfma_f32_16x16x32_bf16 v[88:91], v[152:155], v[202:205], v[88:91]
	v_mfma_f32_16x16x32_bf16 v[76:79], v[140:143], v[210:213], v[76:79]
	v_mfma_f32_16x16x32_bf16 v[72:75], v[152:155], v[210:213], v[72:75]
	v_mfma_f32_16x16x32_bf16 v[124:127], v[148:151], v[180:183], v[124:127]
	v_mfma_f32_16x16x32_bf16 v[120:123], v[156:159], v[180:183], v[120:123]
	v_mfma_f32_16x16x32_bf16 v[108:111], v[148:151], v[198:201], v[108:111]
	v_mfma_f32_16x16x32_bf16 v[104:107], v[156:159], v[198:201], v[104:107]
	v_mfma_f32_16x16x32_bf16 v[92:95], v[148:151], v[206:209], v[92:95]
	v_mfma_f32_16x16x32_bf16 v[88:91], v[156:159], v[206:209], v[88:91]
	v_mfma_f32_16x16x32_bf16 v[76:79], v[148:151], v[214:217], v[76:79]
	v_mfma_f32_16x16x32_bf16 v[72:75], v[156:159], v[214:217], v[72:75]
	s_setprio 0
	s_setprio 1
	v_mfma_f32_16x16x32_bf16 v[116:119], v[160:163], v[176:179], v[116:119]
	v_mfma_f32_16x16x32_bf16 v[112:115], v[168:171], v[176:179], v[112:115]
	v_mfma_f32_16x16x32_bf16 v[100:103], v[160:163], v[184:187], v[100:103]
	v_mfma_f32_16x16x32_bf16 v[96:99], v[168:171], v[184:187], v[96:99]
	v_mfma_f32_16x16x32_bf16 v[84:87], v[160:163], v[202:205], v[84:87]
	v_mfma_f32_16x16x32_bf16 v[80:83], v[168:171], v[202:205], v[80:83]
	v_mfma_f32_16x16x32_bf16 v[68:71], v[160:163], v[210:213], v[68:71]
	v_mfma_f32_16x16x32_bf16 v[64:67], v[168:171], v[210:213], v[64:67]
	v_mfma_f32_16x16x32_bf16 v[116:119], v[164:167], v[180:183], v[116:119]
	v_mfma_f32_16x16x32_bf16 v[112:115], v[172:175], v[180:183], v[112:115]
	v_mfma_f32_16x16x32_bf16 v[100:103], v[164:167], v[198:201], v[100:103]
	v_mfma_f32_16x16x32_bf16 v[96:99], v[172:175], v[198:201], v[96:99]
	v_mfma_f32_16x16x32_bf16 v[84:87], v[164:167], v[206:209], v[84:87]
	v_mfma_f32_16x16x32_bf16 v[80:83], v[172:175], v[206:209], v[80:83]
	v_mfma_f32_16x16x32_bf16 v[68:71], v[164:167], v[214:217], v[68:71]
	v_mfma_f32_16x16x32_bf16 v[64:67], v[172:175], v[214:217], v[64:67]
	s_setprio 0
	s_barrier
	s_add_i32 s47, s47, s26
	v_lshl_add_u64 v[218:219], s[18:19], 0, v[132:133]
	s_mov_b32 m0, s47
	ds_read_b128 v[176:179], v147 offset:16384
	ds_read_b128 v[180:183], v147 offset:17408
	ds_read_b128 v[184:187], v147 offset:18432
	ds_read_b128 v[198:201], v147 offset:19456
	ds_read_b128 v[202:205], v147 offset:20480
	ds_read_b128 v[206:209], v147 offset:21504
	ds_read_b128 v[210:213], v147 offset:22528
	ds_read_b128 v[214:217], v147 offset:23552
	global_load_lds_dwordx4 v[218:219], off
	s_add_i32 m0, s47, 0x2000
	s_add_u32 s48, s18, 0x4000
	v_lshl_add_u64 v[220:221], s[18:19], 0, v[128:129]
	s_addc_u32 s49, s19, 0
	s_add_i32 s47, s50, s26
	global_load_lds_dwordx4 v[220:221], off
	v_lshl_add_u64 v[222:223], s[48:49], 0, v[132:133]
	s_mov_b32 m0, s47
	v_lshl_add_u64 v[228:229], s[20:21], 0, v[130:131]
	global_load_lds_dwordx4 v[222:223], off
	v_lshl_add_u64 v[222:223], s[48:49], 0, v[128:129]
	s_add_i32 m0, s47, 0x2000
	s_nop 0
	global_load_lds_dwordx4 v[222:223], off
	v_lshl_add_u64 v[222:223], s[20:21], 0, v[134:135]
	s_mov_b32 m0, s27
	s_nop 0
	global_load_lds_dwordx4 v[222:223], off
	s_mov_b32 m0, s28
	s_nop 0
	global_load_lds_dwordx4 v[228:229], off
	s_nop 0
	s_waitcnt vmcnt(8)
	s_waitcnt lgkmcnt(0)
	s_barrier
; #define PG8_STAGE(bufoff, gbase, voff) do { _Pragma("unroll") for (int _i = 0; _i < 2; ++_i) \
;         __builtin_amdgcn_global_load_lds((const unsigned*)((const char*)(gbase) + (voff)[_i]), (LAS unsigned*)(lds + (bufoff) + ldsw + _i * 8192), 16, 0, 0); } while (0)
; #define PG8_LDA(dst, b, h) do { _Pragma("unroll") for (int m = 0; m < 4; ++m) _Pragma("unroll") for (int k = 0; k < 2; ++k) dst[m][k] = *(const LAS bf16x8*)(lds + PG8_SA(b, h) + aoff + m * 2048 + k * 1024); } while (0)
; #define PG8_LDB(dst, b, h) do { _Pragma("unroll") for (int n = 0; n < 2; ++n) _Pragma("unroll") for (int k = 0; k < 2; ++k) dst[n][k] = *(const LAS bf16x8*)(lds + PG8_SB(b, h) + boff + n * 2048 + k * 1024); } while (0)
; #define PG8_MMA(ai, bj, At, Bt) do { __builtin_amdgcn_s_setprio(1); _Pragma("unroll") for (int m = 0; m < 4; ++m) _Pragma("unroll") for (int n = 0; n < 2; ++n) _Pragma("unroll") for (int k = 0; k < 2; ++k) \
;         acc[ai][bj][m][n] = __builtin_amdgcn_mfma_f32_16x16x32_bf16(Bt[n][k], At[m][k], acc[ai][bj][m][n], 0, 0, 0); __builtin_amdgcn_s_setprio(0); } while (0)
; #define PG8_WAIT_V(n) asm volatile("s_waitcnt vmcnt(" #n ")" ::: "memory")
; #define PG8_WAIT_L(n) asm volatile("s_waitcnt lgkmcnt(" #n ")" ::: "memory")
; #define PG8_BAR __builtin_amdgcn_s_barrier()
; #define PG8_SCHED __builtin_amdgcn_sched_barrier(0)
; template <class Epi, class Sched>
; __device__ __forceinline__ void gemm_phase(int wv, LAS unsigned char* lds, const Gemm g, const Sched& S, const Epi& E) {
;     ...
;             PG8_WAIT_V(8); PG8_WAIT_L(0); PG8_BAR; PG8_MMA(1, 0, At, B0); PG8_MMA(1, 1, At, B1); PG8_BAR; PG8_SCHED;
;             PG8_LDB(B0, 1, 0); PG8_LDB(B1, 1, 1); PG8_SCHED; PG8_LDA(At, 1, 0); PG8_STAGE(PG8_SA(0, 1), a2 + hstep, voffA);
;             PG8_WAIT_V(8); PG8_WAIT_L(0); PG8_BAR; PG8_MMA(0, 0, At, B0); PG8_MMA(0, 1, At, B1); PG8_BAR; PG8_SCHED;
	s_setprio 1
	s_waitcnt lgkmcnt(0)
	v_mfma_f32_16x16x32_bf16 v[60:63], v[140:143], v[176:179], v[60:63]
	v_mfma_f32_16x16x32_bf16 v[56:59], v[152:155], v[176:179], v[56:59]
	v_mfma_f32_16x16x32_bf16 v[44:47], v[140:143], v[184:187], v[44:47]
	v_mfma_f32_16x16x32_bf16 v[40:43], v[152:155], v[184:187], v[40:43]
	v_mfma_f32_16x16x32_bf16 v[28:31], v[140:143], v[202:205], v[28:31]
	v_mfma_f32_16x16x32_bf16 v[24:27], v[152:155], v[202:205], v[24:27]
	v_mfma_f32_16x16x32_bf16 v[12:15], v[140:143], v[210:213], v[12:15]
	v_mfma_f32_16x16x32_bf16 v[8:11], v[152:155], v[210:213], v[8:11]
	v_mfma_f32_16x16x32_bf16 v[60:63], v[148:151], v[180:183], v[60:63]
	v_mfma_f32_16x16x32_bf16 v[56:59], v[156:159], v[180:183], v[56:59]
	v_mfma_f32_16x16x32_bf16 v[44:47], v[148:151], v[198:201], v[44:47]
	v_mfma_f32_16x16x32_bf16 v[40:43], v[156:159], v[198:201], v[40:43]
	v_mfma_f32_16x16x32_bf16 v[28:31], v[148:151], v[206:209], v[28:31]
	v_mfma_f32_16x16x32_bf16 v[24:27], v[156:159], v[206:209], v[24:27]
	v_mfma_f32_16x16x32_bf16 v[12:15], v[148:151], v[214:217], v[12:15]
	v_mfma_f32_16x16x32_bf16 v[8:11], v[156:159], v[214:217], v[8:11]
	s_setprio 0
	s_setprio 1
	v_mfma_f32_16x16x32_bf16 v[52:55], v[160:163], v[176:179], v[52:55]
	v_mfma_f32_16x16x32_bf16 v[48:51], v[168:171], v[176:179], v[48:51]
	v_mfma_f32_16x16x32_bf16 v[36:39], v[160:163], v[184:187], v[36:39]
	v_mfma_f32_16x16x32_bf16 v[32:35], v[168:171], v[184:187], v[32:35]
	v_mfma_f32_16x16x32_bf16 v[20:23], v[160:163], v[202:205], v[20:23]
	v_mfma_f32_16x16x32_bf16 v[16:19], v[168:171], v[202:205], v[16:19]
	v_mfma_f32_16x16x32_bf16 v[4:7], v[160:163], v[210:213], v[4:7]
	v_mfma_f32_16x16x32_bf16 v[0:3], v[168:171], v[210:213], v[0:3]
	v_mfma_f32_16x16x32_bf16 v[52:55], v[164:167], v[180:183], v[52:55]
	v_mfma_f32_16x16x32_bf16 v[48:51], v[172:175], v[180:183], v[48:51]
	v_mfma_f32_16x16x32_bf16 v[36:39], v[164:167], v[198:201], v[36:39]
	v_mfma_f32_16x16x32_bf16 v[32:35], v[172:175], v[198:201], v[32:35]
	v_mfma_f32_16x16x32_bf16 v[20:23], v[164:167], v[206:209], v[20:23]
	v_mfma_f32_16x16x32_bf16 v[16:19], v[172:175], v[206:209], v[16:19]
	v_mfma_f32_16x16x32_bf16 v[4:7], v[164:167], v[214:217], v[4:7]
	v_mfma_f32_16x16x32_bf16 v[0:3], v[172:175], v[214:217], v[0:3]
	s_setprio 0
	s_barrier
	s_add_i32 s47, 0, 0x18000
	s_add_i32 s48, 0, 0x1c000
	v_add_u32_e32 v156, s47, v145
	v_add_u32_e32 v172, s48, v145
	ds_read_b128 v[140:143], v156
	ds_read_b128 v[148:151], v156 offset:1024
	ds_read_b128 v[152:155], v156 offset:2048
	ds_read_b128 v[156:159], v156 offset:3072
	ds_read_b128 v[160:163], v172
	ds_read_b128 v[164:167], v172 offset:1024
	ds_read_b128 v[168:171], v172 offset:2048
	ds_read_b128 v[172:175], v172 offset:3072
	s_add_u32 s20, s20, 0x40000
	s_addc_u32 s21, s21, 0
	s_mov_b32 m0, s29
	v_lshl_add_u64 v[230:231], s[20:21], 0, v[134:135]
	ds_read_b128 v[176:179], v147 offset:32768
	ds_read_b128 v[180:183], v147 offset:33792
	ds_read_b128 v[184:187], v147 offset:34816
	ds_read_b128 v[198:201], v147 offset:35840
	ds_read_b128 v[202:205], v147 offset:36864
	ds_read_b128 v[206:209], v147 offset:37888
	ds_read_b128 v[210:213], v147 offset:38912
	ds_read_b128 v[214:217], v147 offset:39936
	global_load_lds_dwordx4 v[230:231], off
	v_lshl_add_u64 v[230:231], s[20:21], 0, v[130:131]
	s_mov_b32 m0, s30
	s_nop 0
	global_load_lds_dwordx4 v[230:231], off
	s_nop 0
	s_waitcnt vmcnt(8)
	s_waitcnt lgkmcnt(0)
	s_barrier
	s_setprio 1
	s_waitcnt lgkmcnt(0)
	v_mfma_f32_16x16x32_bf16 v[124:127], v[140:143], v[176:179], v[124:127]
	v_mfma_f32_16x16x32_bf16 v[120:123], v[152:155], v[176:179], v[120:123]
	v_mfma_f32_16x16x32_bf16 v[108:111], v[140:143], v[184:187], v[108:111]
	v_mfma_f32_16x16x32_bf16 v[104:107], v[152:155], v[184:187], v[104:107]
	v_mfma_f32_16x16x32_bf16 v[92:95], v[140:143], v[202:205], v[92:95]
	v_mfma_f32_16x16x32_bf16 v[88:91], v[152:155], v[202:205], v[88:91]
	v_mfma_f32_16x16x32_bf16 v[76:79], v[140:143], v[210:213], v[76:79]
	v_mfma_f32_16x16x32_bf16 v[72:75], v[152:155], v[210:213], v[72:75]
	v_mfma_f32_16x16x32_bf16 v[124:127], v[148:151], v[180:183], v[124:127]
	v_mfma_f32_16x16x32_bf16 v[120:123], v[156:159], v[180:183], v[120:123]
	v_mfma_f32_16x16x32_bf16 v[108:111], v[148:151], v[198:201], v[108:111]
	v_mfma_f32_16x16x32_bf16 v[104:107], v[156:159], v[198:201], v[104:107]
	v_mfma_f32_16x16x32_bf16 v[92:95], v[148:151], v[206:209], v[92:95]
	v_mfma_f32_16x16x32_bf16 v[88:91], v[156:159], v[206:209], v[88:91]
	v_mfma_f32_16x16x32_bf16 v[76:79], v[148:151], v[214:217], v[76:79]
	v_mfma_f32_16x16x32_bf16 v[72:75], v[156:159], v[214:217], v[72:75]
	s_setprio 0
	s_setprio 1
	v_mfma_f32_16x16x32_bf16 v[116:119], v[160:163], v[176:179], v[116:119]
	v_mfma_f32_16x16x32_bf16 v[112:115], v[168:171], v[176:179], v[112:115]
	v_mfma_f32_16x16x32_bf16 v[100:103], v[160:163], v[184:187], v[100:103]
	v_mfma_f32_16x16x32_bf16 v[96:99], v[168:171], v[184:187], v[96:99]
	v_mfma_f32_16x16x32_bf16 v[84:87], v[160:163], v[202:205], v[84:87]
	v_mfma_f32_16x16x32_bf16 v[80:83], v[168:171], v[202:205], v[80:83]
	v_mfma_f32_16x16x32_bf16 v[68:71], v[160:163], v[210:213], v[68:71]
	v_mfma_f32_16x16x32_bf16 v[64:67], v[168:171], v[210:213], v[64:67]
	v_mfma_f32_16x16x32_bf16 v[116:119], v[164:167], v[180:183], v[116:119]
	v_mfma_f32_16x16x32_bf16 v[112:115], v[172:175], v[180:183], v[112:115]
	v_mfma_f32_16x16x32_bf16 v[100:103], v[164:167], v[198:201], v[100:103]
	v_mfma_f32_16x16x32_bf16 v[96:99], v[172:175], v[198:201], v[96:99]
	v_mfma_f32_16x16x32_bf16 v[84:87], v[164:167], v[206:209], v[84:87]
	v_mfma_f32_16x16x32_bf16 v[80:83], v[172:175], v[206:209], v[80:83]
	v_mfma_f32_16x16x32_bf16 v[68:71], v[164:167], v[214:217], v[68:71]
	v_mfma_f32_16x16x32_bf16 v[64:67], v[172:175], v[214:217], v[64:67]
	s_setprio 0
	s_barrier
; #define PG8_STAGE(bufoff, gbase, voff) do { _Pragma("unroll") for (int _i = 0; _i < 2; ++_i) \
;         __builtin_amdgcn_global_load_lds((const unsigned*)((const char*)(gbase) + (voff)[_i]), (LAS unsigned*)(lds + (bufoff) + ldsw + _i * 8192), 16, 0, 0); } while (0)
; #define PG8_LDA(dst, b, h) do { _Pragma("unroll") for (int m = 0; m < 4; ++m) _Pragma("unroll") for (int k = 0; k < 2; ++k) dst[m][k] = *(const LAS bf16x8*)(lds + PG8_SA(b, h) + aoff + m * 2048 + k * 1024); } while (0)
; #define PG8_MMA(ai, bj, At, Bt) do { __builtin_amdgcn_s_setprio(1); _Pragma("unroll") for (int m = 0; m < 4; ++m) _Pragma("unroll") for (int n = 0; n < 2; ++n) _Pragma("unroll") for (int k = 0; k < 2; ++k) \
;         acc[ai][bj][m][n] = __builtin_amdgcn_mfma_f32_16x16x32_bf16(Bt[n][k], At[m][k], acc[ai][bj][m][n], 0, 0, 0); __builtin_amdgcn_s_setprio(0); } while (0)
; #define PG8_WAIT_V(n) asm volatile("s_waitcnt vmcnt(" #n ")" ::: "memory")
; #define PG8_WAIT_L(n) asm volatile("s_waitcnt lgkmcnt(" #n ")" ::: "memory")
; #define PG8_BAR __builtin_amdgcn_s_barrier()
; #define PG8_SCHED __builtin_amdgcn_sched_barrier(0)
; template <class Epi, class Sched>
; __device__ __forceinline__ void gemm_phase(int wv, LAS unsigned char* lds, const Gemm g, const Sched& S, const Epi& E) {
;     ...
;             PG8_LDA(At, 1, 1); PG8_STAGE(PG8_SB(1, 0), b3, voffB); PG8_STAGE(PG8_SB(1, 1), b3 + hstepB, voffB); PG8_STAGE(PG8_SA(1, 0), a3, voffA);
;             PG8_WAIT_V(8); PG8_WAIT_L(0); PG8_BAR; PG8_MMA(1, 0, At, B0); PG8_MMA(1, 1, At, B1); PG8_BAR; PG8_SCHED;
;         }
;         if (wr == 0) PG8_BAR;
	s_add_i32 s20, s47, s26
	v_lshl_add_u64 v[218:219], v[218:219], 0, s[74:75]
	s_mov_b32 m0, s20
	ds_read_b128 v[176:179], v147 offset:49152
	ds_read_b128 v[180:183], v147 offset:50176
	ds_read_b128 v[184:187], v147 offset:51200
	ds_read_b128 v[198:201], v147 offset:52224
	ds_read_b128 v[202:205], v147 offset:53248
	ds_read_b128 v[206:209], v147 offset:54272
	ds_read_b128 v[210:213], v147 offset:55296
	ds_read_b128 v[214:217], v147 offset:56320
	global_load_lds_dwordx4 v[218:219], off
	s_add_i32 m0, s20, 0x2000
	s_add_u32 s18, s18, 0x4080
	v_lshl_add_u64 v[218:219], v[220:221], 0, s[74:75]
	s_addc_u32 s19, s19, 0
	s_add_i32 s20, s48, s26
	global_load_lds_dwordx4 v[218:219], off
	v_lshl_add_u64 v[218:219], s[18:19], 0, v[132:133]
	s_mov_b32 m0, s20
	s_nop 0
	global_load_lds_dwordx4 v[218:219], off
	v_lshl_add_u64 v[218:219], s[18:19], 0, v[128:129]
	s_add_i32 m0, s20, 0x2000
	s_nop 0
	global_load_lds_dwordx4 v[218:219], off
	v_lshl_add_u64 v[218:219], v[222:223], 0, s[74:75]
	s_mov_b32 m0, s37
	s_nop 0
	global_load_lds_dwordx4 v[218:219], off
	v_lshl_add_u64 v[218:219], v[228:229], 0, s[74:75]
	s_mov_b32 m0, s38
	s_nop 0
	global_load_lds_dwordx4 v[218:219], off
	s_waitcnt vmcnt(8)
	s_waitcnt lgkmcnt(0)
	s_barrier
	s_setprio 1
	s_waitcnt lgkmcnt(0)
	v_mfma_f32_16x16x32_bf16 v[60:63], v[140:143], v[176:179], v[60:63]
	v_mfma_f32_16x16x32_bf16 v[56:59], v[152:155], v[176:179], v[56:59]
	v_mfma_f32_16x16x32_bf16 v[44:47], v[140:143], v[184:187], v[44:47]
	v_mfma_f32_16x16x32_bf16 v[40:43], v[152:155], v[184:187], v[40:43]
	v_mfma_f32_16x16x32_bf16 v[28:31], v[140:143], v[202:205], v[28:31]
	v_mfma_f32_16x16x32_bf16 v[24:27], v[152:155], v[202:205], v[24:27]
	v_mfma_f32_16x16x32_bf16 v[12:15], v[140:143], v[210:213], v[12:15]
	v_mfma_f32_16x16x32_bf16 v[8:11], v[152:155], v[210:213], v[8:11]
	v_mfma_f32_16x16x32_bf16 v[60:63], v[148:151], v[180:183], v[60:63]
	v_mfma_f32_16x16x32_bf16 v[56:59], v[156:159], v[180:183], v[56:59]
	v_mfma_f32_16x16x32_bf16 v[44:47], v[148:151], v[198:201], v[44:47]
	v_mfma_f32_16x16x32_bf16 v[40:43], v[156:159], v[198:201], v[40:43]
	v_mfma_f32_16x16x32_bf16 v[28:31], v[148:151], v[206:209], v[28:31]
	v_mfma_f32_16x16x32_bf16 v[24:27], v[156:159], v[206:209], v[24:27]
	v_mfma_f32_16x16x32_bf16 v[12:15], v[148:151], v[214:217], v[12:15]
	v_mfma_f32_16x16x32_bf16 v[8:11], v[156:159], v[214:217], v[8:11]
	s_setprio 0
	s_setprio 1
	v_mfma_f32_16x16x32_bf16 v[52:55], v[160:163], v[176:179], v[52:55]
	v_mfma_f32_16x16x32_bf16 v[48:51], v[168:171], v[176:179], v[48:51]
	v_mfma_f32_16x16x32_bf16 v[36:39], v[160:163], v[184:187], v[36:39]
	v_mfma_f32_16x16x32_bf16 v[32:35], v[168:171], v[184:187], v[32:35]
	v_mfma_f32_16x16x32_bf16 v[20:23], v[160:163], v[202:205], v[20:23]
	v_mfma_f32_16x16x32_bf16 v[16:19], v[168:171], v[202:205], v[16:19]
	v_mfma_f32_16x16x32_bf16 v[4:7], v[160:163], v[210:213], v[4:7]
	v_mfma_f32_16x16x32_bf16 v[0:3], v[168:171], v[210:213], v[0:3]
	v_mfma_f32_16x16x32_bf16 v[52:55], v[164:167], v[180:183], v[52:55]
	v_mfma_f32_16x16x32_bf16 v[48:51], v[172:175], v[180:183], v[48:51]
	v_mfma_f32_16x16x32_bf16 v[36:39], v[164:167], v[198:201], v[36:39]
	v_mfma_f32_16x16x32_bf16 v[32:35], v[172:175], v[198:201], v[32:35]
	v_mfma_f32_16x16x32_bf16 v[20:23], v[164:167], v[206:209], v[20:23]
	v_mfma_f32_16x16x32_bf16 v[16:19], v[172:175], v[206:209], v[16:19]
	v_mfma_f32_16x16x32_bf16 v[4:7], v[164:167], v[214:217], v[4:7]
	v_mfma_f32_16x16x32_bf16 v[0:3], v[172:175], v[214:217], v[0:3]
	s_setprio 0
	s_barrier
	s_add_i32 s46, s46, 2
	s_add_u32 s2, s2, 0x100
	s_addc_u32 s3, s3, 0
	s_add_u32 s43, s43, 0x100
	s_addc_u32 s45, s45, 0
	s_cmp_gt_u32 s46, 13
	s_cbranch_scc0 .LBB0_344
	s_and_b64 vcc, exec, s[8:9]
	s_cbranch_vccz .LBB0_347
	s_barrier

; #define PG8_STAGE(bufoff, gbase, voff) do { _Pragma("unroll") for (int _i = 0; _i < 2; ++_i) \
;         __builtin_amdgcn_global_load_lds((const unsigned*)((const char*)(gbase) + (voff)[_i]), (LAS unsigned*)(lds + (bufoff) + ldsw + _i * 8192), 16, 0, 0); } while (0)
; #define PG8_LDA(dst, b, h) do { _Pragma("unroll") for (int m = 0; m < 4; ++m) _Pragma("unroll") for (int k = 0; k < 2; ++k) dst[m][k] = *(const LAS bf16x8*)(lds + PG8_SA(b, h) + aoff + m * 2048 + k * 1024); } while (0)
; #define PG8_LDB(dst, b, h) do { _Pragma("unroll") for (int n = 0; n < 2; ++n) _Pragma("unroll") for (int k = 0; k < 2; ++k) dst[n][k] = *(const LAS bf16x8*)(lds + PG8_SB(b, h) + boff + n * 2048 + k * 1024); } while (0)
; #define PG8_MMA(ai, bj, At, Bt) do { __builtin_amdgcn_s_setprio(1); _Pragma("unroll") for (int m = 0; m < 4; ++m) _Pragma("unroll") for (int n = 0; n < 2; ++n) _Pragma("unroll") for (int k = 0; k < 2; ++k) \
;         acc[ai][bj][m][n] = __builtin_amdgcn_mfma_f32_16x16x32_bf16(Bt[n][k], At[m][k], acc[ai][bj][m][n], 0, 0, 0); __builtin_amdgcn_s_setprio(0); } while (0)
; #define PG8_WAIT_V(n) asm volatile("s_waitcnt vmcnt(" #n ")" ::: "memory")
; #define PG8_WAIT_L(n) asm volatile("s_waitcnt lgkmcnt(" #n ")" ::: "memory")
; #define PG8_BAR __builtin_amdgcn_s_barrier()
; #define PG8_SCHED __builtin_amdgcn_sched_barrier(0)
; template <class Epi, class Sched>
; __device__ __forceinline__ void gemm_phase(int wv, LAS unsigned char* lds, const Gemm g, const Sched& S, const Epi& E) {
;     ...
;         for (int t = 0; t < nt; t += 2) {
;             const bool last = (t == nt - 2);
;             const char* a1 = cA + (size_t)(t + 1) * kstep;
;             const char* a2 = last ? nA : cA + (size_t)(t + 2) * kstep; const char* b2 = last ? nB : cB + (size_t)(t + 2) * kstep;
;             const char* a3 = a2 + kstep; const char* b3 = b2 + kstep;
;             PG8_LDB(B0, 0, 0); PG8_LDB(B1, 0, 1); PG8_SCHED; PG8_LDA(At, 0, 0); PG8_STAGE(PG8_SA(1, 1), a1 + hstep, voffA);
;             PG8_WAIT_V(8); PG8_WAIT_L(0); PG8_BAR; PG8_MMA(0, 0, At, B0); PG8_MMA(0, 1, At, B1); PG8_BAR; PG8_SCHED;
;             PG8_LDA(At, 0, 1); PG8_STAGE(PG8_SB(0, 0), b2, voffB); PG8_STAGE(PG8_SB(0, 1), b2 + hstepB, voffB); PG8_STAGE(PG8_SA(0, 0), a2, voffA);
;             PG8_WAIT_V(8); PG8_WAIT_L(0); PG8_BAR; PG8_MMA(1, 0, At, B0); PG8_MMA(1, 1, At, B1); PG8_BAR; PG8_SCHED;
.LBB0_542:
	s_add_u32 s28, s4, 0xfffc0080
	s_addc_u32 s29, s5, -1
	s_add_i32 s55, 0, 0x10000
	s_cmp_eq_u32 s54, 12
	s_cselect_b32 s31, s21, s29
	s_cselect_b32 s30, s50, s28
	s_cselect_b32 s29, s23, s53
	s_cselect_b32 s28, s51, s52
	s_add_i32 s58, 0, 0x14000
	v_add_u32_e32 v60, s55, v206
	s_waitcnt vmcnt(0)
	v_add_u32_e32 v92, s58, v206
	ds_read_b128 v[48:51], v60
	ds_read_b128 v[52:55], v60 offset:1024
	ds_read_b128 v[56:59], v60 offset:2048
	ds_read_b128 v[60:63], v60 offset:3072
	ds_read_b128 v[64:67], v92
	ds_read_b128 v[68:71], v92 offset:1024
	ds_read_b128 v[88:91], v92 offset:2048
	ds_read_b128 v[92:95], v92 offset:3072
	v_lshl_add_u64 v[222:223], s[4:5], 0, v[174:175]
	s_add_i32 m0, s41, 0xc000
	ds_read_b128 v[180:183], v209
	ds_read_b128 v[184:187], v209 offset:1024
	ds_read_b128 v[198:201], v209 offset:2048
	ds_read_b128 v[202:205], v209 offset:3072
	ds_read_b128 v[210:213], v209 offset:4096
	ds_read_b128 v[214:217], v209 offset:5120
	ds_read_b128 v[218:221], v209 offset:6144
	ds_read_b128 v[228:231], v209 offset:7168
	global_load_lds_dwordx4 v[222:223], off
	v_lshl_add_u64 v[222:223], s[4:5], 0, v[176:177]
	s_add_i32 m0, s41, 0xe000
	s_nop 0
	global_load_lds_dwordx4 v[222:223], off
	s_waitcnt vmcnt(8)
	s_waitcnt lgkmcnt(0)
	s_barrier
	s_setprio 1
	s_waitcnt lgkmcnt(0)
	v_mfma_f32_16x16x32_bf16 v[156:159], v[48:51], v[180:183], v[156:159]
	v_mfma_f32_16x16x32_bf16 v[152:155], v[56:59], v[180:183], v[152:155]
	v_mfma_f32_16x16x32_bf16 v[140:143], v[48:51], v[198:201], v[140:143]
	v_mfma_f32_16x16x32_bf16 v[136:139], v[56:59], v[198:201], v[136:139]
	v_mfma_f32_16x16x32_bf16 v[124:127], v[48:51], v[210:213], v[124:127]
	v_mfma_f32_16x16x32_bf16 v[120:123], v[56:59], v[210:213], v[120:123]
	v_mfma_f32_16x16x32_bf16 v[108:111], v[48:51], v[218:221], v[108:111]
	v_mfma_f32_16x16x32_bf16 v[104:107], v[56:59], v[218:221], v[104:107]
	v_mfma_f32_16x16x32_bf16 v[156:159], v[52:55], v[184:187], v[156:159]
	v_mfma_f32_16x16x32_bf16 v[152:155], v[60:63], v[184:187], v[152:155]
	v_mfma_f32_16x16x32_bf16 v[140:143], v[52:55], v[202:205], v[140:143]
	v_mfma_f32_16x16x32_bf16 v[136:139], v[60:63], v[202:205], v[136:139]
	v_mfma_f32_16x16x32_bf16 v[124:127], v[52:55], v[214:217], v[124:127]
	v_mfma_f32_16x16x32_bf16 v[120:123], v[60:63], v[214:217], v[120:123]
	v_mfma_f32_16x16x32_bf16 v[108:111], v[52:55], v[228:231], v[108:111]
	v_mfma_f32_16x16x32_bf16 v[104:107], v[60:63], v[228:231], v[104:107]
	s_setprio 0
	s_setprio 1
	v_mfma_f32_16x16x32_bf16 v[148:151], v[64:67], v[180:183], v[148:151]
	v_mfma_f32_16x16x32_bf16 v[144:147], v[88:91], v[180:183], v[144:147]
	v_mfma_f32_16x16x32_bf16 v[132:135], v[64:67], v[198:201], v[132:135]
	v_mfma_f32_16x16x32_bf16 v[128:131], v[88:91], v[198:201], v[128:131]
	v_mfma_f32_16x16x32_bf16 v[116:119], v[64:67], v[210:213], v[116:119]
	v_mfma_f32_16x16x32_bf16 v[112:115], v[88:91], v[210:213], v[112:115]
	v_mfma_f32_16x16x32_bf16 v[100:103], v[64:67], v[218:221], v[100:103]
	v_mfma_f32_16x16x32_bf16 v[96:99], v[88:91], v[218:221], v[96:99]
	v_mfma_f32_16x16x32_bf16 v[148:151], v[68:71], v[184:187], v[148:151]
	v_mfma_f32_16x16x32_bf16 v[144:147], v[92:95], v[184:187], v[144:147]
	v_mfma_f32_16x16x32_bf16 v[132:135], v[68:71], v[202:205], v[132:135]
	v_mfma_f32_16x16x32_bf16 v[128:131], v[92:95], v[202:205], v[128:131]
	v_mfma_f32_16x16x32_bf16 v[116:119], v[68:71], v[214:217], v[116:119]
	v_mfma_f32_16x16x32_bf16 v[112:115], v[92:95], v[214:217], v[112:115]
	v_mfma_f32_16x16x32_bf16 v[100:103], v[68:71], v[228:231], v[100:103]
	v_mfma_f32_16x16x32_bf16 v[96:99], v[92:95], v[228:231], v[96:99]
	s_setprio 0
	s_barrier
	s_add_i32 s55, s55, s40
	v_lshl_add_u64 v[222:223], s[28:29], 0, v[164:165]
	s_mov_b32 m0, s55
	ds_read_b128 v[180:183], v209 offset:16384
	ds_read_b128 v[184:187], v209 offset:17408
	ds_read_b128 v[198:201], v209 offset:18432
	ds_read_b128 v[202:205], v209 offset:19456
	ds_read_b128 v[210:213], v209 offset:20480
	ds_read_b128 v[214:217], v209 offset:21504
	ds_read_b128 v[218:221], v209 offset:22528
	ds_read_b128 v[228:231], v209 offset:23552
	global_load_lds_dwordx4 v[222:223], off
	s_add_i32 m0, s55, 0x2000
	s_add_u32 s56, s28, 0x20000
	v_lshl_add_u64 v[240:241], s[28:29], 0, v[160:161]
	s_addc_u32 s57, s29, 0
	s_add_i32 s55, s58, s40
	global_load_lds_dwordx4 v[240:241], off
	v_lshl_add_u64 v[232:233], s[56:57], 0, v[164:165]
	s_mov_b32 m0, s55
	v_lshl_add_u64 v[242:243], s[30:31], 0, v[166:167]
	global_load_lds_dwordx4 v[232:233], off
	v_lshl_add_u64 v[232:233], s[56:57], 0, v[160:161]
	s_add_i32 m0, s55, 0x2000
	v_lshl_add_u64 v[244:245], s[30:31], 0, v[162:163]
	global_load_lds_dwordx4 v[232:233], off
	s_mov_b32 m0, s41
	s_nop 0
	global_load_lds_dwordx4 v[242:243], off
	s_mov_b32 m0, s42
	s_nop 0
	global_load_lds_dwordx4 v[244:245], off
	s_waitcnt vmcnt(8)
	s_waitcnt lgkmcnt(0)
	s_barrier
; #define PG8_STAGE(bufoff, gbase, voff) do { _Pragma("unroll") for (int _i = 0; _i < 2; ++_i) \
;         __builtin_amdgcn_global_load_lds((const unsigned*)((const char*)(gbase) + (voff)[_i]), (LAS unsigned*)(lds + (bufoff) + ldsw + _i * 8192), 16, 0, 0); } while (0)
; #define PG8_LDA(dst, b, h) do { _Pragma("unroll") for (int m = 0; m < 4; ++m) _Pragma("unroll") for (int k = 0; k < 2; ++k) dst[m][k] = *(const LAS bf16x8*)(lds + PG8_SA(b, h) + aoff + m * 2048 + k * 1024); } while (0)
; #define PG8_LDB(dst, b, h) do { _Pragma("unroll") for (int n = 0; n < 2; ++n) _Pragma("unroll") for (int k = 0; k < 2; ++k) dst[n][k] = *(const LAS bf16x8*)(lds + PG8_SB(b, h) + boff + n * 2048 + k * 1024); } while (0)
; #define PG8_MMA(ai, bj, At, Bt) do { __builtin_amdgcn_s_setprio(1); _Pragma("unroll") for (int m = 0; m < 4; ++m) _Pragma("unroll") for (int n = 0; n < 2; ++n) _Pragma("unroll") for (int k = 0; k < 2; ++k) \
;         acc[ai][bj][m][n] = __builtin_amdgcn_mfma_f32_16x16x32_bf16(Bt[n][k], At[m][k], acc[ai][bj][m][n], 0, 0, 0); __builtin_amdgcn_s_setprio(0); } while (0)
; #define PG8_WAIT_V(n) asm volatile("s_waitcnt vmcnt(" #n ")" ::: "memory")
; #define PG8_WAIT_L(n) asm volatile("s_waitcnt lgkmcnt(" #n ")" ::: "memory")
; #define PG8_BAR __builtin_amdgcn_s_barrier()
; #define PG8_SCHED __builtin_amdgcn_sched_barrier(0)
; template <class Epi, class Sched>
; __device__ __forceinline__ void gemm_phase(int wv, LAS unsigned char* lds, const Gemm g, const Sched& S, const Epi& E) {
;     ...
;             PG8_WAIT_V(8); PG8_WAIT_L(0); PG8_BAR; PG8_MMA(1, 0, At, B0); PG8_MMA(1, 1, At, B1); PG8_BAR; PG8_SCHED;
;             PG8_LDB(B0, 1, 0); PG8_LDB(B1, 1, 1); PG8_SCHED; PG8_LDA(At, 1, 0); PG8_STAGE(PG8_SA(0, 1), a2 + hstep, voffA);
;             PG8_WAIT_V(8); PG8_WAIT_L(0); PG8_BAR; PG8_MMA(0, 0, At, B0); PG8_MMA(0, 1, At, B1); PG8_BAR; PG8_SCHED;
	s_setprio 1
	s_waitcnt lgkmcnt(0)
	v_mfma_f32_16x16x32_bf16 v[84:87], v[48:51], v[180:183], v[84:87]
	v_mfma_f32_16x16x32_bf16 v[80:83], v[56:59], v[180:183], v[80:83]
	v_mfma_f32_16x16x32_bf16 v[44:47], v[48:51], v[198:201], v[44:47]
	v_mfma_f32_16x16x32_bf16 v[40:43], v[56:59], v[198:201], v[40:43]
	v_mfma_f32_16x16x32_bf16 v[28:31], v[48:51], v[210:213], v[28:31]
	v_mfma_f32_16x16x32_bf16 v[24:27], v[56:59], v[210:213], v[24:27]
	v_mfma_f32_16x16x32_bf16 v[12:15], v[48:51], v[218:221], v[12:15]
	v_mfma_f32_16x16x32_bf16 v[8:11], v[56:59], v[218:221], v[8:11]
	v_mfma_f32_16x16x32_bf16 v[84:87], v[52:55], v[184:187], v[84:87]
	v_mfma_f32_16x16x32_bf16 v[80:83], v[60:63], v[184:187], v[80:83]
	v_mfma_f32_16x16x32_bf16 v[44:47], v[52:55], v[202:205], v[44:47]
	v_mfma_f32_16x16x32_bf16 v[40:43], v[60:63], v[202:205], v[40:43]
	v_mfma_f32_16x16x32_bf16 v[28:31], v[52:55], v[214:217], v[28:31]
	v_mfma_f32_16x16x32_bf16 v[24:27], v[60:63], v[214:217], v[24:27]
	v_mfma_f32_16x16x32_bf16 v[12:15], v[52:55], v[228:231], v[12:15]
	v_mfma_f32_16x16x32_bf16 v[8:11], v[60:63], v[228:231], v[8:11]
	s_setprio 0
	s_setprio 1
	v_mfma_f32_16x16x32_bf16 v[36:39], v[64:67], v[198:201], v[36:39]
	v_mfma_f32_16x16x32_bf16 v[32:35], v[88:91], v[198:201], v[32:35]
	v_mfma_f32_16x16x32_bf16 v[20:23], v[64:67], v[210:213], v[20:23]
	v_mfma_f32_16x16x32_bf16 v[16:19], v[88:91], v[210:213], v[16:19]
	v_mfma_f32_16x16x32_bf16 v[4:7], v[64:67], v[218:221], v[4:7]
	v_mfma_f32_16x16x32_bf16 v[0:3], v[88:91], v[218:221], v[0:3]
	v_mfma_f32_16x16x32_bf16 v[48:51], v[64:67], v[180:183], v[76:79]
	v_mfma_f32_16x16x32_bf16 v[52:55], v[88:91], v[180:183], v[72:75]
	v_mfma_f32_16x16x32_bf16 v[36:39], v[68:71], v[202:205], v[36:39]
	v_mfma_f32_16x16x32_bf16 v[32:35], v[92:95], v[202:205], v[32:35]
	v_mfma_f32_16x16x32_bf16 v[20:23], v[68:71], v[214:217], v[20:23]
	v_mfma_f32_16x16x32_bf16 v[16:19], v[92:95], v[214:217], v[16:19]
	v_mfma_f32_16x16x32_bf16 v[4:7], v[68:71], v[228:231], v[4:7]
	v_mfma_f32_16x16x32_bf16 v[0:3], v[92:95], v[228:231], v[0:3]
	v_mfma_f32_16x16x32_bf16 v[48:51], v[68:71], v[184:187], v[48:51]
	v_mfma_f32_16x16x32_bf16 v[52:55], v[92:95], v[184:187], v[52:55]
	s_setprio 0
	s_barrier
	s_add_i32 s55, 0, 0x1c000
	v_add_u32_e32 v68, s95, v206
	v_add_u32_e32 v72, s55, v206
	ds_read_b128 v[56:59], v68
	ds_read_b128 v[60:63], v68 offset:1024
	ds_read_b128 v[64:67], v68 offset:2048
	ds_read_b128 v[68:71], v68 offset:3072
	ds_read_b128 v[88:91], v72
	ds_read_b128 v[92:95], v72 offset:1024
	ds_read_b128 v[180:183], v72 offset:2048
	ds_read_b128 v[184:187], v72 offset:3072
	s_add_u32 s30, s30, 0x40000
	s_addc_u32 s31, s31, 0
	s_mov_b32 m0, s43
	v_lshl_add_u64 v[232:233], s[30:31], 0, v[166:167]
	ds_read_b128 v[72:75], v209 offset:32768
	ds_read_b128 v[76:79], v209 offset:33792
	ds_read_b128 v[198:201], v209 offset:34816
	ds_read_b128 v[202:205], v209 offset:35840
	ds_read_b128 v[210:213], v209 offset:36864
	ds_read_b128 v[214:217], v209 offset:37888
	ds_read_b128 v[218:221], v209 offset:38912
	ds_read_b128 v[228:231], v209 offset:39936
	global_load_lds_dwordx4 v[232:233], off
	v_lshl_add_u64 v[232:233], s[30:31], 0, v[162:163]
	s_mov_b32 m0, s45
	s_nop 0
	global_load_lds_dwordx4 v[232:233], off
	s_nop 0
	s_waitcnt vmcnt(8)
	s_waitcnt lgkmcnt(0)
	s_barrier
	s_setprio 1
	s_waitcnt lgkmcnt(0)
	v_mfma_f32_16x16x32_bf16 v[156:159], v[56:59], v[72:75], v[156:159]
	v_mfma_f32_16x16x32_bf16 v[152:155], v[64:67], v[72:75], v[152:155]
	v_mfma_f32_16x16x32_bf16 v[140:143], v[56:59], v[198:201], v[140:143]
	v_mfma_f32_16x16x32_bf16 v[136:139], v[64:67], v[198:201], v[136:139]
	v_mfma_f32_16x16x32_bf16 v[124:127], v[56:59], v[210:213], v[124:127]
	v_mfma_f32_16x16x32_bf16 v[120:123], v[64:67], v[210:213], v[120:123]
	v_mfma_f32_16x16x32_bf16 v[108:111], v[56:59], v[218:221], v[108:111]
	v_mfma_f32_16x16x32_bf16 v[104:107], v[64:67], v[218:221], v[104:107]
	v_mfma_f32_16x16x32_bf16 v[156:159], v[60:63], v[76:79], v[156:159]
	v_mfma_f32_16x16x32_bf16 v[152:155], v[68:71], v[76:79], v[152:155]
	v_mfma_f32_16x16x32_bf16 v[140:143], v[60:63], v[202:205], v[140:143]
	v_mfma_f32_16x16x32_bf16 v[136:139], v[68:71], v[202:205], v[136:139]
	v_mfma_f32_16x16x32_bf16 v[124:127], v[60:63], v[214:217], v[124:127]
	v_mfma_f32_16x16x32_bf16 v[120:123], v[68:71], v[214:217], v[120:123]
	v_mfma_f32_16x16x32_bf16 v[108:111], v[60:63], v[228:231], v[108:111]
	v_mfma_f32_16x16x32_bf16 v[104:107], v[68:71], v[228:231], v[104:107]
	s_setprio 0
	s_setprio 1
	v_mfma_f32_16x16x32_bf16 v[148:151], v[88:91], v[72:75], v[148:151]
	v_mfma_f32_16x16x32_bf16 v[72:75], v[180:183], v[72:75], v[144:147]
	v_mfma_f32_16x16x32_bf16 v[144:147], v[184:187], v[76:79], v[72:75]
	v_mfma_f32_16x16x32_bf16 v[72:75], v[88:91], v[198:201], v[132:135]
	v_mfma_f32_16x16x32_bf16 v[132:135], v[92:95], v[202:205], v[72:75]
	v_mfma_f32_16x16x32_bf16 v[72:75], v[180:183], v[198:201], v[128:131]
	v_mfma_f32_16x16x32_bf16 v[128:131], v[184:187], v[202:205], v[72:75]
	v_mfma_f32_16x16x32_bf16 v[72:75], v[88:91], v[210:213], v[116:119]
	v_mfma_f32_16x16x32_bf16 v[116:119], v[92:95], v[214:217], v[72:75]
	v_mfma_f32_16x16x32_bf16 v[72:75], v[180:183], v[210:213], v[112:115]
	v_mfma_f32_16x16x32_bf16 v[112:115], v[184:187], v[214:217], v[72:75]
	v_mfma_f32_16x16x32_bf16 v[72:75], v[88:91], v[218:221], v[100:103]
	v_mfma_f32_16x16x32_bf16 v[100:103], v[92:95], v[228:231], v[72:75]
	v_mfma_f32_16x16x32_bf16 v[72:75], v[180:183], v[218:221], v[96:99]
	v_mfma_f32_16x16x32_bf16 v[148:151], v[92:95], v[76:79], v[148:151]
	v_mfma_f32_16x16x32_bf16 v[96:99], v[184:187], v[228:231], v[72:75]
	s_setprio 0
	s_barrier
; #define PG8_STAGE(bufoff, gbase, voff) do { _Pragma("unroll") for (int _i = 0; _i < 2; ++_i) \
;         __builtin_amdgcn_global_load_lds((const unsigned*)((const char*)(gbase) + (voff)[_i]), (LAS unsigned*)(lds + (bufoff) + ldsw + _i * 8192), 16, 0, 0); } while (0)
; #define PG8_LDA(dst, b, h) do { _Pragma("unroll") for (int m = 0; m < 4; ++m) _Pragma("unroll") for (int k = 0; k < 2; ++k) dst[m][k] = *(const LAS bf16x8*)(lds + PG8_SA(b, h) + aoff + m * 2048 + k * 1024); } while (0)
; #define PG8_MMA(ai, bj, At, Bt) do { __builtin_amdgcn_s_setprio(1); _Pragma("unroll") for (int m = 0; m < 4; ++m) _Pragma("unroll") for (int n = 0; n < 2; ++n) _Pragma("unroll") for (int k = 0; k < 2; ++k) \
;         acc[ai][bj][m][n] = __builtin_amdgcn_mfma_f32_16x16x32_bf16(Bt[n][k], At[m][k], acc[ai][bj][m][n], 0, 0, 0); __builtin_amdgcn_s_setprio(0); } while (0)
; #define PG8_WAIT_V(n) asm volatile("s_waitcnt vmcnt(" #n ")" ::: "memory")
; #define PG8_WAIT_L(n) asm volatile("s_waitcnt lgkmcnt(" #n ")" ::: "memory")
; #define PG8_BAR __builtin_amdgcn_s_barrier()
; #define PG8_SCHED __builtin_amdgcn_sched_barrier(0)
; template <class Epi, class Sched>
; __device__ __forceinline__ void gemm_phase(int wv, LAS unsigned char* lds, const Gemm g, const Sched& S, const Epi& E) {
;     ...
;             PG8_LDA(At, 1, 1); PG8_STAGE(PG8_SB(1, 0), b3, voffB); PG8_STAGE(PG8_SB(1, 1), b3 + hstepB, voffB); PG8_STAGE(PG8_SA(1, 0), a3, voffA);
;             PG8_WAIT_V(8); PG8_WAIT_L(0); PG8_BAR; PG8_MMA(1, 0, At, B0); PG8_MMA(1, 1, At, B1); PG8_BAR; PG8_SCHED;
;         }
;         if (wr == 0) PG8_BAR;
	s_add_i32 s30, s95, s40
	v_lshl_add_u64 v[76:77], v[222:223], 0, s[74:75]
	s_mov_b32 m0, s30
	s_nop 0
	ds_read_b128 v[72:75], v209 offset:49152
	ds_read_b128 v[198:201], v209 offset:50176
	ds_read_b128 v[202:205], v209 offset:51200
	ds_read_b128 v[210:213], v209 offset:52224
	ds_read_b128 v[214:217], v209 offset:53248
	ds_read_b128 v[218:221], v209 offset:54272
	ds_read_b128 v[228:231], v209 offset:55296
	ds_read_b128 v[232:235], v209 offset:56320
	global_load_lds_dwordx4 v[76:77], off
	s_add_i32 m0, s30, 0x2000
	s_add_u32 s28, s28, 0x20080
	v_lshl_add_u64 v[76:77], v[240:241], 0, s[74:75]
	s_addc_u32 s29, s29, 0
	s_add_i32 s30, s55, s40
	global_load_lds_dwordx4 v[76:77], off
	v_lshl_add_u64 v[76:77], s[28:29], 0, v[164:165]
	s_mov_b32 m0, s30
	s_nop 0
	global_load_lds_dwordx4 v[76:77], off
	v_lshl_add_u64 v[76:77], s[28:29], 0, v[160:161]
	s_add_i32 m0, s30, 0x2000
	s_nop 0
	global_load_lds_dwordx4 v[76:77], off
	v_lshl_add_u64 v[76:77], v[242:243], 0, s[74:75]
	s_mov_b32 m0, s48
	s_nop 0
	global_load_lds_dwordx4 v[76:77], off
	v_lshl_add_u64 v[76:77], v[244:245], 0, s[74:75]
	s_mov_b32 m0, s49
	s_nop 0
	global_load_lds_dwordx4 v[76:77], off
	s_nop 0
	s_waitcnt vmcnt(8)
	s_waitcnt lgkmcnt(0)
	s_barrier
	s_setprio 1
	s_waitcnt lgkmcnt(0)
	v_mfma_f32_16x16x32_bf16 v[76:79], v[56:59], v[72:75], v[84:87]
	v_mfma_f32_16x16x32_bf16 v[84:87], v[60:63], v[198:201], v[76:79]
	v_mfma_f32_16x16x32_bf16 v[76:79], v[64:67], v[72:75], v[80:83]
	v_mfma_f32_16x16x32_bf16 v[44:47], v[56:59], v[202:205], v[44:47]
	v_mfma_f32_16x16x32_bf16 v[40:43], v[64:67], v[202:205], v[40:43]
	v_mfma_f32_16x16x32_bf16 v[28:31], v[56:59], v[214:217], v[28:31]
	v_mfma_f32_16x16x32_bf16 v[24:27], v[64:67], v[214:217], v[24:27]
	v_mfma_f32_16x16x32_bf16 v[12:15], v[56:59], v[228:231], v[12:15]
	v_mfma_f32_16x16x32_bf16 v[8:11], v[64:67], v[228:231], v[8:11]
	v_mfma_f32_16x16x32_bf16 v[80:83], v[68:71], v[198:201], v[76:79]
	v_mfma_f32_16x16x32_bf16 v[44:47], v[60:63], v[210:213], v[44:47]
	v_mfma_f32_16x16x32_bf16 v[40:43], v[68:71], v[210:213], v[40:43]
	v_mfma_f32_16x16x32_bf16 v[28:31], v[60:63], v[218:221], v[28:31]
	v_mfma_f32_16x16x32_bf16 v[24:27], v[68:71], v[218:221], v[24:27]
	v_mfma_f32_16x16x32_bf16 v[12:15], v[60:63], v[232:235], v[12:15]
	v_mfma_f32_16x16x32_bf16 v[8:11], v[68:71], v[232:235], v[8:11]
	s_setprio 0
	s_setprio 1
	v_mfma_f32_16x16x32_bf16 v[48:51], v[88:91], v[72:75], v[48:51]
	v_mfma_f32_16x16x32_bf16 v[76:79], v[92:95], v[198:201], v[48:51]
	v_mfma_f32_16x16x32_bf16 v[48:51], v[180:183], v[72:75], v[52:55]
	v_mfma_f32_16x16x32_bf16 v[36:39], v[88:91], v[202:205], v[36:39]
	v_mfma_f32_16x16x32_bf16 v[32:35], v[180:183], v[202:205], v[32:35]
	v_mfma_f32_16x16x32_bf16 v[20:23], v[88:91], v[214:217], v[20:23]
	v_mfma_f32_16x16x32_bf16 v[16:19], v[180:183], v[214:217], v[16:19]
	v_mfma_f32_16x16x32_bf16 v[4:7], v[88:91], v[228:231], v[4:7]
	v_mfma_f32_16x16x32_bf16 v[0:3], v[180:183], v[228:231], v[0:3]
	v_mfma_f32_16x16x32_bf16 v[72:75], v[184:187], v[198:201], v[48:51]
	v_mfma_f32_16x16x32_bf16 v[36:39], v[92:95], v[210:213], v[36:39]
	v_mfma_f32_16x16x32_bf16 v[32:35], v[184:187], v[210:213], v[32:35]
	v_mfma_f32_16x16x32_bf16 v[20:23], v[92:95], v[218:221], v[20:23]
	v_mfma_f32_16x16x32_bf16 v[16:19], v[184:187], v[218:221], v[16:19]
	v_mfma_f32_16x16x32_bf16 v[4:7], v[92:95], v[232:235], v[4:7]
	v_mfma_f32_16x16x32_bf16 v[0:3], v[184:187], v[232:235], v[0:3]
	s_setprio 0
	s_barrier
	s_add_i32 s54, s54, 2
	s_add_u32 s4, s4, 0x100
	s_addc_u32 s5, s5, 0
	s_add_u32 s52, s52, 0x100
	s_addc_u32 s53, s53, 0
	s_cmp_gt_u32 s54, 13
	s_cbranch_scc0 .LBB0_542
	s_and_b64 vcc, exec, s[16:17]
	s_cbranch_vccz .LBB0_545
	s_barrier

; #define PG8_STAGE(bufoff, gbase, voff) do { _Pragma("unroll") for (int _i = 0; _i < 2; ++_i) \
;         __builtin_amdgcn_global_load_lds((const unsigned*)((const char*)(gbase) + (voff)[_i]), (LAS unsigned*)(lds + (bufoff) + ldsw + _i * 8192), 16, 0, 0); } while (0)
; #define PG8_LDA(dst, b, h) do { _Pragma("unroll") for (int m = 0; m < 4; ++m) _Pragma("unroll") for (int k = 0; k < 2; ++k) dst[m][k] = *(const LAS bf16x8*)(lds + PG8_SA(b, h) + aoff + m * 2048 + k * 1024); } while (0)
; #define PG8_LDB(dst, b, h) do { _Pragma("unroll") for (int n = 0; n < 2; ++n) _Pragma("unroll") for (int k = 0; k < 2; ++k) dst[n][k] = *(const LAS bf16x8*)(lds + PG8_SB(b, h) + boff + n * 2048 + k * 1024); } while (0)
; #define PG8_MMA(ai, bj, At, Bt) do { __builtin_amdgcn_s_setprio(1); _Pragma("unroll") for (int m = 0; m < 4; ++m) _Pragma("unroll") for (int n = 0; n < 2; ++n) _Pragma("unroll") for (int k = 0; k < 2; ++k) \
;         acc[ai][bj][m][n] = __builtin_amdgcn_mfma_f32_16x16x32_bf16(Bt[n][k], At[m][k], acc[ai][bj][m][n], 0, 0, 0); __builtin_amdgcn_s_setprio(0); } while (0)
; #define PG8_WAIT_V(n) asm volatile("s_waitcnt vmcnt(" #n ")" ::: "memory")
; #define PG8_WAIT_L(n) asm volatile("s_waitcnt lgkmcnt(" #n ")" ::: "memory")
; #define PG8_BAR __builtin_amdgcn_s_barrier()
; #define PG8_SCHED __builtin_amdgcn_sched_barrier(0)
; template <class Epi, class Sched>
; __device__ __forceinline__ void gemm_phase(int wv, LAS unsigned char* lds, const Gemm g, const Sched& S, const Epi& E) {
;     ...
;         for (int t = 0; t < nt; t += 2) {
;             const bool last = (t == nt - 2);
;             const char* a1 = cA + (size_t)(t + 1) * kstep;
;             const char* a2 = last ? nA : cA + (size_t)(t + 2) * kstep; const char* b2 = last ? nB : cB + (size_t)(t + 2) * kstep;
;             const char* a3 = a2 + kstep; const char* b3 = b2 + kstep;
;             PG8_LDB(B0, 0, 0); PG8_LDB(B1, 0, 1); PG8_SCHED; PG8_LDA(At, 0, 0); PG8_STAGE(PG8_SA(1, 1), a1 + hstep, voffA);
;             PG8_WAIT_V(8); PG8_WAIT_L(0); PG8_BAR; PG8_MMA(0, 0, At, B0); PG8_MMA(0, 1, At, B1); PG8_BAR; PG8_SCHED;
;             PG8_LDA(At, 0, 1); PG8_STAGE(PG8_SB(0, 0), b2, voffB); PG8_STAGE(PG8_SB(0, 1), b2 + hstepB, voffB); PG8_STAGE(PG8_SA(0, 0), a2, voffA);
;             PG8_WAIT_V(8); PG8_WAIT_L(0); PG8_BAR; PG8_MMA(1, 0, At, B0); PG8_MMA(1, 1, At, B1); PG8_BAR; PG8_SCHED;
.LBB0_781:
	s_add_u32 s22, s20, 0xfffc0080
	s_addc_u32 s23, s21, -1
	s_add_i32 s44, 0, 0x10000
	s_cmp_eq_u32 s43, 12
	s_cselect_b32 s25, s13, s23
	s_cselect_b32 s24, s39, s22
	s_cselect_b32 s23, s15, s42
	s_cselect_b32 s22, s40, s41
	s_add_i32 s46, 0, 0x14000
	v_add_u32_e32 v154, s44, v139
	v_add_u32_e32 v170, s46, v139
	ds_read_b128 v[142:145], v154
	ds_read_b128 v[146:149], v154 offset:1024
	ds_read_b128 v[150:153], v154 offset:2048
	ds_read_b128 v[154:157], v154 offset:3072
	ds_read_b128 v[158:161], v170
	ds_read_b128 v[162:165], v170 offset:1024
	ds_read_b128 v[166:169], v170 offset:2048
	ds_read_b128 v[170:173], v170 offset:3072
	v_lshl_add_u64 v[186:187], s[20:21], 0, v[134:135]
	s_add_i32 m0, s29, 0xc000
	ds_read_b128 v[174:177], v141
	ds_read_b128 v[178:181], v141 offset:1024
	ds_read_b128 v[182:185], v141 offset:2048
	ds_read_b128 v[198:201], v141 offset:3072
	ds_read_b128 v[202:205], v141 offset:4096
	ds_read_b128 v[206:209], v141 offset:5120
	ds_read_b128 v[210:213], v141 offset:6144
	ds_read_b128 v[214:217], v141 offset:7168
	global_load_lds_dwordx4 v[186:187], off
	v_lshl_add_u64 v[186:187], s[20:21], 0, v[136:137]
	s_add_i32 m0, s29, 0xe000
	s_nop 0
	global_load_lds_dwordx4 v[186:187], off
	s_waitcnt vmcnt(8)
	s_waitcnt lgkmcnt(0)
	s_barrier
	s_setprio 1
	s_waitcnt lgkmcnt(0)
	v_mfma_f32_16x16x32_bf16 v[124:127], v[142:145], v[174:177], v[124:127]
	v_mfma_f32_16x16x32_bf16 v[120:123], v[150:153], v[174:177], v[120:123]
	v_mfma_f32_16x16x32_bf16 v[116:119], v[142:145], v[182:185], v[116:119]
	v_mfma_f32_16x16x32_bf16 v[108:111], v[150:153], v[182:185], v[108:111]
	v_mfma_f32_16x16x32_bf16 v[100:103], v[142:145], v[202:205], v[100:103]
	v_mfma_f32_16x16x32_bf16 v[96:99], v[150:153], v[202:205], v[96:99]
	v_mfma_f32_16x16x32_bf16 v[84:87], v[142:145], v[210:213], v[84:87]
	v_mfma_f32_16x16x32_bf16 v[80:83], v[150:153], v[210:213], v[80:83]
	v_mfma_f32_16x16x32_bf16 v[124:127], v[146:149], v[178:181], v[124:127]
	v_mfma_f32_16x16x32_bf16 v[120:123], v[154:157], v[178:181], v[120:123]
	v_mfma_f32_16x16x32_bf16 v[116:119], v[146:149], v[198:201], v[116:119]
	v_mfma_f32_16x16x32_bf16 v[108:111], v[154:157], v[198:201], v[108:111]
	v_mfma_f32_16x16x32_bf16 v[100:103], v[146:149], v[206:209], v[100:103]
	v_mfma_f32_16x16x32_bf16 v[96:99], v[154:157], v[206:209], v[96:99]
	v_mfma_f32_16x16x32_bf16 v[84:87], v[146:149], v[214:217], v[84:87]
	v_mfma_f32_16x16x32_bf16 v[80:83], v[154:157], v[214:217], v[80:83]
	s_setprio 0
	s_setprio 1
	v_mfma_f32_16x16x32_bf16 v[112:115], v[158:161], v[174:177], v[112:115]
	v_mfma_f32_16x16x32_bf16 v[104:107], v[166:169], v[174:177], v[104:107]
	v_mfma_f32_16x16x32_bf16 v[92:95], v[158:161], v[182:185], v[92:95]
	v_mfma_f32_16x16x32_bf16 v[88:91], v[166:169], v[182:185], v[88:91]
	v_mfma_f32_16x16x32_bf16 v[76:79], v[158:161], v[202:205], v[76:79]
	v_mfma_f32_16x16x32_bf16 v[72:75], v[166:169], v[202:205], v[72:75]
	v_mfma_f32_16x16x32_bf16 v[68:71], v[158:161], v[210:213], v[68:71]
	v_mfma_f32_16x16x32_bf16 v[64:67], v[166:169], v[210:213], v[64:67]
	v_mfma_f32_16x16x32_bf16 v[112:115], v[162:165], v[178:181], v[112:115]
	v_mfma_f32_16x16x32_bf16 v[104:107], v[170:173], v[178:181], v[104:107]
	v_mfma_f32_16x16x32_bf16 v[92:95], v[162:165], v[198:201], v[92:95]
	v_mfma_f32_16x16x32_bf16 v[88:91], v[170:173], v[198:201], v[88:91]
	v_mfma_f32_16x16x32_bf16 v[76:79], v[162:165], v[206:209], v[76:79]
	v_mfma_f32_16x16x32_bf16 v[72:75], v[170:173], v[206:209], v[72:75]
	v_mfma_f32_16x16x32_bf16 v[68:71], v[162:165], v[214:217], v[68:71]
	v_mfma_f32_16x16x32_bf16 v[64:67], v[170:173], v[214:217], v[64:67]
	s_setprio 0
	s_barrier
	s_add_i32 s44, s44, s28
	v_lshl_add_u64 v[186:187], s[22:23], 0, v[188:189]
	s_mov_b32 m0, s44
	ds_read_b128 v[174:177], v141 offset:16384
	ds_read_b128 v[178:181], v141 offset:17408
	ds_read_b128 v[182:185], v141 offset:18432
	ds_read_b128 v[198:201], v141 offset:19456
	ds_read_b128 v[202:205], v141 offset:20480
	ds_read_b128 v[206:209], v141 offset:21504
	ds_read_b128 v[210:213], v141 offset:22528
	ds_read_b128 v[214:217], v141 offset:23552
	global_load_lds_dwordx4 v[186:187], off
	s_add_i32 m0, s44, 0x2000
	s_add_u32 s44, s22, 0x4000
	v_lshl_add_u64 v[218:219], s[22:23], 0, v[128:129]
	s_addc_u32 s45, s23, 0
	s_add_i32 s46, s46, s28
	global_load_lds_dwordx4 v[218:219], off
	v_lshl_add_u64 v[220:221], s[44:45], 0, v[188:189]
	s_mov_b32 m0, s46
	v_lshl_add_u64 v[222:223], s[24:25], 0, v[130:131]
	global_load_lds_dwordx4 v[220:221], off
	v_lshl_add_u64 v[220:221], s[44:45], 0, v[128:129]
	s_add_i32 m0, s46, 0x2000
	s_nop 0
	global_load_lds_dwordx4 v[220:221], off
	v_lshl_add_u64 v[220:221], s[24:25], 0, v[132:133]
	s_mov_b32 m0, s29
	s_nop 0
	global_load_lds_dwordx4 v[220:221], off
	s_mov_b32 m0, s30
	s_nop 0
	global_load_lds_dwordx4 v[222:223], off
	s_nop 0
	s_waitcnt vmcnt(8)
	s_waitcnt lgkmcnt(0)
	s_barrier
; #define PG8_STAGE(bufoff, gbase, voff) do { _Pragma("unroll") for (int _i = 0; _i < 2; ++_i) \
;         __builtin_amdgcn_global_load_lds((const unsigned*)((const char*)(gbase) + (voff)[_i]), (LAS unsigned*)(lds + (bufoff) + ldsw + _i * 8192), 16, 0, 0); } while (0)
; #define PG8_LDA(dst, b, h) do { _Pragma("unroll") for (int m = 0; m < 4; ++m) _Pragma("unroll") for (int k = 0; k < 2; ++k) dst[m][k] = *(const LAS bf16x8*)(lds + PG8_SA(b, h) + aoff + m * 2048 + k * 1024); } while (0)
; #define PG8_LDB(dst, b, h) do { _Pragma("unroll") for (int n = 0; n < 2; ++n) _Pragma("unroll") for (int k = 0; k < 2; ++k) dst[n][k] = *(const LAS bf16x8*)(lds + PG8_SB(b, h) + boff + n * 2048 + k * 1024); } while (0)
; #define PG8_MMA(ai, bj, At, Bt) do { __builtin_amdgcn_s_setprio(1); _Pragma("unroll") for (int m = 0; m < 4; ++m) _Pragma("unroll") for (int n = 0; n < 2; ++n) _Pragma("unroll") for (int k = 0; k < 2; ++k) \
;         acc[ai][bj][m][n] = __builtin_amdgcn_mfma_f32_16x16x32_bf16(Bt[n][k], At[m][k], acc[ai][bj][m][n], 0, 0, 0); __builtin_amdgcn_s_setprio(0); } while (0)
; #define PG8_WAIT_V(n) asm volatile("s_waitcnt vmcnt(" #n ")" ::: "memory")
; #define PG8_WAIT_L(n) asm volatile("s_waitcnt lgkmcnt(" #n ")" ::: "memory")
; #define PG8_BAR __builtin_amdgcn_s_barrier()
; #define PG8_SCHED __builtin_amdgcn_sched_barrier(0)
; template <class Epi, class Sched>
; __device__ __forceinline__ void gemm_phase(int wv, LAS unsigned char* lds, const Gemm g, const Sched& S, const Epi& E) {
;     ...
;             PG8_WAIT_V(8); PG8_WAIT_L(0); PG8_BAR; PG8_MMA(1, 0, At, B0); PG8_MMA(1, 1, At, B1); PG8_BAR; PG8_SCHED;
;             PG8_LDB(B0, 1, 0); PG8_LDB(B1, 1, 1); PG8_SCHED; PG8_LDA(At, 1, 0); PG8_STAGE(PG8_SA(0, 1), a2 + hstep, voffA);
;             PG8_WAIT_V(8); PG8_WAIT_L(0); PG8_BAR; PG8_MMA(0, 0, At, B0); PG8_MMA(0, 1, At, B1); PG8_BAR; PG8_SCHED;
	s_setprio 1
	s_waitcnt lgkmcnt(0)
	v_mfma_f32_16x16x32_bf16 v[60:63], v[142:145], v[174:177], v[60:63]
	v_mfma_f32_16x16x32_bf16 v[56:59], v[150:153], v[174:177], v[56:59]
	v_mfma_f32_16x16x32_bf16 v[52:55], v[142:145], v[182:185], v[52:55]
	v_mfma_f32_16x16x32_bf16 v[48:51], v[150:153], v[182:185], v[48:51]
	v_mfma_f32_16x16x32_bf16 v[36:39], v[142:145], v[202:205], v[36:39]
	v_mfma_f32_16x16x32_bf16 v[32:35], v[150:153], v[202:205], v[32:35]
	v_mfma_f32_16x16x32_bf16 v[20:23], v[142:145], v[210:213], v[20:23]
	v_mfma_f32_16x16x32_bf16 v[16:19], v[150:153], v[210:213], v[16:19]
	v_mfma_f32_16x16x32_bf16 v[60:63], v[146:149], v[178:181], v[60:63]
	v_mfma_f32_16x16x32_bf16 v[56:59], v[154:157], v[178:181], v[56:59]
	v_mfma_f32_16x16x32_bf16 v[52:55], v[146:149], v[198:201], v[52:55]
	v_mfma_f32_16x16x32_bf16 v[48:51], v[154:157], v[198:201], v[48:51]
	v_mfma_f32_16x16x32_bf16 v[36:39], v[146:149], v[206:209], v[36:39]
	v_mfma_f32_16x16x32_bf16 v[32:35], v[154:157], v[206:209], v[32:35]
	v_mfma_f32_16x16x32_bf16 v[20:23], v[146:149], v[214:217], v[20:23]
	v_mfma_f32_16x16x32_bf16 v[16:19], v[154:157], v[214:217], v[16:19]
	s_setprio 0
	s_setprio 1
	v_mfma_f32_16x16x32_bf16 v[44:47], v[158:161], v[174:177], v[44:47]
	v_mfma_f32_16x16x32_bf16 v[40:43], v[166:169], v[174:177], v[40:43]
	v_mfma_f32_16x16x32_bf16 v[28:31], v[158:161], v[182:185], v[28:31]
	v_mfma_f32_16x16x32_bf16 v[24:27], v[166:169], v[182:185], v[24:27]
	v_mfma_f32_16x16x32_bf16 v[12:15], v[158:161], v[202:205], v[12:15]
	v_mfma_f32_16x16x32_bf16 v[8:11], v[166:169], v[202:205], v[8:11]
	v_mfma_f32_16x16x32_bf16 v[4:7], v[158:161], v[210:213], v[4:7]
	v_mfma_f32_16x16x32_bf16 v[0:3], v[166:169], v[210:213], v[0:3]
	v_mfma_f32_16x16x32_bf16 v[44:47], v[162:165], v[178:181], v[44:47]
	v_mfma_f32_16x16x32_bf16 v[40:43], v[170:173], v[178:181], v[40:43]
	v_mfma_f32_16x16x32_bf16 v[28:31], v[162:165], v[198:201], v[28:31]
	v_mfma_f32_16x16x32_bf16 v[24:27], v[170:173], v[198:201], v[24:27]
	v_mfma_f32_16x16x32_bf16 v[12:15], v[162:165], v[206:209], v[12:15]
	v_mfma_f32_16x16x32_bf16 v[8:11], v[170:173], v[206:209], v[8:11]
	v_mfma_f32_16x16x32_bf16 v[4:7], v[162:165], v[214:217], v[4:7]
	v_mfma_f32_16x16x32_bf16 v[0:3], v[170:173], v[214:217], v[0:3]
	s_setprio 0
	s_barrier
	s_add_i32 s44, 0, 0x1c000
	v_add_u32_e32 v154, s95, v139
	v_add_u32_e32 v170, s44, v139
	ds_read_b128 v[142:145], v154
	ds_read_b128 v[146:149], v154 offset:1024
	ds_read_b128 v[150:153], v154 offset:2048
	ds_read_b128 v[154:157], v154 offset:3072
	ds_read_b128 v[158:161], v170
	ds_read_b128 v[162:165], v170 offset:1024
	ds_read_b128 v[166:169], v170 offset:2048
	ds_read_b128 v[170:173], v170 offset:3072
	s_add_u32 s24, s24, 0x40000
	s_addc_u32 s25, s25, 0
	s_mov_b32 m0, s31
	v_lshl_add_u64 v[228:229], s[24:25], 0, v[132:133]
	ds_read_b128 v[174:177], v141 offset:32768
	ds_read_b128 v[178:181], v141 offset:33792
	ds_read_b128 v[182:185], v141 offset:34816
	ds_read_b128 v[198:201], v141 offset:35840
	ds_read_b128 v[202:205], v141 offset:36864
	ds_read_b128 v[206:209], v141 offset:37888
	ds_read_b128 v[210:213], v141 offset:38912
	ds_read_b128 v[214:217], v141 offset:39936
	global_load_lds_dwordx4 v[228:229], off
	v_lshl_add_u64 v[228:229], s[24:25], 0, v[130:131]
	s_mov_b32 m0, s34
	s_nop 0
	global_load_lds_dwordx4 v[228:229], off
	s_nop 0
	s_waitcnt vmcnt(8)
	s_waitcnt lgkmcnt(0)
	s_barrier
	s_setprio 1
	s_waitcnt lgkmcnt(0)
	v_mfma_f32_16x16x32_bf16 v[124:127], v[142:145], v[174:177], v[124:127]
	v_mfma_f32_16x16x32_bf16 v[120:123], v[150:153], v[174:177], v[120:123]
	v_mfma_f32_16x16x32_bf16 v[116:119], v[142:145], v[182:185], v[116:119]
	v_mfma_f32_16x16x32_bf16 v[108:111], v[150:153], v[182:185], v[108:111]
	v_mfma_f32_16x16x32_bf16 v[100:103], v[142:145], v[202:205], v[100:103]
	v_mfma_f32_16x16x32_bf16 v[96:99], v[150:153], v[202:205], v[96:99]
	v_mfma_f32_16x16x32_bf16 v[84:87], v[142:145], v[210:213], v[84:87]
	v_mfma_f32_16x16x32_bf16 v[80:83], v[150:153], v[210:213], v[80:83]
	v_mfma_f32_16x16x32_bf16 v[124:127], v[146:149], v[178:181], v[124:127]
	v_mfma_f32_16x16x32_bf16 v[120:123], v[154:157], v[178:181], v[120:123]
	v_mfma_f32_16x16x32_bf16 v[116:119], v[146:149], v[198:201], v[116:119]
	v_mfma_f32_16x16x32_bf16 v[108:111], v[154:157], v[198:201], v[108:111]
	v_mfma_f32_16x16x32_bf16 v[100:103], v[146:149], v[206:209], v[100:103]
	v_mfma_f32_16x16x32_bf16 v[96:99], v[154:157], v[206:209], v[96:99]
	v_mfma_f32_16x16x32_bf16 v[84:87], v[146:149], v[214:217], v[84:87]
	v_mfma_f32_16x16x32_bf16 v[80:83], v[154:157], v[214:217], v[80:83]
	s_setprio 0
	s_setprio 1
	v_mfma_f32_16x16x32_bf16 v[112:115], v[158:161], v[174:177], v[112:115]
	v_mfma_f32_16x16x32_bf16 v[104:107], v[166:169], v[174:177], v[104:107]
	v_mfma_f32_16x16x32_bf16 v[92:95], v[158:161], v[182:185], v[92:95]
	v_mfma_f32_16x16x32_bf16 v[88:91], v[166:169], v[182:185], v[88:91]
	v_mfma_f32_16x16x32_bf16 v[76:79], v[158:161], v[202:205], v[76:79]
	v_mfma_f32_16x16x32_bf16 v[72:75], v[166:169], v[202:205], v[72:75]
	v_mfma_f32_16x16x32_bf16 v[68:71], v[158:161], v[210:213], v[68:71]
	v_mfma_f32_16x16x32_bf16 v[64:67], v[166:169], v[210:213], v[64:67]
	v_mfma_f32_16x16x32_bf16 v[112:115], v[162:165], v[178:181], v[112:115]
	v_mfma_f32_16x16x32_bf16 v[104:107], v[170:173], v[178:181], v[104:107]
	v_mfma_f32_16x16x32_bf16 v[92:95], v[162:165], v[198:201], v[92:95]
	v_mfma_f32_16x16x32_bf16 v[88:91], v[170:173], v[198:201], v[88:91]
	v_mfma_f32_16x16x32_bf16 v[76:79], v[162:165], v[206:209], v[76:79]
	v_mfma_f32_16x16x32_bf16 v[72:75], v[170:173], v[206:209], v[72:75]
	v_mfma_f32_16x16x32_bf16 v[68:71], v[162:165], v[214:217], v[68:71]
	v_mfma_f32_16x16x32_bf16 v[64:67], v[170:173], v[214:217], v[64:67]
	s_setprio 0
	s_barrier
; #define PG8_STAGE(bufoff, gbase, voff) do { _Pragma("unroll") for (int _i = 0; _i < 2; ++_i) \
;         __builtin_amdgcn_global_load_lds((const unsigned*)((const char*)(gbase) + (voff)[_i]), (LAS unsigned*)(lds + (bufoff) + ldsw + _i * 8192), 16, 0, 0); } while (0)
; #define PG8_LDA(dst, b, h) do { _Pragma("unroll") for (int m = 0; m < 4; ++m) _Pragma("unroll") for (int k = 0; k < 2; ++k) dst[m][k] = *(const LAS bf16x8*)(lds + PG8_SA(b, h) + aoff + m * 2048 + k * 1024); } while (0)
; #define PG8_MMA(ai, bj, At, Bt) do { __builtin_amdgcn_s_setprio(1); _Pragma("unroll") for (int m = 0; m < 4; ++m) _Pragma("unroll") for (int n = 0; n < 2; ++n) _Pragma("unroll") for (int k = 0; k < 2; ++k) \
;         acc[ai][bj][m][n] = __builtin_amdgcn_mfma_f32_16x16x32_bf16(Bt[n][k], At[m][k], acc[ai][bj][m][n], 0, 0, 0); __builtin_amdgcn_s_setprio(0); } while (0)
; #define PG8_WAIT_V(n) asm volatile("s_waitcnt vmcnt(" #n ")" ::: "memory")
; #define PG8_WAIT_L(n) asm volatile("s_waitcnt lgkmcnt(" #n ")" ::: "memory")
; #define PG8_BAR __builtin_amdgcn_s_barrier()
; #define PG8_SCHED __builtin_amdgcn_sched_barrier(0)
; template <class Epi, class Sched>
; __device__ __forceinline__ void gemm_phase(int wv, LAS unsigned char* lds, const Gemm g, const Sched& S, const Epi& E) {
;     ...
;             PG8_LDA(At, 1, 1); PG8_STAGE(PG8_SB(1, 0), b3, voffB); PG8_STAGE(PG8_SB(1, 1), b3 + hstepB, voffB); PG8_STAGE(PG8_SA(1, 0), a3, voffA);
;             PG8_WAIT_V(8); PG8_WAIT_L(0); PG8_BAR; PG8_MMA(1, 0, At, B0); PG8_MMA(1, 1, At, B1); PG8_BAR; PG8_SCHED;
;         }
;         if (wr == 0) PG8_BAR;
	s_add_i32 s24, s95, s28
	v_lshl_add_u64 v[186:187], v[186:187], 0, s[74:75]
	s_mov_b32 m0, s24
	ds_read_b128 v[174:177], v141 offset:49152
	ds_read_b128 v[178:181], v141 offset:50176
	ds_read_b128 v[182:185], v141 offset:51200
	ds_read_b128 v[198:201], v141 offset:52224
	ds_read_b128 v[202:205], v141 offset:53248
	ds_read_b128 v[206:209], v141 offset:54272
	ds_read_b128 v[210:213], v141 offset:55296
	ds_read_b128 v[214:217], v141 offset:56320
	global_load_lds_dwordx4 v[186:187], off
	s_add_i32 m0, s24, 0x2000
	s_add_u32 s22, s22, 0x4080
	v_lshl_add_u64 v[186:187], v[218:219], 0, s[74:75]
	s_addc_u32 s23, s23, 0
	s_add_i32 s24, s44, s28
	global_load_lds_dwordx4 v[186:187], off
	v_lshl_add_u64 v[186:187], s[22:23], 0, v[188:189]
	s_mov_b32 m0, s24
	s_nop 0
	global_load_lds_dwordx4 v[186:187], off
	v_lshl_add_u64 v[186:187], s[22:23], 0, v[128:129]
	s_add_i32 m0, s24, 0x2000
	s_nop 0
	global_load_lds_dwordx4 v[186:187], off
	v_lshl_add_u64 v[186:187], v[220:221], 0, s[74:75]
	s_mov_b32 m0, s35
	s_nop 0
	global_load_lds_dwordx4 v[186:187], off
	v_lshl_add_u64 v[186:187], v[222:223], 0, s[74:75]
	s_mov_b32 m0, s36
	s_nop 0
	global_load_lds_dwordx4 v[186:187], off
	s_waitcnt vmcnt(8)
	s_waitcnt lgkmcnt(0)
	s_barrier
	s_setprio 1
	s_waitcnt lgkmcnt(0)
	v_mfma_f32_16x16x32_bf16 v[60:63], v[142:145], v[174:177], v[60:63]
	v_mfma_f32_16x16x32_bf16 v[56:59], v[150:153], v[174:177], v[56:59]
	v_mfma_f32_16x16x32_bf16 v[52:55], v[142:145], v[182:185], v[52:55]
	v_mfma_f32_16x16x32_bf16 v[48:51], v[150:153], v[182:185], v[48:51]
	v_mfma_f32_16x16x32_bf16 v[36:39], v[142:145], v[202:205], v[36:39]
	v_mfma_f32_16x16x32_bf16 v[32:35], v[150:153], v[202:205], v[32:35]
	v_mfma_f32_16x16x32_bf16 v[20:23], v[142:145], v[210:213], v[20:23]
	v_mfma_f32_16x16x32_bf16 v[16:19], v[150:153], v[210:213], v[16:19]
	v_mfma_f32_16x16x32_bf16 v[60:63], v[146:149], v[178:181], v[60:63]
	v_mfma_f32_16x16x32_bf16 v[56:59], v[154:157], v[178:181], v[56:59]
	v_mfma_f32_16x16x32_bf16 v[52:55], v[146:149], v[198:201], v[52:55]
	v_mfma_f32_16x16x32_bf16 v[48:51], v[154:157], v[198:201], v[48:51]
	v_mfma_f32_16x16x32_bf16 v[36:39], v[146:149], v[206:209], v[36:39]
	v_mfma_f32_16x16x32_bf16 v[32:35], v[154:157], v[206:209], v[32:35]
	v_mfma_f32_16x16x32_bf16 v[20:23], v[146:149], v[214:217], v[20:23]
	v_mfma_f32_16x16x32_bf16 v[16:19], v[154:157], v[214:217], v[16:19]
	s_setprio 0
	s_setprio 1
	v_mfma_f32_16x16x32_bf16 v[44:47], v[158:161], v[174:177], v[44:47]
	v_mfma_f32_16x16x32_bf16 v[40:43], v[166:169], v[174:177], v[40:43]
	v_mfma_f32_16x16x32_bf16 v[28:31], v[158:161], v[182:185], v[28:31]
	v_mfma_f32_16x16x32_bf16 v[24:27], v[166:169], v[182:185], v[24:27]
	v_mfma_f32_16x16x32_bf16 v[12:15], v[158:161], v[202:205], v[12:15]
	v_mfma_f32_16x16x32_bf16 v[8:11], v[166:169], v[202:205], v[8:11]
	v_mfma_f32_16x16x32_bf16 v[4:7], v[158:161], v[210:213], v[4:7]
	v_mfma_f32_16x16x32_bf16 v[0:3], v[166:169], v[210:213], v[0:3]
	v_mfma_f32_16x16x32_bf16 v[44:47], v[162:165], v[178:181], v[44:47]
	v_mfma_f32_16x16x32_bf16 v[40:43], v[170:173], v[178:181], v[40:43]
	v_mfma_f32_16x16x32_bf16 v[28:31], v[162:165], v[198:201], v[28:31]
	v_mfma_f32_16x16x32_bf16 v[24:27], v[170:173], v[198:201], v[24:27]
	v_mfma_f32_16x16x32_bf16 v[12:15], v[162:165], v[206:209], v[12:15]
	v_mfma_f32_16x16x32_bf16 v[8:11], v[170:173], v[206:209], v[8:11]
	v_mfma_f32_16x16x32_bf16 v[4:7], v[162:165], v[214:217], v[4:7]
	v_mfma_f32_16x16x32_bf16 v[0:3], v[170:173], v[214:217], v[0:3]
	s_setprio 0
	s_barrier
	s_add_i32 s43, s43, 2
	s_add_u32 s20, s20, 0x100
	s_addc_u32 s21, s21, 0
	s_add_u32 s41, s41, 0x100
	s_addc_u32 s42, s42, 0
	s_cmp_gt_u32 s43, 13
	s_cbranch_scc0 .LBB0_781
	s_and_b64 vcc, exec, s[10:11]
	s_cbranch_vccz .LBB0_784
	s_barrier

; #define PG8_STAGE(bufoff, gbase, voff) do { _Pragma("unroll") for (int _i = 0; _i < 2; ++_i) \
;         __builtin_amdgcn_global_load_lds((const unsigned*)((const char*)(gbase) + (voff)[_i]), (LAS unsigned*)(lds + (bufoff) + ldsw + _i * 8192), 16, 0, 0); } while (0)
; #define PG8_LDA(dst, b, h) do { _Pragma("unroll") for (int m = 0; m < 4; ++m) _Pragma("unroll") for (int k = 0; k < 2; ++k) dst[m][k] = *(const LAS bf16x8*)(lds + PG8_SA(b, h) + aoff + m * 2048 + k * 1024); } while (0)
; #define PG8_LDB(dst, b, h) do { _Pragma("unroll") for (int n = 0; n < 2; ++n) _Pragma("unroll") for (int k = 0; k < 2; ++k) dst[n][k] = *(const LAS bf16x8*)(lds + PG8_SB(b, h) + boff + n * 2048 + k * 1024); } while (0)
; #define PG8_MMA(ai, bj, At, Bt) do { __builtin_amdgcn_s_setprio(1); _Pragma("unroll") for (int m = 0; m < 4; ++m) _Pragma("unroll") for (int n = 0; n < 2; ++n) _Pragma("unroll") for (int k = 0; k < 2; ++k) \
;         acc[ai][bj][m][n] = __builtin_amdgcn_mfma_f32_16x16x32_bf16(Bt[n][k], At[m][k], acc[ai][bj][m][n], 0, 0, 0); __builtin_amdgcn_s_setprio(0); } while (0)
; #define PG8_WAIT_V(n) asm volatile("s_waitcnt vmcnt(" #n ")" ::: "memory")
; #define PG8_WAIT_L(n) asm volatile("s_waitcnt lgkmcnt(" #n ")" ::: "memory")
; #define PG8_BAR __builtin_amdgcn_s_barrier()
; #define PG8_SCHED __builtin_amdgcn_sched_barrier(0)
; template <class Epi, class Sched>
; __device__ __forceinline__ void gemm_phase(int wv, LAS unsigned char* lds, const Gemm g, const Sched& S, const Epi& E) {
;     ...
;         for (int t = 0; t < nt; t += 2) {
;             const bool last = (t == nt - 2);
;             const char* a1 = cA + (size_t)(t + 1) * kstep;
;             const char* a2 = last ? nA : cA + (size_t)(t + 2) * kstep; const char* b2 = last ? nB : cB + (size_t)(t + 2) * kstep;
;             const char* a3 = a2 + kstep; const char* b3 = b2 + kstep;
;             PG8_LDB(B0, 0, 0); PG8_LDB(B1, 0, 1); PG8_SCHED; PG8_LDA(At, 0, 0); PG8_STAGE(PG8_SA(1, 1), a1 + hstep, voffA);
;             PG8_WAIT_V(8); PG8_WAIT_L(0); PG8_BAR; PG8_MMA(0, 0, At, B0); PG8_MMA(0, 1, At, B1); PG8_BAR; PG8_SCHED;
;             PG8_LDA(At, 0, 1); PG8_STAGE(PG8_SB(0, 0), b2, voffB); PG8_STAGE(PG8_SB(0, 1), b2 + hstepB, voffB); PG8_STAGE(PG8_SA(0, 0), a2, voffA);
;             PG8_WAIT_V(8); PG8_WAIT_L(0); PG8_BAR; PG8_MMA(1, 0, At, B0); PG8_MMA(1, 1, At, B1); PG8_BAR; PG8_SCHED;
.LBB0_801:
	s_add_u32 s20, s18, 0xfffe0080
	s_addc_u32 s21, s19, -1
	s_add_i32 s44, 0, 0x10000
	s_cmp_eq_u32 s43, 4
	s_cselect_b32 s23, s11, s21
	s_cselect_b32 s22, s39, s20
	s_cselect_b32 s21, s13, s42
	s_cselect_b32 s20, s40, s41
	s_add_i32 s46, 0, 0x14000
	v_add_u32_e32 v154, s44, v139
	v_add_u32_e32 v170, s46, v139
	ds_read_b128 v[142:145], v154
	ds_read_b128 v[146:149], v154 offset:1024
	ds_read_b128 v[150:153], v154 offset:2048
	ds_read_b128 v[154:157], v154 offset:3072
	ds_read_b128 v[158:161], v170
	ds_read_b128 v[162:165], v170 offset:1024
	ds_read_b128 v[166:169], v170 offset:2048
	ds_read_b128 v[170:173], v170 offset:3072
	v_lshl_add_u64 v[186:187], s[18:19], 0, v[134:135]
	s_add_i32 m0, s29, 0xc000
	ds_read_b128 v[174:177], v141
	ds_read_b128 v[178:181], v141 offset:1024
	ds_read_b128 v[182:185], v141 offset:2048
	ds_read_b128 v[198:201], v141 offset:3072
	ds_read_b128 v[202:205], v141 offset:4096
	ds_read_b128 v[206:209], v141 offset:5120
	ds_read_b128 v[210:213], v141 offset:6144
	ds_read_b128 v[214:217], v141 offset:7168
	global_load_lds_dwordx4 v[186:187], off
	v_lshl_add_u64 v[186:187], s[18:19], 0, v[136:137]
	s_add_i32 m0, s29, 0xe000
	s_nop 0
	global_load_lds_dwordx4 v[186:187], off
	s_waitcnt vmcnt(8)
	s_waitcnt lgkmcnt(0)
	s_barrier
	s_setprio 1
	s_waitcnt lgkmcnt(0)
	v_mfma_f32_16x16x32_bf16 v[124:127], v[142:145], v[174:177], v[124:127]
	v_mfma_f32_16x16x32_bf16 v[120:123], v[150:153], v[174:177], v[120:123]
	v_mfma_f32_16x16x32_bf16 v[116:119], v[142:145], v[182:185], v[116:119]
	v_mfma_f32_16x16x32_bf16 v[108:111], v[150:153], v[182:185], v[108:111]
	v_mfma_f32_16x16x32_bf16 v[100:103], v[142:145], v[202:205], v[100:103]
	v_mfma_f32_16x16x32_bf16 v[96:99], v[150:153], v[202:205], v[96:99]
	v_mfma_f32_16x16x32_bf16 v[84:87], v[142:145], v[210:213], v[84:87]
	v_mfma_f32_16x16x32_bf16 v[80:83], v[150:153], v[210:213], v[80:83]
	v_mfma_f32_16x16x32_bf16 v[124:127], v[146:149], v[178:181], v[124:127]
	v_mfma_f32_16x16x32_bf16 v[120:123], v[154:157], v[178:181], v[120:123]
	v_mfma_f32_16x16x32_bf16 v[116:119], v[146:149], v[198:201], v[116:119]
	v_mfma_f32_16x16x32_bf16 v[108:111], v[154:157], v[198:201], v[108:111]
	v_mfma_f32_16x16x32_bf16 v[100:103], v[146:149], v[206:209], v[100:103]
	v_mfma_f32_16x16x32_bf16 v[96:99], v[154:157], v[206:209], v[96:99]
	v_mfma_f32_16x16x32_bf16 v[84:87], v[146:149], v[214:217], v[84:87]
	v_mfma_f32_16x16x32_bf16 v[80:83], v[154:157], v[214:217], v[80:83]
	s_setprio 0
	s_setprio 1
	v_mfma_f32_16x16x32_bf16 v[112:115], v[158:161], v[174:177], v[112:115]
	v_mfma_f32_16x16x32_bf16 v[104:107], v[166:169], v[174:177], v[104:107]
	v_mfma_f32_16x16x32_bf16 v[92:95], v[158:161], v[182:185], v[92:95]
	v_mfma_f32_16x16x32_bf16 v[88:91], v[166:169], v[182:185], v[88:91]
	v_mfma_f32_16x16x32_bf16 v[76:79], v[158:161], v[202:205], v[76:79]
	v_mfma_f32_16x16x32_bf16 v[72:75], v[166:169], v[202:205], v[72:75]
	v_mfma_f32_16x16x32_bf16 v[68:71], v[158:161], v[210:213], v[68:71]
	v_mfma_f32_16x16x32_bf16 v[64:67], v[166:169], v[210:213], v[64:67]
	v_mfma_f32_16x16x32_bf16 v[112:115], v[162:165], v[178:181], v[112:115]
	v_mfma_f32_16x16x32_bf16 v[104:107], v[170:173], v[178:181], v[104:107]
	v_mfma_f32_16x16x32_bf16 v[92:95], v[162:165], v[198:201], v[92:95]
	v_mfma_f32_16x16x32_bf16 v[88:91], v[170:173], v[198:201], v[88:91]
	v_mfma_f32_16x16x32_bf16 v[76:79], v[162:165], v[206:209], v[76:79]
	v_mfma_f32_16x16x32_bf16 v[72:75], v[170:173], v[206:209], v[72:75]
	v_mfma_f32_16x16x32_bf16 v[68:71], v[162:165], v[214:217], v[68:71]
	v_mfma_f32_16x16x32_bf16 v[64:67], v[170:173], v[214:217], v[64:67]
	s_setprio 0
	s_barrier
	s_add_i32 s44, s44, s28
	v_lshl_add_u64 v[186:187], s[20:21], 0, v[188:189]
	s_mov_b32 m0, s44
	ds_read_b128 v[174:177], v141 offset:16384
	ds_read_b128 v[178:181], v141 offset:17408
	ds_read_b128 v[182:185], v141 offset:18432
	ds_read_b128 v[198:201], v141 offset:19456
	ds_read_b128 v[202:205], v141 offset:20480
	ds_read_b128 v[206:209], v141 offset:21504
	ds_read_b128 v[210:213], v141 offset:22528
	ds_read_b128 v[214:217], v141 offset:23552
	global_load_lds_dwordx4 v[186:187], off
	s_add_i32 m0, s44, 0x2000
	s_add_u32 s44, s20, 0x2000
	v_lshl_add_u64 v[218:219], s[20:21], 0, v[128:129]
	s_addc_u32 s45, s21, 0
	s_add_i32 s46, s46, s28
	global_load_lds_dwordx4 v[218:219], off
	v_lshl_add_u64 v[220:221], s[44:45], 0, v[188:189]
	s_mov_b32 m0, s46
	v_lshl_add_u64 v[222:223], s[22:23], 0, v[130:131]
	global_load_lds_dwordx4 v[220:221], off
	v_lshl_add_u64 v[220:221], s[44:45], 0, v[128:129]
	s_add_i32 m0, s46, 0x2000
	s_nop 0
	global_load_lds_dwordx4 v[220:221], off
	v_lshl_add_u64 v[220:221], s[22:23], 0, v[132:133]
	s_mov_b32 m0, s29
	s_nop 0
	global_load_lds_dwordx4 v[220:221], off
	s_mov_b32 m0, s30
	s_nop 0
	global_load_lds_dwordx4 v[222:223], off
	s_nop 0
	s_waitcnt vmcnt(8)
	s_waitcnt lgkmcnt(0)
	s_barrier
; #define PG8_STAGE(bufoff, gbase, voff) do { _Pragma("unroll") for (int _i = 0; _i < 2; ++_i) \
;         __builtin_amdgcn_global_load_lds((const unsigned*)((const char*)(gbase) + (voff)[_i]), (LAS unsigned*)(lds + (bufoff) + ldsw + _i * 8192), 16, 0, 0); } while (0)
; #define PG8_LDA(dst, b, h) do { _Pragma("unroll") for (int m = 0; m < 4; ++m) _Pragma("unroll") for (int k = 0; k < 2; ++k) dst[m][k] = *(const LAS bf16x8*)(lds + PG8_SA(b, h) + aoff + m * 2048 + k * 1024); } while (0)
; #define PG8_LDB(dst, b, h) do { _Pragma("unroll") for (int n = 0; n < 2; ++n) _Pragma("unroll") for (int k = 0; k < 2; ++k) dst[n][k] = *(const LAS bf16x8*)(lds + PG8_SB(b, h) + boff + n * 2048 + k * 1024); } while (0)
; #define PG8_MMA(ai, bj, At, Bt) do { __builtin_amdgcn_s_setprio(1); _Pragma("unroll") for (int m = 0; m < 4; ++m) _Pragma("unroll") for (int n = 0; n < 2; ++n) _Pragma("unroll") for (int k = 0; k < 2; ++k) \
;         acc[ai][bj][m][n] = __builtin_amdgcn_mfma_f32_16x16x32_bf16(Bt[n][k], At[m][k], acc[ai][bj][m][n], 0, 0, 0); __builtin_amdgcn_s_setprio(0); } while (0)
; #define PG8_WAIT_V(n) asm volatile("s_waitcnt vmcnt(" #n ")" ::: "memory")
; #define PG8_WAIT_L(n) asm volatile("s_waitcnt lgkmcnt(" #n ")" ::: "memory")
; #define PG8_BAR __builtin_amdgcn_s_barrier()
; #define PG8_SCHED __builtin_amdgcn_sched_barrier(0)
; template <class Epi, class Sched>
; __device__ __forceinline__ void gemm_phase(int wv, LAS unsigned char* lds, const Gemm g, const Sched& S, const Epi& E) {
;     ...
;             PG8_WAIT_V(8); PG8_WAIT_L(0); PG8_BAR; PG8_MMA(1, 0, At, B0); PG8_MMA(1, 1, At, B1); PG8_BAR; PG8_SCHED;
;             PG8_LDB(B0, 1, 0); PG8_LDB(B1, 1, 1); PG8_SCHED; PG8_LDA(At, 1, 0); PG8_STAGE(PG8_SA(0, 1), a2 + hstep, voffA);
;             PG8_WAIT_V(8); PG8_WAIT_L(0); PG8_BAR; PG8_MMA(0, 0, At, B0); PG8_MMA(0, 1, At, B1); PG8_BAR; PG8_SCHED;
	s_setprio 1
	s_waitcnt lgkmcnt(0)
	v_mfma_f32_16x16x32_bf16 v[60:63], v[142:145], v[174:177], v[60:63]
	v_mfma_f32_16x16x32_bf16 v[56:59], v[150:153], v[174:177], v[56:59]
	v_mfma_f32_16x16x32_bf16 v[52:55], v[142:145], v[182:185], v[52:55]
	v_mfma_f32_16x16x32_bf16 v[48:51], v[150:153], v[182:185], v[48:51]
	v_mfma_f32_16x16x32_bf16 v[36:39], v[142:145], v[202:205], v[36:39]
	v_mfma_f32_16x16x32_bf16 v[32:35], v[150:153], v[202:205], v[32:35]
	v_mfma_f32_16x16x32_bf16 v[20:23], v[142:145], v[210:213], v[20:23]
	v_mfma_f32_16x16x32_bf16 v[16:19], v[150:153], v[210:213], v[16:19]
	v_mfma_f32_16x16x32_bf16 v[60:63], v[146:149], v[178:181], v[60:63]
	v_mfma_f32_16x16x32_bf16 v[56:59], v[154:157], v[178:181], v[56:59]
	v_mfma_f32_16x16x32_bf16 v[52:55], v[146:149], v[198:201], v[52:55]
	v_mfma_f32_16x16x32_bf16 v[48:51], v[154:157], v[198:201], v[48:51]
	v_mfma_f32_16x16x32_bf16 v[36:39], v[146:149], v[206:209], v[36:39]
	v_mfma_f32_16x16x32_bf16 v[32:35], v[154:157], v[206:209], v[32:35]
	v_mfma_f32_16x16x32_bf16 v[20:23], v[146:149], v[214:217], v[20:23]
	v_mfma_f32_16x16x32_bf16 v[16:19], v[154:157], v[214:217], v[16:19]
	s_setprio 0
	s_setprio 1
	v_mfma_f32_16x16x32_bf16 v[44:47], v[158:161], v[174:177], v[44:47]
	v_mfma_f32_16x16x32_bf16 v[40:43], v[166:169], v[174:177], v[40:43]
	v_mfma_f32_16x16x32_bf16 v[28:31], v[158:161], v[182:185], v[28:31]
	v_mfma_f32_16x16x32_bf16 v[24:27], v[166:169], v[182:185], v[24:27]
	v_mfma_f32_16x16x32_bf16 v[12:15], v[158:161], v[202:205], v[12:15]
	v_mfma_f32_16x16x32_bf16 v[8:11], v[166:169], v[202:205], v[8:11]
	v_mfma_f32_16x16x32_bf16 v[4:7], v[158:161], v[210:213], v[4:7]
	v_mfma_f32_16x16x32_bf16 v[0:3], v[166:169], v[210:213], v[0:3]
	v_mfma_f32_16x16x32_bf16 v[44:47], v[162:165], v[178:181], v[44:47]
	v_mfma_f32_16x16x32_bf16 v[40:43], v[170:173], v[178:181], v[40:43]
	v_mfma_f32_16x16x32_bf16 v[28:31], v[162:165], v[198:201], v[28:31]
	v_mfma_f32_16x16x32_bf16 v[24:27], v[170:173], v[198:201], v[24:27]
	v_mfma_f32_16x16x32_bf16 v[12:15], v[162:165], v[206:209], v[12:15]
	v_mfma_f32_16x16x32_bf16 v[8:11], v[170:173], v[206:209], v[8:11]
	v_mfma_f32_16x16x32_bf16 v[4:7], v[162:165], v[214:217], v[4:7]
	v_mfma_f32_16x16x32_bf16 v[0:3], v[170:173], v[214:217], v[0:3]
	s_setprio 0
	s_barrier
	s_add_i32 s44, 0, 0x1c000
	v_add_u32_e32 v154, s95, v139
	v_add_u32_e32 v170, s44, v139
	ds_read_b128 v[142:145], v154
	ds_read_b128 v[146:149], v154 offset:1024
	ds_read_b128 v[150:153], v154 offset:2048
	ds_read_b128 v[154:157], v154 offset:3072
	ds_read_b128 v[158:161], v170
	ds_read_b128 v[162:165], v170 offset:1024
	ds_read_b128 v[166:169], v170 offset:2048
	ds_read_b128 v[170:173], v170 offset:3072
	s_add_u32 s22, s22, 0x20000
	s_addc_u32 s23, s23, 0
	s_mov_b32 m0, s31
	v_lshl_add_u64 v[228:229], s[22:23], 0, v[132:133]
	ds_read_b128 v[174:177], v141 offset:32768
	ds_read_b128 v[178:181], v141 offset:33792
	ds_read_b128 v[182:185], v141 offset:34816
	ds_read_b128 v[198:201], v141 offset:35840
	ds_read_b128 v[202:205], v141 offset:36864
	ds_read_b128 v[206:209], v141 offset:37888
	ds_read_b128 v[210:213], v141 offset:38912
	ds_read_b128 v[214:217], v141 offset:39936
	global_load_lds_dwordx4 v[228:229], off
	v_lshl_add_u64 v[228:229], s[22:23], 0, v[130:131]
	s_mov_b32 m0, s34
	s_nop 0
	global_load_lds_dwordx4 v[228:229], off
	s_nop 0
	s_waitcnt vmcnt(8)
	s_waitcnt lgkmcnt(0)
	s_barrier
	s_setprio 1
	s_waitcnt lgkmcnt(0)
	v_mfma_f32_16x16x32_bf16 v[124:127], v[142:145], v[174:177], v[124:127]
	v_mfma_f32_16x16x32_bf16 v[120:123], v[150:153], v[174:177], v[120:123]
	v_mfma_f32_16x16x32_bf16 v[116:119], v[142:145], v[182:185], v[116:119]
	v_mfma_f32_16x16x32_bf16 v[108:111], v[150:153], v[182:185], v[108:111]
	v_mfma_f32_16x16x32_bf16 v[100:103], v[142:145], v[202:205], v[100:103]
	v_mfma_f32_16x16x32_bf16 v[96:99], v[150:153], v[202:205], v[96:99]
	v_mfma_f32_16x16x32_bf16 v[84:87], v[142:145], v[210:213], v[84:87]
	v_mfma_f32_16x16x32_bf16 v[80:83], v[150:153], v[210:213], v[80:83]
	v_mfma_f32_16x16x32_bf16 v[124:127], v[146:149], v[178:181], v[124:127]
	v_mfma_f32_16x16x32_bf16 v[120:123], v[154:157], v[178:181], v[120:123]
	v_mfma_f32_16x16x32_bf16 v[116:119], v[146:149], v[198:201], v[116:119]
	v_mfma_f32_16x16x32_bf16 v[108:111], v[154:157], v[198:201], v[108:111]
	v_mfma_f32_16x16x32_bf16 v[100:103], v[146:149], v[206:209], v[100:103]
	v_mfma_f32_16x16x32_bf16 v[96:99], v[154:157], v[206:209], v[96:99]
	v_mfma_f32_16x16x32_bf16 v[84:87], v[146:149], v[214:217], v[84:87]
	v_mfma_f32_16x16x32_bf16 v[80:83], v[154:157], v[214:217], v[80:83]
	s_setprio 0
	s_setprio 1
	v_mfma_f32_16x16x32_bf16 v[112:115], v[158:161], v[174:177], v[112:115]
	v_mfma_f32_16x16x32_bf16 v[104:107], v[166:169], v[174:177], v[104:107]
	v_mfma_f32_16x16x32_bf16 v[92:95], v[158:161], v[182:185], v[92:95]
	v_mfma_f32_16x16x32_bf16 v[88:91], v[166:169], v[182:185], v[88:91]
	v_mfma_f32_16x16x32_bf16 v[76:79], v[158:161], v[202:205], v[76:79]
	v_mfma_f32_16x16x32_bf16 v[72:75], v[166:169], v[202:205], v[72:75]
	v_mfma_f32_16x16x32_bf16 v[68:71], v[158:161], v[210:213], v[68:71]
	v_mfma_f32_16x16x32_bf16 v[64:67], v[166:169], v[210:213], v[64:67]
	v_mfma_f32_16x16x32_bf16 v[112:115], v[162:165], v[178:181], v[112:115]
	v_mfma_f32_16x16x32_bf16 v[104:107], v[170:173], v[178:181], v[104:107]
	v_mfma_f32_16x16x32_bf16 v[92:95], v[162:165], v[198:201], v[92:95]
	v_mfma_f32_16x16x32_bf16 v[88:91], v[170:173], v[198:201], v[88:91]
	v_mfma_f32_16x16x32_bf16 v[76:79], v[162:165], v[206:209], v[76:79]
	v_mfma_f32_16x16x32_bf16 v[72:75], v[170:173], v[206:209], v[72:75]
	v_mfma_f32_16x16x32_bf16 v[68:71], v[162:165], v[214:217], v[68:71]
	v_mfma_f32_16x16x32_bf16 v[64:67], v[170:173], v[214:217], v[64:67]
	s_setprio 0
	s_barrier
; #define PG8_STAGE(bufoff, gbase, voff) do { _Pragma("unroll") for (int _i = 0; _i < 2; ++_i) \
;         __builtin_amdgcn_global_load_lds((const unsigned*)((const char*)(gbase) + (voff)[_i]), (LAS unsigned*)(lds + (bufoff) + ldsw + _i * 8192), 16, 0, 0); } while (0)
; #define PG8_LDA(dst, b, h) do { _Pragma("unroll") for (int m = 0; m < 4; ++m) _Pragma("unroll") for (int k = 0; k < 2; ++k) dst[m][k] = *(const LAS bf16x8*)(lds + PG8_SA(b, h) + aoff + m * 2048 + k * 1024); } while (0)
; #define PG8_MMA(ai, bj, At, Bt) do { __builtin_amdgcn_s_setprio(1); _Pragma("unroll") for (int m = 0; m < 4; ++m) _Pragma("unroll") for (int n = 0; n < 2; ++n) _Pragma("unroll") for (int k = 0; k < 2; ++k) \
;         acc[ai][bj][m][n] = __builtin_amdgcn_mfma_f32_16x16x32_bf16(Bt[n][k], At[m][k], acc[ai][bj][m][n], 0, 0, 0); __builtin_amdgcn_s_setprio(0); } while (0)
; #define PG8_WAIT_V(n) asm volatile("s_waitcnt vmcnt(" #n ")" ::: "memory")
; #define PG8_WAIT_L(n) asm volatile("s_waitcnt lgkmcnt(" #n ")" ::: "memory")
; #define PG8_BAR __builtin_amdgcn_s_barrier()
; #define PG8_SCHED __builtin_amdgcn_sched_barrier(0)
; template <class Epi, class Sched>
; __device__ __forceinline__ void gemm_phase(int wv, LAS unsigned char* lds, const Gemm g, const Sched& S, const Epi& E) {
;     ...
;             PG8_LDA(At, 1, 1); PG8_STAGE(PG8_SB(1, 0), b3, voffB); PG8_STAGE(PG8_SB(1, 1), b3 + hstepB, voffB); PG8_STAGE(PG8_SA(1, 0), a3, voffA);
;             PG8_WAIT_V(8); PG8_WAIT_L(0); PG8_BAR; PG8_MMA(1, 0, At, B0); PG8_MMA(1, 1, At, B1); PG8_BAR; PG8_SCHED;
;         }
;         if (wr == 0) PG8_BAR;
	s_add_i32 s22, s95, s28
	v_lshl_add_u64 v[186:187], v[186:187], 0, s[74:75]
	s_mov_b32 m0, s22
	ds_read_b128 v[174:177], v141 offset:49152
	ds_read_b128 v[178:181], v141 offset:50176
	ds_read_b128 v[182:185], v141 offset:51200
	ds_read_b128 v[198:201], v141 offset:52224
	ds_read_b128 v[202:205], v141 offset:53248
	ds_read_b128 v[206:209], v141 offset:54272
	ds_read_b128 v[210:213], v141 offset:55296
	ds_read_b128 v[214:217], v141 offset:56320
	global_load_lds_dwordx4 v[186:187], off
	s_add_i32 m0, s22, 0x2000
	s_add_u32 s20, s20, 0x2080
	v_lshl_add_u64 v[186:187], v[218:219], 0, s[74:75]
	s_addc_u32 s21, s21, 0
	s_add_i32 s22, s44, s28
	global_load_lds_dwordx4 v[186:187], off
	v_lshl_add_u64 v[186:187], s[20:21], 0, v[188:189]
	s_mov_b32 m0, s22
	s_nop 0
	global_load_lds_dwordx4 v[186:187], off
	v_lshl_add_u64 v[186:187], s[20:21], 0, v[128:129]
	s_add_i32 m0, s22, 0x2000
	s_nop 0
	global_load_lds_dwordx4 v[186:187], off
	v_lshl_add_u64 v[186:187], v[220:221], 0, s[74:75]
	s_mov_b32 m0, s35
	s_nop 0
	global_load_lds_dwordx4 v[186:187], off
	v_lshl_add_u64 v[186:187], v[222:223], 0, s[74:75]
	s_mov_b32 m0, s36
	s_nop 0
	global_load_lds_dwordx4 v[186:187], off
	s_waitcnt vmcnt(8)
	s_waitcnt lgkmcnt(0)
	s_barrier
	s_setprio 1
	s_waitcnt lgkmcnt(0)
	v_mfma_f32_16x16x32_bf16 v[60:63], v[142:145], v[174:177], v[60:63]
	v_mfma_f32_16x16x32_bf16 v[56:59], v[150:153], v[174:177], v[56:59]
	v_mfma_f32_16x16x32_bf16 v[52:55], v[142:145], v[182:185], v[52:55]
	v_mfma_f32_16x16x32_bf16 v[48:51], v[150:153], v[182:185], v[48:51]
	v_mfma_f32_16x16x32_bf16 v[36:39], v[142:145], v[202:205], v[36:39]
	v_mfma_f32_16x16x32_bf16 v[32:35], v[150:153], v[202:205], v[32:35]
	v_mfma_f32_16x16x32_bf16 v[20:23], v[142:145], v[210:213], v[20:23]
	v_mfma_f32_16x16x32_bf16 v[16:19], v[150:153], v[210:213], v[16:19]
	v_mfma_f32_16x16x32_bf16 v[60:63], v[146:149], v[178:181], v[60:63]
	v_mfma_f32_16x16x32_bf16 v[56:59], v[154:157], v[178:181], v[56:59]
	v_mfma_f32_16x16x32_bf16 v[52:55], v[146:149], v[198:201], v[52:55]
	v_mfma_f32_16x16x32_bf16 v[48:51], v[154:157], v[198:201], v[48:51]
	v_mfma_f32_16x16x32_bf16 v[36:39], v[146:149], v[206:209], v[36:39]
	v_mfma_f32_16x16x32_bf16 v[32:35], v[154:157], v[206:209], v[32:35]
	v_mfma_f32_16x16x32_bf16 v[20:23], v[146:149], v[214:217], v[20:23]
	v_mfma_f32_16x16x32_bf16 v[16:19], v[154:157], v[214:217], v[16:19]
	s_setprio 0
	s_setprio 1
	v_mfma_f32_16x16x32_bf16 v[44:47], v[158:161], v[174:177], v[44:47]
	v_mfma_f32_16x16x32_bf16 v[40:43], v[166:169], v[174:177], v[40:43]
	v_mfma_f32_16x16x32_bf16 v[28:31], v[158:161], v[182:185], v[28:31]
	v_mfma_f32_16x16x32_bf16 v[24:27], v[166:169], v[182:185], v[24:27]
	v_mfma_f32_16x16x32_bf16 v[12:15], v[158:161], v[202:205], v[12:15]
	v_mfma_f32_16x16x32_bf16 v[8:11], v[166:169], v[202:205], v[8:11]
	v_mfma_f32_16x16x32_bf16 v[4:7], v[158:161], v[210:213], v[4:7]
	v_mfma_f32_16x16x32_bf16 v[0:3], v[166:169], v[210:213], v[0:3]
	v_mfma_f32_16x16x32_bf16 v[44:47], v[162:165], v[178:181], v[44:47]
	v_mfma_f32_16x16x32_bf16 v[40:43], v[170:173], v[178:181], v[40:43]
	v_mfma_f32_16x16x32_bf16 v[28:31], v[162:165], v[198:201], v[28:31]
	v_mfma_f32_16x16x32_bf16 v[24:27], v[170:173], v[198:201], v[24:27]
	v_mfma_f32_16x16x32_bf16 v[12:15], v[162:165], v[206:209], v[12:15]
	v_mfma_f32_16x16x32_bf16 v[8:11], v[170:173], v[206:209], v[8:11]
	v_mfma_f32_16x16x32_bf16 v[4:7], v[162:165], v[214:217], v[4:7]
	v_mfma_f32_16x16x32_bf16 v[0:3], v[170:173], v[214:217], v[0:3]
	s_setprio 0
	s_barrier
	s_add_i32 s43, s43, 2
	s_add_u32 s18, s18, 0x100
	s_addc_u32 s19, s19, 0
	s_add_u32 s41, s41, 0x100
	s_addc_u32 s42, s42, 0
	s_cmp_gt_u32 s43, 5
	s_cbranch_scc0 .LBB0_801
	s_and_b64 vcc, exec, s[8:9]
	s_cbranch_vccz .LBB0_804
	s_barrier

; #define PG8_STAGE(bufoff, gbase, voff) do { _Pragma("unroll") for (int _i = 0; _i < 2; ++_i) \
;         __builtin_amdgcn_global_load_lds((const unsigned*)((const char*)(gbase) + (voff)[_i]), (LAS unsigned*)(lds + (bufoff) + ldsw + _i * 8192), 16, 0, 0); } while (0)
; #define PG8_LDA(dst, b, h) do { _Pragma("unroll") for (int m = 0; m < 4; ++m) _Pragma("unroll") for (int k = 0; k < 2; ++k) dst[m][k] = *(const LAS bf16x8*)(lds + PG8_SA(b, h) + aoff + m * 2048 + k * 1024); } while (0)
; #define PG8_LDB(dst, b, h) do { _Pragma("unroll") for (int n = 0; n < 2; ++n) _Pragma("unroll") for (int k = 0; k < 2; ++k) dst[n][k] = *(const LAS bf16x8*)(lds + PG8_SB(b, h) + boff + n * 2048 + k * 1024); } while (0)
; #define PG8_MMA(ai, bj, At, Bt) do { __builtin_amdgcn_s_setprio(1); _Pragma("unroll") for (int m = 0; m < 4; ++m) _Pragma("unroll") for (int n = 0; n < 2; ++n) _Pragma("unroll") for (int k = 0; k < 2; ++k) \
;         acc[ai][bj][m][n] = __builtin_amdgcn_mfma_f32_16x16x32_bf16(Bt[n][k], At[m][k], acc[ai][bj][m][n], 0, 0, 0); __builtin_amdgcn_s_setprio(0); } while (0)
; #define PG8_WAIT_V(n) asm volatile("s_waitcnt vmcnt(" #n ")" ::: "memory")
; #define PG8_WAIT_L(n) asm volatile("s_waitcnt lgkmcnt(" #n ")" ::: "memory")
; #define PG8_BAR __builtin_amdgcn_s_barrier()
; #define PG8_SCHED __builtin_amdgcn_sched_barrier(0)
; template <class Epi, class Sched>
; __device__ __forceinline__ void gemm_phase(int wv, LAS unsigned char* lds, const Gemm g, const Sched& S, const Epi& E) {
;     ...
;         for (int t = 0; t < nt; t += 2) {
;             const bool last = (t == nt - 2);
;             const char* a1 = cA + (size_t)(t + 1) * kstep;
;             const char* a2 = last ? nA : cA + (size_t)(t + 2) * kstep; const char* b2 = last ? nB : cB + (size_t)(t + 2) * kstep;
;             const char* a3 = a2 + kstep; const char* b3 = b2 + kstep;
;             PG8_LDB(B0, 0, 0); PG8_LDB(B1, 0, 1); PG8_SCHED; PG8_LDA(At, 0, 0); PG8_STAGE(PG8_SA(1, 1), a1 + hstep, voffA);
;             PG8_WAIT_V(8); PG8_WAIT_L(0); PG8_BAR; PG8_MMA(0, 0, At, B0); PG8_MMA(0, 1, At, B1); PG8_BAR; PG8_SCHED;
;             PG8_LDA(At, 0, 1); PG8_STAGE(PG8_SB(0, 0), b2, voffB); PG8_STAGE(PG8_SB(0, 1), b2 + hstepB, voffB); PG8_STAGE(PG8_SA(0, 0), a2, voffA);
;             PG8_WAIT_V(8); PG8_WAIT_L(0); PG8_BAR; PG8_MMA(1, 0, At, B0); PG8_MMA(1, 1, At, B1); PG8_BAR; PG8_SCHED;
.LBB0_821:
	s_add_u32 s22, s20, 0xfffc0080
	s_addc_u32 s23, s21, -1
	s_add_i32 s47, 0, 0x10000
	s_cmp_eq_u32 s46, 12
	s_cselect_b32 s25, s13, s23
	s_cselect_b32 s24, s42, s22
	s_cselect_b32 s23, s15, s45
	s_cselect_b32 s22, s43, s44
	s_add_i32 s50, 0, 0x14000
	v_add_u32_e32 v140, s47, v201
	v_add_u32_e32 v156, s50, v201
	ds_read_b128 v[120:123], v140
	ds_read_b128 v[124:127], v140 offset:1024
	ds_read_b128 v[136:139], v140 offset:2048
	ds_read_b128 v[140:143], v140 offset:3072
	ds_read_b128 v[144:147], v156
	ds_read_b128 v[148:151], v156 offset:1024
	ds_read_b128 v[152:155], v156 offset:2048
	ds_read_b128 v[156:159], v156 offset:3072
	v_lshl_add_u64 v[186:187], s[20:21], 0, v[174:175]
	s_add_i32 m0, s31, 0xc000
	ds_read_b128 v[160:163], v203
	ds_read_b128 v[164:167], v203 offset:1024
	ds_read_b128 v[178:181], v203 offset:2048
	ds_read_b128 v[182:185], v203 offset:3072
	ds_read_b128 v[204:207], v203 offset:4096
	ds_read_b128 v[208:211], v203 offset:5120
	ds_read_b128 v[212:215], v203 offset:6144
	ds_read_b128 v[216:219], v203 offset:7168
	global_load_lds_dwordx4 v[186:187], off
	v_lshl_add_u64 v[186:187], s[20:21], 0, v[176:177]
	s_add_i32 m0, s31, 0xe000
	s_nop 0
	global_load_lds_dwordx4 v[186:187], off
	s_nop 0
	s_waitcnt vmcnt(8)
	s_waitcnt lgkmcnt(0)
	s_barrier
	s_setprio 1
	s_waitcnt lgkmcnt(0)
	v_mfma_f32_16x16x32_bf16 v[132:135], v[120:123], v[160:163], v[132:135]
	v_mfma_f32_16x16x32_bf16 v[116:119], v[136:139], v[160:163], v[116:119]
	v_mfma_f32_16x16x32_bf16 v[108:111], v[120:123], v[178:181], v[108:111]
	v_mfma_f32_16x16x32_bf16 v[100:103], v[136:139], v[178:181], v[100:103]
	v_mfma_f32_16x16x32_bf16 v[92:95], v[120:123], v[204:207], v[92:95]
	v_mfma_f32_16x16x32_bf16 v[84:87], v[136:139], v[204:207], v[84:87]
	v_mfma_f32_16x16x32_bf16 v[76:79], v[120:123], v[212:215], v[76:79]
	v_mfma_f32_16x16x32_bf16 v[68:71], v[136:139], v[212:215], v[68:71]
	v_mfma_f32_16x16x32_bf16 v[132:135], v[124:127], v[164:167], v[132:135]
	v_mfma_f32_16x16x32_bf16 v[116:119], v[140:143], v[164:167], v[116:119]
	v_mfma_f32_16x16x32_bf16 v[108:111], v[124:127], v[182:185], v[108:111]
	v_mfma_f32_16x16x32_bf16 v[100:103], v[140:143], v[182:185], v[100:103]
	v_mfma_f32_16x16x32_bf16 v[92:95], v[124:127], v[208:211], v[92:95]
	v_mfma_f32_16x16x32_bf16 v[84:87], v[140:143], v[208:211], v[84:87]
	v_mfma_f32_16x16x32_bf16 v[76:79], v[124:127], v[216:219], v[76:79]
	v_mfma_f32_16x16x32_bf16 v[68:71], v[140:143], v[216:219], v[68:71]
	s_setprio 0
	s_setprio 1
	v_mfma_f32_16x16x32_bf16 v[128:131], v[144:147], v[160:163], v[128:131]
	v_mfma_f32_16x16x32_bf16 v[112:115], v[152:155], v[160:163], v[112:115]
	v_mfma_f32_16x16x32_bf16 v[104:107], v[144:147], v[178:181], v[104:107]
	v_mfma_f32_16x16x32_bf16 v[96:99], v[152:155], v[178:181], v[96:99]
	v_mfma_f32_16x16x32_bf16 v[88:91], v[144:147], v[204:207], v[88:91]
	v_mfma_f32_16x16x32_bf16 v[80:83], v[152:155], v[204:207], v[80:83]
	v_mfma_f32_16x16x32_bf16 v[72:75], v[144:147], v[212:215], v[72:75]
	v_mfma_f32_16x16x32_bf16 v[64:67], v[152:155], v[212:215], v[64:67]
	v_mfma_f32_16x16x32_bf16 v[128:131], v[148:151], v[164:167], v[128:131]
	v_mfma_f32_16x16x32_bf16 v[112:115], v[156:159], v[164:167], v[112:115]
	v_mfma_f32_16x16x32_bf16 v[104:107], v[148:151], v[182:185], v[104:107]
	v_mfma_f32_16x16x32_bf16 v[96:99], v[156:159], v[182:185], v[96:99]
	v_mfma_f32_16x16x32_bf16 v[88:91], v[148:151], v[208:211], v[88:91]
	v_mfma_f32_16x16x32_bf16 v[80:83], v[156:159], v[208:211], v[80:83]
	v_mfma_f32_16x16x32_bf16 v[72:75], v[148:151], v[216:219], v[72:75]
	v_mfma_f32_16x16x32_bf16 v[64:67], v[156:159], v[216:219], v[64:67]
	s_setprio 0
	s_barrier
	s_add_i32 s47, s47, s30
	v_lshl_add_u64 v[186:187], s[22:23], 0, v[188:189]
	s_mov_b32 m0, s47
	ds_read_b128 v[160:163], v203 offset:16384
	ds_read_b128 v[164:167], v203 offset:17408
	ds_read_b128 v[178:181], v203 offset:18432
	ds_read_b128 v[182:185], v203 offset:19456
	ds_read_b128 v[204:207], v203 offset:20480
	ds_read_b128 v[208:211], v203 offset:21504
	ds_read_b128 v[212:215], v203 offset:22528
	ds_read_b128 v[216:219], v203 offset:23552
	global_load_lds_dwordx4 v[186:187], off
	s_add_i32 m0, s47, 0x2000
	s_add_u32 s48, s22, 0x200000
	v_lshl_add_u64 v[198:199], s[22:23], 0, v[168:169]
	s_addc_u32 s49, s23, 0
	s_add_i32 s47, s50, s30
	global_load_lds_dwordx4 v[198:199], off
	v_lshl_add_u64 v[220:221], s[48:49], 0, v[188:189]
	s_mov_b32 m0, s47
	v_lshl_add_u64 v[222:223], s[24:25], 0, v[170:171]
	global_load_lds_dwordx4 v[220:221], off
	v_lshl_add_u64 v[220:221], s[48:49], 0, v[168:169]
	s_add_i32 m0, s47, 0x2000
	s_nop 0
	global_load_lds_dwordx4 v[220:221], off
	v_lshl_add_u64 v[220:221], s[24:25], 0, v[172:173]
	s_mov_b32 m0, s31
	s_nop 0
	global_load_lds_dwordx4 v[220:221], off
	s_mov_b32 m0, s34
	s_nop 0
	global_load_lds_dwordx4 v[222:223], off
	s_nop 0
	s_waitcnt vmcnt(8)
	s_waitcnt lgkmcnt(0)
	s_barrier
; #define PG8_STAGE(bufoff, gbase, voff) do { _Pragma("unroll") for (int _i = 0; _i < 2; ++_i) \
;         __builtin_amdgcn_global_load_lds((const unsigned*)((const char*)(gbase) + (voff)[_i]), (LAS unsigned*)(lds + (bufoff) + ldsw + _i * 8192), 16, 0, 0); } while (0)
; #define PG8_LDA(dst, b, h) do { _Pragma("unroll") for (int m = 0; m < 4; ++m) _Pragma("unroll") for (int k = 0; k < 2; ++k) dst[m][k] = *(const LAS bf16x8*)(lds + PG8_SA(b, h) + aoff + m * 2048 + k * 1024); } while (0)
; #define PG8_LDB(dst, b, h) do { _Pragma("unroll") for (int n = 0; n < 2; ++n) _Pragma("unroll") for (int k = 0; k < 2; ++k) dst[n][k] = *(const LAS bf16x8*)(lds + PG8_SB(b, h) + boff + n * 2048 + k * 1024); } while (0)
; #define PG8_MMA(ai, bj, At, Bt) do { __builtin_amdgcn_s_setprio(1); _Pragma("unroll") for (int m = 0; m < 4; ++m) _Pragma("unroll") for (int n = 0; n < 2; ++n) _Pragma("unroll") for (int k = 0; k < 2; ++k) \
;         acc[ai][bj][m][n] = __builtin_amdgcn_mfma_f32_16x16x32_bf16(Bt[n][k], At[m][k], acc[ai][bj][m][n], 0, 0, 0); __builtin_amdgcn_s_setprio(0); } while (0)
; #define PG8_WAIT_V(n) asm volatile("s_waitcnt vmcnt(" #n ")" ::: "memory")
; #define PG8_WAIT_L(n) asm volatile("s_waitcnt lgkmcnt(" #n ")" ::: "memory")
; #define PG8_BAR __builtin_amdgcn_s_barrier()
; #define PG8_SCHED __builtin_amdgcn_sched_barrier(0)
; template <class Epi, class Sched>
; __device__ __forceinline__ void gemm_phase(int wv, LAS unsigned char* lds, const Gemm g, const Sched& S, const Epi& E) {
;     ...
;             PG8_WAIT_V(8); PG8_WAIT_L(0); PG8_BAR; PG8_MMA(1, 0, At, B0); PG8_MMA(1, 1, At, B1); PG8_BAR; PG8_SCHED;
;             PG8_LDB(B0, 1, 0); PG8_LDB(B1, 1, 1); PG8_SCHED; PG8_LDA(At, 1, 0); PG8_STAGE(PG8_SA(0, 1), a2 + hstep, voffA);
;             PG8_WAIT_V(8); PG8_WAIT_L(0); PG8_BAR; PG8_MMA(0, 0, At, B0); PG8_MMA(0, 1, At, B1); PG8_BAR; PG8_SCHED;
	s_setprio 1
	s_waitcnt lgkmcnt(0)
	v_mfma_f32_16x16x32_bf16 v[60:63], v[120:123], v[160:163], v[60:63]
	v_mfma_f32_16x16x32_bf16 v[52:55], v[136:139], v[160:163], v[52:55]
	v_mfma_f32_16x16x32_bf16 v[44:47], v[120:123], v[178:181], v[44:47]
	v_mfma_f32_16x16x32_bf16 v[36:39], v[136:139], v[178:181], v[36:39]
	v_mfma_f32_16x16x32_bf16 v[28:31], v[120:123], v[204:207], v[28:31]
	v_mfma_f32_16x16x32_bf16 v[20:23], v[136:139], v[204:207], v[20:23]
	v_mfma_f32_16x16x32_bf16 v[12:15], v[120:123], v[212:215], v[12:15]
	v_mfma_f32_16x16x32_bf16 v[4:7], v[136:139], v[212:215], v[4:7]
	v_mfma_f32_16x16x32_bf16 v[60:63], v[124:127], v[164:167], v[60:63]
	v_mfma_f32_16x16x32_bf16 v[52:55], v[140:143], v[164:167], v[52:55]
	v_mfma_f32_16x16x32_bf16 v[44:47], v[124:127], v[182:185], v[44:47]
	v_mfma_f32_16x16x32_bf16 v[36:39], v[140:143], v[182:185], v[36:39]
	v_mfma_f32_16x16x32_bf16 v[28:31], v[124:127], v[208:211], v[28:31]
	v_mfma_f32_16x16x32_bf16 v[20:23], v[140:143], v[208:211], v[20:23]
	v_mfma_f32_16x16x32_bf16 v[12:15], v[124:127], v[216:219], v[12:15]
	v_mfma_f32_16x16x32_bf16 v[4:7], v[140:143], v[216:219], v[4:7]
	s_setprio 0
	s_setprio 1
	v_mfma_f32_16x16x32_bf16 v[56:59], v[144:147], v[160:163], v[56:59]
	v_mfma_f32_16x16x32_bf16 v[48:51], v[152:155], v[160:163], v[48:51]
	v_mfma_f32_16x16x32_bf16 v[40:43], v[144:147], v[178:181], v[40:43]
	v_mfma_f32_16x16x32_bf16 v[32:35], v[152:155], v[178:181], v[32:35]
	v_mfma_f32_16x16x32_bf16 v[24:27], v[144:147], v[204:207], v[24:27]
	v_mfma_f32_16x16x32_bf16 v[16:19], v[152:155], v[204:207], v[16:19]
	v_mfma_f32_16x16x32_bf16 v[8:11], v[144:147], v[212:215], v[8:11]
	v_mfma_f32_16x16x32_bf16 v[0:3], v[152:155], v[212:215], v[0:3]
	v_mfma_f32_16x16x32_bf16 v[56:59], v[148:151], v[164:167], v[56:59]
	v_mfma_f32_16x16x32_bf16 v[48:51], v[156:159], v[164:167], v[48:51]
	v_mfma_f32_16x16x32_bf16 v[40:43], v[148:151], v[182:185], v[40:43]
	v_mfma_f32_16x16x32_bf16 v[32:35], v[156:159], v[182:185], v[32:35]
	v_mfma_f32_16x16x32_bf16 v[24:27], v[148:151], v[208:211], v[24:27]
	v_mfma_f32_16x16x32_bf16 v[16:19], v[156:159], v[208:211], v[16:19]
	v_mfma_f32_16x16x32_bf16 v[8:11], v[148:151], v[216:219], v[8:11]
	v_mfma_f32_16x16x32_bf16 v[0:3], v[156:159], v[216:219], v[0:3]
	s_setprio 0
	s_barrier
	s_add_i32 s47, 0, 0x1c000
	v_add_u32_e32 v140, s95, v201
	v_add_u32_e32 v156, s47, v201
	ds_read_b128 v[120:123], v140
	ds_read_b128 v[124:127], v140 offset:1024
	ds_read_b128 v[136:139], v140 offset:2048
	ds_read_b128 v[140:143], v140 offset:3072
	ds_read_b128 v[144:147], v156
	ds_read_b128 v[148:151], v156 offset:1024
	ds_read_b128 v[152:155], v156 offset:2048
	ds_read_b128 v[156:159], v156 offset:3072
	s_add_u32 s24, s24, 0x40000
	s_addc_u32 s25, s25, 0
	s_mov_b32 m0, s35
	v_lshl_add_u64 v[228:229], s[24:25], 0, v[172:173]
	ds_read_b128 v[160:163], v203 offset:32768
	ds_read_b128 v[164:167], v203 offset:33792
	ds_read_b128 v[178:181], v203 offset:34816
	ds_read_b128 v[182:185], v203 offset:35840
	ds_read_b128 v[204:207], v203 offset:36864
	ds_read_b128 v[208:211], v203 offset:37888
	ds_read_b128 v[212:215], v203 offset:38912
	ds_read_b128 v[216:219], v203 offset:39936
	global_load_lds_dwordx4 v[228:229], off
	v_lshl_add_u64 v[228:229], s[24:25], 0, v[170:171]
	s_mov_b32 m0, s36
	s_nop 0
	global_load_lds_dwordx4 v[228:229], off
	s_nop 0
	s_waitcnt vmcnt(8)
	s_waitcnt lgkmcnt(0)
	s_barrier
	s_setprio 1
	s_waitcnt lgkmcnt(0)
	v_mfma_f32_16x16x32_bf16 v[132:135], v[120:123], v[160:163], v[132:135]
	v_mfma_f32_16x16x32_bf16 v[116:119], v[136:139], v[160:163], v[116:119]
	v_mfma_f32_16x16x32_bf16 v[108:111], v[120:123], v[178:181], v[108:111]
	v_mfma_f32_16x16x32_bf16 v[100:103], v[136:139], v[178:181], v[100:103]
	v_mfma_f32_16x16x32_bf16 v[92:95], v[120:123], v[204:207], v[92:95]
	v_mfma_f32_16x16x32_bf16 v[84:87], v[136:139], v[204:207], v[84:87]
	v_mfma_f32_16x16x32_bf16 v[76:79], v[120:123], v[212:215], v[76:79]
	v_mfma_f32_16x16x32_bf16 v[68:71], v[136:139], v[212:215], v[68:71]
	v_mfma_f32_16x16x32_bf16 v[132:135], v[124:127], v[164:167], v[132:135]
	v_mfma_f32_16x16x32_bf16 v[116:119], v[140:143], v[164:167], v[116:119]
	v_mfma_f32_16x16x32_bf16 v[108:111], v[124:127], v[182:185], v[108:111]
	v_mfma_f32_16x16x32_bf16 v[100:103], v[140:143], v[182:185], v[100:103]
	v_mfma_f32_16x16x32_bf16 v[92:95], v[124:127], v[208:211], v[92:95]
	v_mfma_f32_16x16x32_bf16 v[84:87], v[140:143], v[208:211], v[84:87]
	v_mfma_f32_16x16x32_bf16 v[76:79], v[124:127], v[216:219], v[76:79]
	v_mfma_f32_16x16x32_bf16 v[68:71], v[140:143], v[216:219], v[68:71]
	s_setprio 0
	s_setprio 1
	v_mfma_f32_16x16x32_bf16 v[128:131], v[144:147], v[160:163], v[128:131]
	v_mfma_f32_16x16x32_bf16 v[112:115], v[152:155], v[160:163], v[112:115]
	v_mfma_f32_16x16x32_bf16 v[104:107], v[144:147], v[178:181], v[104:107]
	v_mfma_f32_16x16x32_bf16 v[96:99], v[152:155], v[178:181], v[96:99]
	v_mfma_f32_16x16x32_bf16 v[88:91], v[144:147], v[204:207], v[88:91]
	v_mfma_f32_16x16x32_bf16 v[80:83], v[152:155], v[204:207], v[80:83]
	v_mfma_f32_16x16x32_bf16 v[72:75], v[144:147], v[212:215], v[72:75]
	v_mfma_f32_16x16x32_bf16 v[64:67], v[152:155], v[212:215], v[64:67]
	v_mfma_f32_16x16x32_bf16 v[128:131], v[148:151], v[164:167], v[128:131]
	v_mfma_f32_16x16x32_bf16 v[112:115], v[156:159], v[164:167], v[112:115]
	v_mfma_f32_16x16x32_bf16 v[104:107], v[148:151], v[182:185], v[104:107]
	v_mfma_f32_16x16x32_bf16 v[96:99], v[156:159], v[182:185], v[96:99]
	v_mfma_f32_16x16x32_bf16 v[88:91], v[148:151], v[208:211], v[88:91]
	v_mfma_f32_16x16x32_bf16 v[80:83], v[156:159], v[208:211], v[80:83]
	v_mfma_f32_16x16x32_bf16 v[72:75], v[148:151], v[216:219], v[72:75]
	v_mfma_f32_16x16x32_bf16 v[64:67], v[156:159], v[216:219], v[64:67]
	s_setprio 0
	s_barrier
; #define PG8_STAGE(bufoff, gbase, voff) do { _Pragma("unroll") for (int _i = 0; _i < 2; ++_i) \
;         __builtin_amdgcn_global_load_lds((const unsigned*)((const char*)(gbase) + (voff)[_i]), (LAS unsigned*)(lds + (bufoff) + ldsw + _i * 8192), 16, 0, 0); } while (0)
; #define PG8_LDA(dst, b, h) do { _Pragma("unroll") for (int m = 0; m < 4; ++m) _Pragma("unroll") for (int k = 0; k < 2; ++k) dst[m][k] = *(const LAS bf16x8*)(lds + PG8_SA(b, h) + aoff + m * 2048 + k * 1024); } while (0)
; #define PG8_MMA(ai, bj, At, Bt) do { __builtin_amdgcn_s_setprio(1); _Pragma("unroll") for (int m = 0; m < 4; ++m) _Pragma("unroll") for (int n = 0; n < 2; ++n) _Pragma("unroll") for (int k = 0; k < 2; ++k) \
;         acc[ai][bj][m][n] = __builtin_amdgcn_mfma_f32_16x16x32_bf16(Bt[n][k], At[m][k], acc[ai][bj][m][n], 0, 0, 0); __builtin_amdgcn_s_setprio(0); } while (0)
; #define PG8_WAIT_V(n) asm volatile("s_waitcnt vmcnt(" #n ")" ::: "memory")
; #define PG8_WAIT_L(n) asm volatile("s_waitcnt lgkmcnt(" #n ")" ::: "memory")
; #define PG8_BAR __builtin_amdgcn_s_barrier()
; #define PG8_SCHED __builtin_amdgcn_sched_barrier(0)
; template <class Epi, class Sched>
; __device__ __forceinline__ void gemm_phase(int wv, LAS unsigned char* lds, const Gemm g, const Sched& S, const Epi& E) {
;     ...
;             PG8_LDA(At, 1, 1); PG8_STAGE(PG8_SB(1, 0), b3, voffB); PG8_STAGE(PG8_SB(1, 1), b3 + hstepB, voffB); PG8_STAGE(PG8_SA(1, 0), a3, voffA);
;             PG8_WAIT_V(8); PG8_WAIT_L(0); PG8_BAR; PG8_MMA(1, 0, At, B0); PG8_MMA(1, 1, At, B1); PG8_BAR; PG8_SCHED;
;         }
;         if (wr == 0) PG8_BAR;
	s_add_i32 s24, s95, s30
	v_lshl_add_u64 v[186:187], v[186:187], 0, s[74:75]
	s_mov_b32 m0, s24
	ds_read_b128 v[160:163], v203 offset:49152
	ds_read_b128 v[164:167], v203 offset:50176
	ds_read_b128 v[178:181], v203 offset:51200
	ds_read_b128 v[182:185], v203 offset:52224
	ds_read_b128 v[204:207], v203 offset:53248
	ds_read_b128 v[208:211], v203 offset:54272
	ds_read_b128 v[212:215], v203 offset:55296
	ds_read_b128 v[216:219], v203 offset:56320
	global_load_lds_dwordx4 v[186:187], off
	s_add_i32 m0, s24, 0x2000
	s_add_u32 s22, s22, 0x200080
	v_lshl_add_u64 v[186:187], v[198:199], 0, s[74:75]
	s_addc_u32 s23, s23, 0
	s_add_i32 s24, s47, s30
	global_load_lds_dwordx4 v[186:187], off
	v_lshl_add_u64 v[186:187], s[22:23], 0, v[188:189]
	s_mov_b32 m0, s24
	s_nop 0
	global_load_lds_dwordx4 v[186:187], off
	v_lshl_add_u64 v[186:187], s[22:23], 0, v[168:169]
	s_add_i32 m0, s24, 0x2000
	s_nop 0
	global_load_lds_dwordx4 v[186:187], off
	v_lshl_add_u64 v[186:187], v[220:221], 0, s[74:75]
	s_mov_b32 m0, s37
	s_nop 0
	global_load_lds_dwordx4 v[186:187], off
	v_lshl_add_u64 v[186:187], v[222:223], 0, s[74:75]
	s_mov_b32 m0, s38
	s_nop 0
	global_load_lds_dwordx4 v[186:187], off
	s_waitcnt vmcnt(8)
	s_waitcnt lgkmcnt(0)
	s_barrier
	s_setprio 1
	s_waitcnt lgkmcnt(0)
	v_mfma_f32_16x16x32_bf16 v[60:63], v[120:123], v[160:163], v[60:63]
	v_mfma_f32_16x16x32_bf16 v[52:55], v[136:139], v[160:163], v[52:55]
	v_mfma_f32_16x16x32_bf16 v[44:47], v[120:123], v[178:181], v[44:47]
	v_mfma_f32_16x16x32_bf16 v[36:39], v[136:139], v[178:181], v[36:39]
	v_mfma_f32_16x16x32_bf16 v[28:31], v[120:123], v[204:207], v[28:31]
	v_mfma_f32_16x16x32_bf16 v[20:23], v[136:139], v[204:207], v[20:23]
	v_mfma_f32_16x16x32_bf16 v[12:15], v[120:123], v[212:215], v[12:15]
	v_mfma_f32_16x16x32_bf16 v[4:7], v[136:139], v[212:215], v[4:7]
	v_mfma_f32_16x16x32_bf16 v[60:63], v[124:127], v[164:167], v[60:63]
	v_mfma_f32_16x16x32_bf16 v[52:55], v[140:143], v[164:167], v[52:55]
	v_mfma_f32_16x16x32_bf16 v[44:47], v[124:127], v[182:185], v[44:47]
	v_mfma_f32_16x16x32_bf16 v[36:39], v[140:143], v[182:185], v[36:39]
	v_mfma_f32_16x16x32_bf16 v[28:31], v[124:127], v[208:211], v[28:31]
	v_mfma_f32_16x16x32_bf16 v[20:23], v[140:143], v[208:211], v[20:23]
	v_mfma_f32_16x16x32_bf16 v[12:15], v[124:127], v[216:219], v[12:15]
	v_mfma_f32_16x16x32_bf16 v[4:7], v[140:143], v[216:219], v[4:7]
	s_setprio 0
	s_setprio 1
	v_mfma_f32_16x16x32_bf16 v[56:59], v[144:147], v[160:163], v[56:59]
	v_mfma_f32_16x16x32_bf16 v[48:51], v[152:155], v[160:163], v[48:51]
	v_mfma_f32_16x16x32_bf16 v[40:43], v[144:147], v[178:181], v[40:43]
	v_mfma_f32_16x16x32_bf16 v[32:35], v[152:155], v[178:181], v[32:35]
	v_mfma_f32_16x16x32_bf16 v[24:27], v[144:147], v[204:207], v[24:27]
	v_mfma_f32_16x16x32_bf16 v[16:19], v[152:155], v[204:207], v[16:19]
	v_mfma_f32_16x16x32_bf16 v[8:11], v[144:147], v[212:215], v[8:11]
	v_mfma_f32_16x16x32_bf16 v[0:3], v[152:155], v[212:215], v[0:3]
	v_mfma_f32_16x16x32_bf16 v[56:59], v[148:151], v[164:167], v[56:59]
	v_mfma_f32_16x16x32_bf16 v[48:51], v[156:159], v[164:167], v[48:51]
	v_mfma_f32_16x16x32_bf16 v[40:43], v[148:151], v[182:185], v[40:43]
	v_mfma_f32_16x16x32_bf16 v[32:35], v[156:159], v[182:185], v[32:35]
	v_mfma_f32_16x16x32_bf16 v[24:27], v[148:151], v[208:211], v[24:27]
	v_mfma_f32_16x16x32_bf16 v[16:19], v[156:159], v[208:211], v[16:19]
	v_mfma_f32_16x16x32_bf16 v[8:11], v[148:151], v[216:219], v[8:11]
	v_mfma_f32_16x16x32_bf16 v[0:3], v[156:159], v[216:219], v[0:3]
	s_setprio 0
	s_barrier
	s_add_i32 s46, s46, 2
	s_add_u32 s20, s20, 0x100
	s_addc_u32 s21, s21, 0
	s_add_u32 s44, s44, 0x100
	s_addc_u32 s45, s45, 0
	s_cmp_gt_u32 s46, 13
	s_cbranch_scc0 .LBB0_821
	s_and_b64 vcc, exec, s[10:11]
	s_cbranch_vccz .LBB0_824
	s_barrier

; #define PG8_STAGE(bufoff, gbase, voff) do { _Pragma("unroll") for (int _i = 0; _i < 2; ++_i) \
;         __builtin_amdgcn_global_load_lds((const unsigned*)((const char*)(gbase) + (voff)[_i]), (LAS unsigned*)(lds + (bufoff) + ldsw + _i * 8192), 16, 0, 0); } while (0)
; #define PG8_LDA(dst, b, h) do { _Pragma("unroll") for (int m = 0; m < 4; ++m) _Pragma("unroll") for (int k = 0; k < 2; ++k) dst[m][k] = *(const LAS bf16x8*)(lds + PG8_SA(b, h) + aoff + m * 2048 + k * 1024); } while (0)
; #define PG8_LDB(dst, b, h) do { _Pragma("unroll") for (int n = 0; n < 2; ++n) _Pragma("unroll") for (int k = 0; k < 2; ++k) dst[n][k] = *(const LAS bf16x8*)(lds + PG8_SB(b, h) + boff + n * 2048 + k * 1024); } while (0)
; #define PG8_MMA(ai, bj, At, Bt) do { __builtin_amdgcn_s_setprio(1); _Pragma("unroll") for (int m = 0; m < 4; ++m) _Pragma("unroll") for (int n = 0; n < 2; ++n) _Pragma("unroll") for (int k = 0; k < 2; ++k) \
;         acc[ai][bj][m][n] = __builtin_amdgcn_mfma_f32_16x16x32_bf16(Bt[n][k], At[m][k], acc[ai][bj][m][n], 0, 0, 0); __builtin_amdgcn_s_setprio(0); } while (0)
; #define PG8_WAIT_V(n) asm volatile("s_waitcnt vmcnt(" #n ")" ::: "memory")
; #define PG8_WAIT_L(n) asm volatile("s_waitcnt lgkmcnt(" #n ")" ::: "memory")
; #define PG8_BAR __builtin_amdgcn_s_barrier()
; #define PG8_SCHED __builtin_amdgcn_sched_barrier(0)
; template <class Epi, class Sched>
; __device__ __forceinline__ void gemm_phase(int wv, LAS unsigned char* lds, const Gemm g, const Sched& S, const Epi& E) {
;     ...
;         for (int t = 0; t < nt; t += 2) {
;             const bool last = (t == nt - 2);
;             const char* a1 = cA + (size_t)(t + 1) * kstep;
;             const char* a2 = last ? nA : cA + (size_t)(t + 2) * kstep; const char* b2 = last ? nB : cB + (size_t)(t + 2) * kstep;
;             const char* a3 = a2 + kstep; const char* b3 = b2 + kstep;
;             PG8_LDB(B0, 0, 0); PG8_LDB(B1, 0, 1); PG8_SCHED; PG8_LDA(At, 0, 0); PG8_STAGE(PG8_SA(1, 1), a1 + hstep, voffA);
;             PG8_WAIT_V(8); PG8_WAIT_L(0); PG8_BAR; PG8_MMA(0, 0, At, B0); PG8_MMA(0, 1, At, B1); PG8_BAR; PG8_SCHED;
;             PG8_LDA(At, 0, 1); PG8_STAGE(PG8_SB(0, 0), b2, voffB); PG8_STAGE(PG8_SB(0, 1), b2 + hstepB, voffB); PG8_STAGE(PG8_SA(0, 0), a2, voffA);
;             PG8_WAIT_V(8); PG8_WAIT_L(0); PG8_BAR; PG8_MMA(1, 0, At, B0); PG8_MMA(1, 1, At, B1); PG8_BAR; PG8_SCHED;
.LBB0_893:
	s_add_u32 s26, s24, 0xfffc0080
	s_addc_u32 s27, s25, -1
	s_add_i32 s50, 0, 0x10000
	s_cmp_eq_u32 s49, 12
	s_cselect_b32 s29, s17, s27
	s_cselect_b32 s28, s45, s26
	s_cselect_b32 s27, s19, s48
	s_cselect_b32 s26, s46, s47
	s_add_i32 s52, 0, 0x14000
	v_add_u32_e32 v124, s50, v240
	v_add_u32_e32 v156, s52, v240
	ds_read_b128 v[112:115], v124
	ds_read_b128 v[116:119], v124 offset:1024
	ds_read_b128 v[120:123], v124 offset:2048
	ds_read_b128 v[124:127], v124 offset:3072
	ds_read_b128 v[128:131], v156
	ds_read_b128 v[140:143], v156 offset:1024
	ds_read_b128 v[152:155], v156 offset:2048
	ds_read_b128 v[156:159], v156 offset:3072
	v_lshl_add_u64 v[212:213], s[24:25], 0, v[204:205]
	s_add_i32 m0, s37, 0xc000
	ds_read_b128 v[160:163], v244
	ds_read_b128 v[164:167], v244 offset:1024
	ds_read_b128 v[168:171], v244 offset:2048
	ds_read_b128 v[172:175], v244 offset:3072
	ds_read_b128 v[176:179], v244 offset:4096
	ds_read_b128 v[180:183], v244 offset:5120
	ds_read_b128 v[184:187], v244 offset:6144
	ds_read_b128 v[208:211], v244 offset:7168
	global_load_lds_dwordx4 v[212:213], off
	v_lshl_add_u64 v[212:213], s[24:25], 0, v[206:207]
	s_add_i32 m0, s37, 0xe000
	s_nop 0
	global_load_lds_dwordx4 v[212:213], off
	s_waitcnt vmcnt(8)
	s_waitcnt lgkmcnt(0)
	s_barrier
	s_setprio 1
	s_waitcnt lgkmcnt(0)
	v_mfma_f32_16x16x32_bf16 v[148:151], v[112:115], v[160:163], v[148:151]
	v_mfma_f32_16x16x32_bf16 v[144:147], v[120:123], v[160:163], v[144:147]
	v_mfma_f32_16x16x32_bf16 v[108:111], v[112:115], v[168:171], v[108:111]
	v_mfma_f32_16x16x32_bf16 v[104:107], v[120:123], v[168:171], v[104:107]
	v_mfma_f32_16x16x32_bf16 v[92:95], v[112:115], v[176:179], v[92:95]
	v_mfma_f32_16x16x32_bf16 v[88:91], v[120:123], v[176:179], v[88:91]
	v_mfma_f32_16x16x32_bf16 v[76:79], v[112:115], v[184:187], v[76:79]
	v_mfma_f32_16x16x32_bf16 v[72:75], v[120:123], v[184:187], v[72:75]
	v_mfma_f32_16x16x32_bf16 v[148:151], v[116:119], v[164:167], v[148:151]
	v_mfma_f32_16x16x32_bf16 v[144:147], v[124:127], v[164:167], v[144:147]
	v_mfma_f32_16x16x32_bf16 v[108:111], v[116:119], v[172:175], v[108:111]
	v_mfma_f32_16x16x32_bf16 v[104:107], v[124:127], v[172:175], v[104:107]
	v_mfma_f32_16x16x32_bf16 v[92:95], v[116:119], v[180:183], v[92:95]
	v_mfma_f32_16x16x32_bf16 v[88:91], v[124:127], v[180:183], v[88:91]
	v_mfma_f32_16x16x32_bf16 v[76:79], v[116:119], v[208:211], v[76:79]
	v_mfma_f32_16x16x32_bf16 v[72:75], v[124:127], v[208:211], v[72:75]
	s_setprio 0
	s_setprio 1
	v_mfma_f32_16x16x32_bf16 v[136:139], v[128:131], v[160:163], v[136:139]
	v_mfma_f32_16x16x32_bf16 v[132:135], v[152:155], v[160:163], v[132:135]
	v_mfma_f32_16x16x32_bf16 v[100:103], v[128:131], v[168:171], v[100:103]
	v_mfma_f32_16x16x32_bf16 v[96:99], v[152:155], v[168:171], v[96:99]
	v_mfma_f32_16x16x32_bf16 v[84:87], v[128:131], v[176:179], v[84:87]
	v_mfma_f32_16x16x32_bf16 v[80:83], v[152:155], v[176:179], v[80:83]
	v_mfma_f32_16x16x32_bf16 v[68:71], v[128:131], v[184:187], v[68:71]
	v_mfma_f32_16x16x32_bf16 v[64:67], v[152:155], v[184:187], v[64:67]
	v_mfma_f32_16x16x32_bf16 v[136:139], v[140:143], v[164:167], v[136:139]
	v_mfma_f32_16x16x32_bf16 v[132:135], v[156:159], v[164:167], v[132:135]
	v_mfma_f32_16x16x32_bf16 v[100:103], v[140:143], v[172:175], v[100:103]
	v_mfma_f32_16x16x32_bf16 v[96:99], v[156:159], v[172:175], v[96:99]
	v_mfma_f32_16x16x32_bf16 v[84:87], v[140:143], v[180:183], v[84:87]
	v_mfma_f32_16x16x32_bf16 v[80:83], v[156:159], v[180:183], v[80:83]
	v_mfma_f32_16x16x32_bf16 v[68:71], v[140:143], v[208:211], v[68:71]
	v_mfma_f32_16x16x32_bf16 v[64:67], v[156:159], v[208:211], v[64:67]
	s_setprio 0
	s_barrier
	s_add_i32 s50, s50, s36
	v_lshl_add_u64 v[212:213], s[26:27], 0, v[188:189]
	s_mov_b32 m0, s50
	ds_read_b128 v[160:163], v244 offset:16384
	ds_read_b128 v[164:167], v244 offset:17408
	ds_read_b128 v[168:171], v244 offset:18432
	ds_read_b128 v[172:175], v244 offset:19456
	ds_read_b128 v[176:179], v244 offset:20480
	ds_read_b128 v[180:183], v244 offset:21504
	ds_read_b128 v[184:187], v244 offset:22528
	ds_read_b128 v[208:211], v244 offset:23552
	global_load_lds_dwordx4 v[212:213], off
	s_add_i32 m0, s50, 0x2000
	s_add_u32 s50, s26, 0x4000
	v_lshl_add_u64 v[214:215], s[26:27], 0, v[198:199]
	s_addc_u32 s51, s27, 0
	s_add_i32 s52, s52, s36
	global_load_lds_dwordx4 v[214:215], off
	v_lshl_add_u64 v[216:217], s[50:51], 0, v[188:189]
	s_mov_b32 m0, s52
	v_lshl_add_u64 v[218:219], s[28:29], 0, v[200:201]
	global_load_lds_dwordx4 v[216:217], off
	v_lshl_add_u64 v[216:217], s[50:51], 0, v[198:199]
	s_add_i32 m0, s52, 0x2000
	s_nop 0
	global_load_lds_dwordx4 v[216:217], off
	v_lshl_add_u64 v[216:217], s[28:29], 0, v[202:203]
	s_mov_b32 m0, s37
	s_nop 0
	global_load_lds_dwordx4 v[216:217], off
	s_mov_b32 m0, s38
	s_nop 0
	global_load_lds_dwordx4 v[218:219], off
	s_nop 0
	s_waitcnt vmcnt(8)
	s_waitcnt lgkmcnt(0)
	s_barrier
; #define PG8_STAGE(bufoff, gbase, voff) do { _Pragma("unroll") for (int _i = 0; _i < 2; ++_i) \
;         __builtin_amdgcn_global_load_lds((const unsigned*)((const char*)(gbase) + (voff)[_i]), (LAS unsigned*)(lds + (bufoff) + ldsw + _i * 8192), 16, 0, 0); } while (0)
; #define PG8_LDA(dst, b, h) do { _Pragma("unroll") for (int m = 0; m < 4; ++m) _Pragma("unroll") for (int k = 0; k < 2; ++k) dst[m][k] = *(const LAS bf16x8*)(lds + PG8_SA(b, h) + aoff + m * 2048 + k * 1024); } while (0)
; #define PG8_LDB(dst, b, h) do { _Pragma("unroll") for (int n = 0; n < 2; ++n) _Pragma("unroll") for (int k = 0; k < 2; ++k) dst[n][k] = *(const LAS bf16x8*)(lds + PG8_SB(b, h) + boff + n * 2048 + k * 1024); } while (0)
; #define PG8_MMA(ai, bj, At, Bt) do { __builtin_amdgcn_s_setprio(1); _Pragma("unroll") for (int m = 0; m < 4; ++m) _Pragma("unroll") for (int n = 0; n < 2; ++n) _Pragma("unroll") for (int k = 0; k < 2; ++k) \
;         acc[ai][bj][m][n] = __builtin_amdgcn_mfma_f32_16x16x32_bf16(Bt[n][k], At[m][k], acc[ai][bj][m][n], 0, 0, 0); __builtin_amdgcn_s_setprio(0); } while (0)
; #define PG8_WAIT_V(n) asm volatile("s_waitcnt vmcnt(" #n ")" ::: "memory")
; #define PG8_WAIT_L(n) asm volatile("s_waitcnt lgkmcnt(" #n ")" ::: "memory")
; #define PG8_BAR __builtin_amdgcn_s_barrier()
; #define PG8_SCHED __builtin_amdgcn_sched_barrier(0)
; template <class Epi, class Sched>
; __device__ __forceinline__ void gemm_phase(int wv, LAS unsigned char* lds, const Gemm g, const Sched& S, const Epi& E) {
;     ...
;             PG8_WAIT_V(8); PG8_WAIT_L(0); PG8_BAR; PG8_MMA(1, 0, At, B0); PG8_MMA(1, 1, At, B1); PG8_BAR; PG8_SCHED;
;             PG8_LDB(B0, 1, 0); PG8_LDB(B1, 1, 1); PG8_SCHED; PG8_LDA(At, 1, 0); PG8_STAGE(PG8_SA(0, 1), a2 + hstep, voffA);
;             PG8_WAIT_V(8); PG8_WAIT_L(0); PG8_BAR; PG8_MMA(0, 0, At, B0); PG8_MMA(0, 1, At, B1); PG8_BAR; PG8_SCHED;
	s_setprio 1
	s_waitcnt lgkmcnt(0)
	v_mfma_f32_16x16x32_bf16 v[60:63], v[112:115], v[160:163], v[60:63]
	v_mfma_f32_16x16x32_bf16 v[56:59], v[120:123], v[160:163], v[56:59]
	v_mfma_f32_16x16x32_bf16 v[44:47], v[112:115], v[168:171], v[44:47]
	v_mfma_f32_16x16x32_bf16 v[40:43], v[120:123], v[168:171], v[40:43]
	v_mfma_f32_16x16x32_bf16 v[28:31], v[112:115], v[176:179], v[28:31]
	v_mfma_f32_16x16x32_bf16 v[24:27], v[120:123], v[176:179], v[24:27]
	v_mfma_f32_16x16x32_bf16 v[12:15], v[112:115], v[184:187], v[12:15]
	v_mfma_f32_16x16x32_bf16 v[8:11], v[120:123], v[184:187], v[8:11]
	v_mfma_f32_16x16x32_bf16 v[60:63], v[116:119], v[164:167], v[60:63]
	v_mfma_f32_16x16x32_bf16 v[56:59], v[124:127], v[164:167], v[56:59]
	v_mfma_f32_16x16x32_bf16 v[44:47], v[116:119], v[172:175], v[44:47]
	v_mfma_f32_16x16x32_bf16 v[40:43], v[124:127], v[172:175], v[40:43]
	v_mfma_f32_16x16x32_bf16 v[28:31], v[116:119], v[180:183], v[28:31]
	v_mfma_f32_16x16x32_bf16 v[24:27], v[124:127], v[180:183], v[24:27]
	v_mfma_f32_16x16x32_bf16 v[12:15], v[116:119], v[208:211], v[12:15]
	v_mfma_f32_16x16x32_bf16 v[8:11], v[124:127], v[208:211], v[8:11]
	s_setprio 0
	s_setprio 1
	v_mfma_f32_16x16x32_bf16 v[52:55], v[128:131], v[160:163], v[52:55]
	v_mfma_f32_16x16x32_bf16 v[48:51], v[152:155], v[160:163], v[48:51]
	v_mfma_f32_16x16x32_bf16 v[36:39], v[128:131], v[168:171], v[36:39]
	v_mfma_f32_16x16x32_bf16 v[32:35], v[152:155], v[168:171], v[32:35]
	v_mfma_f32_16x16x32_bf16 v[20:23], v[128:131], v[176:179], v[20:23]
	v_mfma_f32_16x16x32_bf16 v[16:19], v[152:155], v[176:179], v[16:19]
	v_mfma_f32_16x16x32_bf16 v[4:7], v[128:131], v[184:187], v[4:7]
	v_mfma_f32_16x16x32_bf16 v[0:3], v[152:155], v[184:187], v[0:3]
	v_mfma_f32_16x16x32_bf16 v[52:55], v[140:143], v[164:167], v[52:55]
	v_mfma_f32_16x16x32_bf16 v[48:51], v[156:159], v[164:167], v[48:51]
	v_mfma_f32_16x16x32_bf16 v[36:39], v[140:143], v[172:175], v[36:39]
	v_mfma_f32_16x16x32_bf16 v[32:35], v[156:159], v[172:175], v[32:35]
	v_mfma_f32_16x16x32_bf16 v[20:23], v[140:143], v[180:183], v[20:23]
	v_mfma_f32_16x16x32_bf16 v[16:19], v[156:159], v[180:183], v[16:19]
	v_mfma_f32_16x16x32_bf16 v[4:7], v[140:143], v[208:211], v[4:7]
	v_mfma_f32_16x16x32_bf16 v[0:3], v[156:159], v[208:211], v[0:3]
	s_setprio 0
	s_barrier
	s_add_i32 s50, 0, 0x1c000
	v_add_u32_e32 v124, s95, v240
	v_add_u32_e32 v156, s50, v240
	ds_read_b128 v[112:115], v124
	ds_read_b128 v[116:119], v124 offset:1024
	ds_read_b128 v[120:123], v124 offset:2048
	ds_read_b128 v[124:127], v124 offset:3072
	ds_read_b128 v[128:131], v156
	ds_read_b128 v[140:143], v156 offset:1024
	ds_read_b128 v[152:155], v156 offset:2048
	ds_read_b128 v[156:159], v156 offset:3072
	s_add_u32 s28, s28, 0x40000
	s_addc_u32 s29, s29, 0
	s_mov_b32 m0, s39
	v_lshl_add_u64 v[220:221], s[28:29], 0, v[202:203]
	ds_read_b128 v[160:163], v244 offset:32768
	ds_read_b128 v[164:167], v244 offset:33792
	ds_read_b128 v[168:171], v244 offset:34816
	ds_read_b128 v[172:175], v244 offset:35840
	ds_read_b128 v[176:179], v244 offset:36864
	ds_read_b128 v[180:183], v244 offset:37888
	ds_read_b128 v[184:187], v244 offset:38912
	ds_read_b128 v[208:211], v244 offset:39936
	global_load_lds_dwordx4 v[220:221], off
	v_lshl_add_u64 v[220:221], s[28:29], 0, v[200:201]
	s_mov_b32 m0, s40
	s_nop 0
	global_load_lds_dwordx4 v[220:221], off
	s_nop 0
	s_waitcnt vmcnt(8)
	s_waitcnt lgkmcnt(0)
	s_barrier
	s_setprio 1
	s_waitcnt lgkmcnt(0)
	v_mfma_f32_16x16x32_bf16 v[148:151], v[112:115], v[160:163], v[148:151]
	v_mfma_f32_16x16x32_bf16 v[144:147], v[120:123], v[160:163], v[144:147]
	v_mfma_f32_16x16x32_bf16 v[108:111], v[112:115], v[168:171], v[108:111]
	v_mfma_f32_16x16x32_bf16 v[104:107], v[120:123], v[168:171], v[104:107]
	v_mfma_f32_16x16x32_bf16 v[92:95], v[112:115], v[176:179], v[92:95]
	v_mfma_f32_16x16x32_bf16 v[88:91], v[120:123], v[176:179], v[88:91]
	v_mfma_f32_16x16x32_bf16 v[76:79], v[112:115], v[184:187], v[76:79]
	v_mfma_f32_16x16x32_bf16 v[72:75], v[120:123], v[184:187], v[72:75]
	v_mfma_f32_16x16x32_bf16 v[148:151], v[116:119], v[164:167], v[148:151]
	v_mfma_f32_16x16x32_bf16 v[144:147], v[124:127], v[164:167], v[144:147]
	v_mfma_f32_16x16x32_bf16 v[108:111], v[116:119], v[172:175], v[108:111]
	v_mfma_f32_16x16x32_bf16 v[104:107], v[124:127], v[172:175], v[104:107]
	v_mfma_f32_16x16x32_bf16 v[92:95], v[116:119], v[180:183], v[92:95]
	v_mfma_f32_16x16x32_bf16 v[88:91], v[124:127], v[180:183], v[88:91]
	v_mfma_f32_16x16x32_bf16 v[76:79], v[116:119], v[208:211], v[76:79]
	v_mfma_f32_16x16x32_bf16 v[72:75], v[124:127], v[208:211], v[72:75]
	s_setprio 0
	s_setprio 1
	v_mfma_f32_16x16x32_bf16 v[136:139], v[128:131], v[160:163], v[136:139]
	v_mfma_f32_16x16x32_bf16 v[132:135], v[152:155], v[160:163], v[132:135]
	v_mfma_f32_16x16x32_bf16 v[100:103], v[128:131], v[168:171], v[100:103]
	v_mfma_f32_16x16x32_bf16 v[96:99], v[152:155], v[168:171], v[96:99]
	v_mfma_f32_16x16x32_bf16 v[84:87], v[128:131], v[176:179], v[84:87]
	v_mfma_f32_16x16x32_bf16 v[80:83], v[152:155], v[176:179], v[80:83]
	v_mfma_f32_16x16x32_bf16 v[68:71], v[128:131], v[184:187], v[68:71]
	v_mfma_f32_16x16x32_bf16 v[64:67], v[152:155], v[184:187], v[64:67]
	v_mfma_f32_16x16x32_bf16 v[136:139], v[140:143], v[164:167], v[136:139]
	v_mfma_f32_16x16x32_bf16 v[132:135], v[156:159], v[164:167], v[132:135]
	v_mfma_f32_16x16x32_bf16 v[100:103], v[140:143], v[172:175], v[100:103]
	v_mfma_f32_16x16x32_bf16 v[96:99], v[156:159], v[172:175], v[96:99]
	v_mfma_f32_16x16x32_bf16 v[84:87], v[140:143], v[180:183], v[84:87]
	v_mfma_f32_16x16x32_bf16 v[80:83], v[156:159], v[180:183], v[80:83]
	v_mfma_f32_16x16x32_bf16 v[68:71], v[140:143], v[208:211], v[68:71]
	v_mfma_f32_16x16x32_bf16 v[64:67], v[156:159], v[208:211], v[64:67]
	s_setprio 0
	s_barrier
; #define PG8_STAGE(bufoff, gbase, voff) do { _Pragma("unroll") for (int _i = 0; _i < 2; ++_i) \
;         __builtin_amdgcn_global_load_lds((const unsigned*)((const char*)(gbase) + (voff)[_i]), (LAS unsigned*)(lds + (bufoff) + ldsw + _i * 8192), 16, 0, 0); } while (0)
; #define PG8_LDA(dst, b, h) do { _Pragma("unroll") for (int m = 0; m < 4; ++m) _Pragma("unroll") for (int k = 0; k < 2; ++k) dst[m][k] = *(const LAS bf16x8*)(lds + PG8_SA(b, h) + aoff + m * 2048 + k * 1024); } while (0)
; #define PG8_MMA(ai, bj, At, Bt) do { __builtin_amdgcn_s_setprio(1); _Pragma("unroll") for (int m = 0; m < 4; ++m) _Pragma("unroll") for (int n = 0; n < 2; ++n) _Pragma("unroll") for (int k = 0; k < 2; ++k) \
;         acc[ai][bj][m][n] = __builtin_amdgcn_mfma_f32_16x16x32_bf16(Bt[n][k], At[m][k], acc[ai][bj][m][n], 0, 0, 0); __builtin_amdgcn_s_setprio(0); } while (0)
; #define PG8_WAIT_V(n) asm volatile("s_waitcnt vmcnt(" #n ")" ::: "memory")
; #define PG8_WAIT_L(n) asm volatile("s_waitcnt lgkmcnt(" #n ")" ::: "memory")
; #define PG8_BAR __builtin_amdgcn_s_barrier()
; #define PG8_SCHED __builtin_amdgcn_sched_barrier(0)
; template <class Epi, class Sched>
; __device__ __forceinline__ void gemm_phase(int wv, LAS unsigned char* lds, const Gemm g, const Sched& S, const Epi& E) {
;     ...
;             PG8_LDA(At, 1, 1); PG8_STAGE(PG8_SB(1, 0), b3, voffB); PG8_STAGE(PG8_SB(1, 1), b3 + hstepB, voffB); PG8_STAGE(PG8_SA(1, 0), a3, voffA);
;             PG8_WAIT_V(8); PG8_WAIT_L(0); PG8_BAR; PG8_MMA(1, 0, At, B0); PG8_MMA(1, 1, At, B1); PG8_BAR; PG8_SCHED;
;         }
;         if (wr == 0) PG8_BAR;
	s_add_i32 s28, s95, s36
	v_lshl_add_u64 v[212:213], v[212:213], 0, s[74:75]
	s_mov_b32 m0, s28
	ds_read_b128 v[160:163], v244 offset:49152
	ds_read_b128 v[164:167], v244 offset:50176
	ds_read_b128 v[168:171], v244 offset:51200
	ds_read_b128 v[172:175], v244 offset:52224
	ds_read_b128 v[176:179], v244 offset:53248
	ds_read_b128 v[180:183], v244 offset:54272
	ds_read_b128 v[184:187], v244 offset:55296
	ds_read_b128 v[208:211], v244 offset:56320
	global_load_lds_dwordx4 v[212:213], off
	s_add_i32 m0, s28, 0x2000
	s_add_u32 s26, s26, 0x4080
	v_lshl_add_u64 v[212:213], v[214:215], 0, s[74:75]
	s_addc_u32 s27, s27, 0
	s_add_i32 s28, s50, s36
	global_load_lds_dwordx4 v[212:213], off
	v_lshl_add_u64 v[212:213], s[26:27], 0, v[188:189]
	s_mov_b32 m0, s28
	s_nop 0
	global_load_lds_dwordx4 v[212:213], off
	v_lshl_add_u64 v[212:213], s[26:27], 0, v[198:199]
	s_add_i32 m0, s28, 0x2000
	s_nop 0
	global_load_lds_dwordx4 v[212:213], off
	v_lshl_add_u64 v[212:213], v[216:217], 0, s[74:75]
	s_mov_b32 m0, s41
	s_nop 0
	global_load_lds_dwordx4 v[212:213], off
	v_lshl_add_u64 v[212:213], v[218:219], 0, s[74:75]
	s_mov_b32 m0, s42
	s_nop 0
	global_load_lds_dwordx4 v[212:213], off
	s_waitcnt vmcnt(8)
	s_waitcnt lgkmcnt(0)
	s_barrier
	s_setprio 1
	s_waitcnt lgkmcnt(0)
	v_mfma_f32_16x16x32_bf16 v[60:63], v[112:115], v[160:163], v[60:63]
	v_mfma_f32_16x16x32_bf16 v[56:59], v[120:123], v[160:163], v[56:59]
	v_mfma_f32_16x16x32_bf16 v[44:47], v[112:115], v[168:171], v[44:47]
	v_mfma_f32_16x16x32_bf16 v[40:43], v[120:123], v[168:171], v[40:43]
	v_mfma_f32_16x16x32_bf16 v[28:31], v[112:115], v[176:179], v[28:31]
	v_mfma_f32_16x16x32_bf16 v[24:27], v[120:123], v[176:179], v[24:27]
	v_mfma_f32_16x16x32_bf16 v[12:15], v[112:115], v[184:187], v[12:15]
	v_mfma_f32_16x16x32_bf16 v[8:11], v[120:123], v[184:187], v[8:11]
	v_mfma_f32_16x16x32_bf16 v[60:63], v[116:119], v[164:167], v[60:63]
	v_mfma_f32_16x16x32_bf16 v[56:59], v[124:127], v[164:167], v[56:59]
	v_mfma_f32_16x16x32_bf16 v[44:47], v[116:119], v[172:175], v[44:47]
	v_mfma_f32_16x16x32_bf16 v[40:43], v[124:127], v[172:175], v[40:43]
	v_mfma_f32_16x16x32_bf16 v[28:31], v[116:119], v[180:183], v[28:31]
	v_mfma_f32_16x16x32_bf16 v[24:27], v[124:127], v[180:183], v[24:27]
	v_mfma_f32_16x16x32_bf16 v[12:15], v[116:119], v[208:211], v[12:15]
	v_mfma_f32_16x16x32_bf16 v[8:11], v[124:127], v[208:211], v[8:11]
	s_setprio 0
	s_setprio 1
	v_mfma_f32_16x16x32_bf16 v[52:55], v[128:131], v[160:163], v[52:55]
	v_mfma_f32_16x16x32_bf16 v[48:51], v[152:155], v[160:163], v[48:51]
	v_mfma_f32_16x16x32_bf16 v[36:39], v[128:131], v[168:171], v[36:39]
	v_mfma_f32_16x16x32_bf16 v[32:35], v[152:155], v[168:171], v[32:35]
	v_mfma_f32_16x16x32_bf16 v[20:23], v[128:131], v[176:179], v[20:23]
	v_mfma_f32_16x16x32_bf16 v[16:19], v[152:155], v[176:179], v[16:19]
	v_mfma_f32_16x16x32_bf16 v[4:7], v[128:131], v[184:187], v[4:7]
	v_mfma_f32_16x16x32_bf16 v[0:3], v[152:155], v[184:187], v[0:3]
	v_mfma_f32_16x16x32_bf16 v[52:55], v[140:143], v[164:167], v[52:55]
	v_mfma_f32_16x16x32_bf16 v[48:51], v[156:159], v[164:167], v[48:51]
	v_mfma_f32_16x16x32_bf16 v[36:39], v[140:143], v[172:175], v[36:39]
	v_mfma_f32_16x16x32_bf16 v[32:35], v[156:159], v[172:175], v[32:35]
	v_mfma_f32_16x16x32_bf16 v[20:23], v[140:143], v[180:183], v[20:23]
	v_mfma_f32_16x16x32_bf16 v[16:19], v[156:159], v[180:183], v[16:19]
	v_mfma_f32_16x16x32_bf16 v[4:7], v[140:143], v[208:211], v[4:7]
	v_mfma_f32_16x16x32_bf16 v[0:3], v[156:159], v[208:211], v[0:3]
	s_setprio 0
	s_barrier
	s_add_i32 s49, s49, 2
	s_add_u32 s24, s24, 0x100
	s_addc_u32 s25, s25, 0
	s_add_u32 s47, s47, 0x100
	s_addc_u32 s48, s48, 0
	s_cmp_gt_u32 s49, 13
	s_cbranch_scc0 .LBB0_893
	s_and_b64 vcc, exec, s[14:15]
	s_cbranch_vccz .LBB0_896
	s_barrier

; #define PG8_STAGE(bufoff, gbase, voff) do { _Pragma("unroll") for (int _i = 0; _i < 2; ++_i) \
;         __builtin_amdgcn_global_load_lds((const unsigned*)((const char*)(gbase) + (voff)[_i]), (LAS unsigned*)(lds + (bufoff) + ldsw + _i * 8192), 16, 0, 0); } while (0)
; #define PG8_LDA(dst, b, h) do { _Pragma("unroll") for (int m = 0; m < 4; ++m) _Pragma("unroll") for (int k = 0; k < 2; ++k) dst[m][k] = *(const LAS bf16x8*)(lds + PG8_SA(b, h) + aoff + m * 2048 + k * 1024); } while (0)
; #define PG8_LDB(dst, b, h) do { _Pragma("unroll") for (int n = 0; n < 2; ++n) _Pragma("unroll") for (int k = 0; k < 2; ++k) dst[n][k] = *(const LAS bf16x8*)(lds + PG8_SB(b, h) + boff + n * 2048 + k * 1024); } while (0)
; #define PG8_MMA(ai, bj, At, Bt) do { __builtin_amdgcn_s_setprio(1); _Pragma("unroll") for (int m = 0; m < 4; ++m) _Pragma("unroll") for (int n = 0; n < 2; ++n) _Pragma("unroll") for (int k = 0; k < 2; ++k) \
;         acc[ai][bj][m][n] = __builtin_amdgcn_mfma_f32_16x16x32_bf16(Bt[n][k], At[m][k], acc[ai][bj][m][n], 0, 0, 0); __builtin_amdgcn_s_setprio(0); } while (0)
; #define PG8_WAIT_V(n) asm volatile("s_waitcnt vmcnt(" #n ")" ::: "memory")
; #define PG8_WAIT_L(n) asm volatile("s_waitcnt lgkmcnt(" #n ")" ::: "memory")
; #define PG8_BAR __builtin_amdgcn_s_barrier()
; #define PG8_SCHED __builtin_amdgcn_sched_barrier(0)
; template <class Epi, class Sched>
; __device__ __forceinline__ void gemm_phase(int wv, LAS unsigned char* lds, const Gemm g, const Sched& S, const Epi& E) {
;     ...
;         for (int t = 0; t < nt; t += 2) {
;             const bool last = (t == nt - 2);
;             const char* a1 = cA + (size_t)(t + 1) * kstep;
;             const char* a2 = last ? nA : cA + (size_t)(t + 2) * kstep; const char* b2 = last ? nB : cB + (size_t)(t + 2) * kstep;
;             const char* a3 = a2 + kstep; const char* b3 = b2 + kstep;
;             PG8_LDB(B0, 0, 0); PG8_LDB(B1, 0, 1); PG8_SCHED; PG8_LDA(At, 0, 0); PG8_STAGE(PG8_SA(1, 1), a1 + hstep, voffA);
;             PG8_WAIT_V(8); PG8_WAIT_L(0); PG8_BAR; PG8_MMA(0, 0, At, B0); PG8_MMA(0, 1, At, B1); PG8_BAR; PG8_SCHED;
;             PG8_LDA(At, 0, 1); PG8_STAGE(PG8_SB(0, 0), b2, voffB); PG8_STAGE(PG8_SB(0, 1), b2 + hstepB, voffB); PG8_STAGE(PG8_SA(0, 0), a2, voffA);
;             PG8_WAIT_V(8); PG8_WAIT_L(0); PG8_BAR; PG8_MMA(1, 0, At, B0); PG8_MMA(1, 1, At, B1); PG8_BAR; PG8_SCHED;
.LBB0_978:
	s_add_u32 s20, s18, 0xfffc0080
	s_addc_u32 s21, s19, -1
	s_add_i32 s44, 0, 0x10000
	s_cmp_eq_u32 s43, 12
	s_cselect_b32 s23, s11, s21
	s_cselect_b32 s22, s39, s20
	s_cselect_b32 s21, s13, s42
	s_cselect_b32 s20, s40, s41
	s_add_i32 s46, 0, 0x14000
	v_add_u32_e32 v154, s44, v143
	v_add_u32_e32 v170, s46, v143
	ds_read_b128 v[138:141], v154
	ds_read_b128 v[146:149], v154 offset:1024
	ds_read_b128 v[150:153], v154 offset:2048
	ds_read_b128 v[154:157], v154 offset:3072
	ds_read_b128 v[158:161], v170
	ds_read_b128 v[162:165], v170 offset:1024
	ds_read_b128 v[166:169], v170 offset:2048
	ds_read_b128 v[170:173], v170 offset:3072
	v_lshl_add_u64 v[186:187], s[18:19], 0, v[134:135]
	s_add_i32 m0, s29, 0xc000
	ds_read_b128 v[174:177], v145
	ds_read_b128 v[178:181], v145 offset:1024
	ds_read_b128 v[182:185], v145 offset:2048
	ds_read_b128 v[198:201], v145 offset:3072
	ds_read_b128 v[202:205], v145 offset:4096
	ds_read_b128 v[206:209], v145 offset:5120
	ds_read_b128 v[210:213], v145 offset:6144
	ds_read_b128 v[214:217], v145 offset:7168
	global_load_lds_dwordx4 v[186:187], off
	v_lshl_add_u64 v[186:187], s[18:19], 0, v[136:137]
	s_add_i32 m0, s29, 0xe000
	s_nop 0
	global_load_lds_dwordx4 v[186:187], off
	s_nop 0
	s_waitcnt vmcnt(8)
	s_waitcnt lgkmcnt(0)
	s_barrier
	s_setprio 1
	s_waitcnt lgkmcnt(0)
	v_mfma_f32_16x16x32_bf16 v[124:127], v[138:141], v[174:177], v[124:127]
	v_mfma_f32_16x16x32_bf16 v[120:123], v[150:153], v[174:177], v[120:123]
	v_mfma_f32_16x16x32_bf16 v[108:111], v[138:141], v[182:185], v[108:111]
	v_mfma_f32_16x16x32_bf16 v[100:103], v[150:153], v[182:185], v[100:103]
	v_mfma_f32_16x16x32_bf16 v[92:95], v[138:141], v[202:205], v[92:95]
	v_mfma_f32_16x16x32_bf16 v[84:87], v[150:153], v[202:205], v[84:87]
	v_mfma_f32_16x16x32_bf16 v[76:79], v[138:141], v[210:213], v[76:79]
	v_mfma_f32_16x16x32_bf16 v[68:71], v[150:153], v[210:213], v[68:71]
	v_mfma_f32_16x16x32_bf16 v[124:127], v[146:149], v[178:181], v[124:127]
	v_mfma_f32_16x16x32_bf16 v[120:123], v[154:157], v[178:181], v[120:123]
	v_mfma_f32_16x16x32_bf16 v[108:111], v[146:149], v[198:201], v[108:111]
	v_mfma_f32_16x16x32_bf16 v[100:103], v[154:157], v[198:201], v[100:103]
	v_mfma_f32_16x16x32_bf16 v[92:95], v[146:149], v[206:209], v[92:95]
	v_mfma_f32_16x16x32_bf16 v[84:87], v[154:157], v[206:209], v[84:87]
	v_mfma_f32_16x16x32_bf16 v[76:79], v[146:149], v[214:217], v[76:79]
	v_mfma_f32_16x16x32_bf16 v[68:71], v[154:157], v[214:217], v[68:71]
	s_setprio 0
	s_setprio 1
	v_mfma_f32_16x16x32_bf16 v[116:119], v[158:161], v[174:177], v[116:119]
	v_mfma_f32_16x16x32_bf16 v[112:115], v[166:169], v[174:177], v[112:115]
	v_mfma_f32_16x16x32_bf16 v[104:107], v[158:161], v[182:185], v[104:107]
	v_mfma_f32_16x16x32_bf16 v[96:99], v[166:169], v[182:185], v[96:99]
	v_mfma_f32_16x16x32_bf16 v[88:91], v[158:161], v[202:205], v[88:91]
	v_mfma_f32_16x16x32_bf16 v[80:83], v[166:169], v[202:205], v[80:83]
	v_mfma_f32_16x16x32_bf16 v[72:75], v[158:161], v[210:213], v[72:75]
	v_mfma_f32_16x16x32_bf16 v[64:67], v[166:169], v[210:213], v[64:67]
	v_mfma_f32_16x16x32_bf16 v[116:119], v[162:165], v[178:181], v[116:119]
	v_mfma_f32_16x16x32_bf16 v[112:115], v[170:173], v[178:181], v[112:115]
	v_mfma_f32_16x16x32_bf16 v[104:107], v[162:165], v[198:201], v[104:107]
	v_mfma_f32_16x16x32_bf16 v[96:99], v[170:173], v[198:201], v[96:99]
	v_mfma_f32_16x16x32_bf16 v[88:91], v[162:165], v[206:209], v[88:91]
	v_mfma_f32_16x16x32_bf16 v[80:83], v[170:173], v[206:209], v[80:83]
	v_mfma_f32_16x16x32_bf16 v[72:75], v[162:165], v[214:217], v[72:75]
	v_mfma_f32_16x16x32_bf16 v[64:67], v[170:173], v[214:217], v[64:67]
	s_setprio 0
	s_barrier
	s_add_i32 s44, s44, s28
	v_lshl_add_u64 v[186:187], s[20:21], 0, v[188:189]
	s_mov_b32 m0, s44
	ds_read_b128 v[174:177], v145 offset:16384
	ds_read_b128 v[178:181], v145 offset:17408
	ds_read_b128 v[182:185], v145 offset:18432
	ds_read_b128 v[198:201], v145 offset:19456
	ds_read_b128 v[202:205], v145 offset:20480
	ds_read_b128 v[206:209], v145 offset:21504
	ds_read_b128 v[210:213], v145 offset:22528
	ds_read_b128 v[214:217], v145 offset:23552
	global_load_lds_dwordx4 v[186:187], off
	s_add_i32 m0, s44, 0x2000
	s_add_u32 s44, s20, 0x40000
	v_lshl_add_u64 v[218:219], s[20:21], 0, v[128:129]
	s_addc_u32 s45, s21, 0
	s_add_i32 s46, s46, s28
	global_load_lds_dwordx4 v[218:219], off
	v_lshl_add_u64 v[220:221], s[44:45], 0, v[188:189]
	s_mov_b32 m0, s46
	v_lshl_add_u64 v[222:223], s[22:23], 0, v[130:131]
	global_load_lds_dwordx4 v[220:221], off
	v_lshl_add_u64 v[220:221], s[44:45], 0, v[128:129]
	s_add_i32 m0, s46, 0x2000
	s_nop 0
	global_load_lds_dwordx4 v[220:221], off
	v_lshl_add_u64 v[220:221], s[22:23], 0, v[132:133]
	s_mov_b32 m0, s29
	s_nop 0
	global_load_lds_dwordx4 v[220:221], off
	s_mov_b32 m0, s30
	s_nop 0
	global_load_lds_dwordx4 v[222:223], off
	s_nop 0
	s_waitcnt vmcnt(8)
	s_waitcnt lgkmcnt(0)
	s_barrier
; #define PG8_STAGE(bufoff, gbase, voff) do { _Pragma("unroll") for (int _i = 0; _i < 2; ++_i) \
;         __builtin_amdgcn_global_load_lds((const unsigned*)((const char*)(gbase) + (voff)[_i]), (LAS unsigned*)(lds + (bufoff) + ldsw + _i * 8192), 16, 0, 0); } while (0)
; #define PG8_LDA(dst, b, h) do { _Pragma("unroll") for (int m = 0; m < 4; ++m) _Pragma("unroll") for (int k = 0; k < 2; ++k) dst[m][k] = *(const LAS bf16x8*)(lds + PG8_SA(b, h) + aoff + m * 2048 + k * 1024); } while (0)
; #define PG8_LDB(dst, b, h) do { _Pragma("unroll") for (int n = 0; n < 2; ++n) _Pragma("unroll") for (int k = 0; k < 2; ++k) dst[n][k] = *(const LAS bf16x8*)(lds + PG8_SB(b, h) + boff + n * 2048 + k * 1024); } while (0)
; #define PG8_MMA(ai, bj, At, Bt) do { __builtin_amdgcn_s_setprio(1); _Pragma("unroll") for (int m = 0; m < 4; ++m) _Pragma("unroll") for (int n = 0; n < 2; ++n) _Pragma("unroll") for (int k = 0; k < 2; ++k) \
;         acc[ai][bj][m][n] = __builtin_amdgcn_mfma_f32_16x16x32_bf16(Bt[n][k], At[m][k], acc[ai][bj][m][n], 0, 0, 0); __builtin_amdgcn_s_setprio(0); } while (0)
; #define PG8_WAIT_V(n) asm volatile("s_waitcnt vmcnt(" #n ")" ::: "memory")
; #define PG8_WAIT_L(n) asm volatile("s_waitcnt lgkmcnt(" #n ")" ::: "memory")
; #define PG8_BAR __builtin_amdgcn_s_barrier()
; #define PG8_SCHED __builtin_amdgcn_sched_barrier(0)
; template <class Epi, class Sched>
; __device__ __forceinline__ void gemm_phase(int wv, LAS unsigned char* lds, const Gemm g, const Sched& S, const Epi& E) {
;     ...
;             PG8_WAIT_V(8); PG8_WAIT_L(0); PG8_BAR; PG8_MMA(1, 0, At, B0); PG8_MMA(1, 1, At, B1); PG8_BAR; PG8_SCHED;
;             PG8_LDB(B0, 1, 0); PG8_LDB(B1, 1, 1); PG8_SCHED; PG8_LDA(At, 1, 0); PG8_STAGE(PG8_SA(0, 1), a2 + hstep, voffA);
;             PG8_WAIT_V(8); PG8_WAIT_L(0); PG8_BAR; PG8_MMA(0, 0, At, B0); PG8_MMA(0, 1, At, B1); PG8_BAR; PG8_SCHED;
	s_setprio 1
	s_waitcnt lgkmcnt(0)
	v_mfma_f32_16x16x32_bf16 v[60:63], v[138:141], v[174:177], v[60:63]
	v_mfma_f32_16x16x32_bf16 v[52:55], v[150:153], v[174:177], v[52:55]
	v_mfma_f32_16x16x32_bf16 v[44:47], v[138:141], v[182:185], v[44:47]
	v_mfma_f32_16x16x32_bf16 v[36:39], v[150:153], v[182:185], v[36:39]
	v_mfma_f32_16x16x32_bf16 v[28:31], v[138:141], v[202:205], v[28:31]
	v_mfma_f32_16x16x32_bf16 v[20:23], v[150:153], v[202:205], v[20:23]
	v_mfma_f32_16x16x32_bf16 v[12:15], v[138:141], v[210:213], v[12:15]
	v_mfma_f32_16x16x32_bf16 v[4:7], v[150:153], v[210:213], v[4:7]
	v_mfma_f32_16x16x32_bf16 v[60:63], v[146:149], v[178:181], v[60:63]
	v_mfma_f32_16x16x32_bf16 v[52:55], v[154:157], v[178:181], v[52:55]
	v_mfma_f32_16x16x32_bf16 v[44:47], v[146:149], v[198:201], v[44:47]
	v_mfma_f32_16x16x32_bf16 v[36:39], v[154:157], v[198:201], v[36:39]
	v_mfma_f32_16x16x32_bf16 v[28:31], v[146:149], v[206:209], v[28:31]
	v_mfma_f32_16x16x32_bf16 v[20:23], v[154:157], v[206:209], v[20:23]
	v_mfma_f32_16x16x32_bf16 v[12:15], v[146:149], v[214:217], v[12:15]
	v_mfma_f32_16x16x32_bf16 v[4:7], v[154:157], v[214:217], v[4:7]
	s_setprio 0
	s_setprio 1
	v_mfma_f32_16x16x32_bf16 v[56:59], v[158:161], v[174:177], v[56:59]
	v_mfma_f32_16x16x32_bf16 v[48:51], v[166:169], v[174:177], v[48:51]
	v_mfma_f32_16x16x32_bf16 v[40:43], v[158:161], v[182:185], v[40:43]
	v_mfma_f32_16x16x32_bf16 v[32:35], v[166:169], v[182:185], v[32:35]
	v_mfma_f32_16x16x32_bf16 v[24:27], v[158:161], v[202:205], v[24:27]
	v_mfma_f32_16x16x32_bf16 v[16:19], v[166:169], v[202:205], v[16:19]
	v_mfma_f32_16x16x32_bf16 v[8:11], v[158:161], v[210:213], v[8:11]
	v_mfma_f32_16x16x32_bf16 v[0:3], v[166:169], v[210:213], v[0:3]
	v_mfma_f32_16x16x32_bf16 v[56:59], v[162:165], v[178:181], v[56:59]
	v_mfma_f32_16x16x32_bf16 v[48:51], v[170:173], v[178:181], v[48:51]
	v_mfma_f32_16x16x32_bf16 v[40:43], v[162:165], v[198:201], v[40:43]
	v_mfma_f32_16x16x32_bf16 v[32:35], v[170:173], v[198:201], v[32:35]
	v_mfma_f32_16x16x32_bf16 v[24:27], v[162:165], v[206:209], v[24:27]
	v_mfma_f32_16x16x32_bf16 v[16:19], v[170:173], v[206:209], v[16:19]
	v_mfma_f32_16x16x32_bf16 v[8:11], v[162:165], v[214:217], v[8:11]
	v_mfma_f32_16x16x32_bf16 v[0:3], v[170:173], v[214:217], v[0:3]
	s_setprio 0
	s_barrier
	s_add_i32 s44, 0, 0x1c000
	v_add_u32_e32 v154, s95, v143
	v_add_u32_e32 v170, s44, v143
	ds_read_b128 v[138:141], v154
	ds_read_b128 v[146:149], v154 offset:1024
	ds_read_b128 v[150:153], v154 offset:2048
	ds_read_b128 v[154:157], v154 offset:3072
	ds_read_b128 v[158:161], v170
	ds_read_b128 v[162:165], v170 offset:1024
	ds_read_b128 v[166:169], v170 offset:2048
	ds_read_b128 v[170:173], v170 offset:3072
	s_add_u32 s22, s22, 0x40000
	s_addc_u32 s23, s23, 0
	s_mov_b32 m0, s31
	v_lshl_add_u64 v[228:229], s[22:23], 0, v[132:133]
	ds_read_b128 v[174:177], v145 offset:32768
	ds_read_b128 v[178:181], v145 offset:33792
	ds_read_b128 v[182:185], v145 offset:34816
	ds_read_b128 v[198:201], v145 offset:35840
	ds_read_b128 v[202:205], v145 offset:36864
	ds_read_b128 v[206:209], v145 offset:37888
	ds_read_b128 v[210:213], v145 offset:38912
	ds_read_b128 v[214:217], v145 offset:39936
	global_load_lds_dwordx4 v[228:229], off
	v_lshl_add_u64 v[228:229], s[22:23], 0, v[130:131]
	s_mov_b32 m0, s34
	s_nop 0
	global_load_lds_dwordx4 v[228:229], off
	s_nop 0
	s_waitcnt vmcnt(8)
	s_waitcnt lgkmcnt(0)
	s_barrier
	s_setprio 1
	s_waitcnt lgkmcnt(0)
	v_mfma_f32_16x16x32_bf16 v[124:127], v[138:141], v[174:177], v[124:127]
	v_mfma_f32_16x16x32_bf16 v[120:123], v[150:153], v[174:177], v[120:123]
	v_mfma_f32_16x16x32_bf16 v[108:111], v[138:141], v[182:185], v[108:111]
	v_mfma_f32_16x16x32_bf16 v[100:103], v[150:153], v[182:185], v[100:103]
	v_mfma_f32_16x16x32_bf16 v[92:95], v[138:141], v[202:205], v[92:95]
	v_mfma_f32_16x16x32_bf16 v[84:87], v[150:153], v[202:205], v[84:87]
	v_mfma_f32_16x16x32_bf16 v[76:79], v[138:141], v[210:213], v[76:79]
	v_mfma_f32_16x16x32_bf16 v[68:71], v[150:153], v[210:213], v[68:71]
	v_mfma_f32_16x16x32_bf16 v[124:127], v[146:149], v[178:181], v[124:127]
	v_mfma_f32_16x16x32_bf16 v[120:123], v[154:157], v[178:181], v[120:123]
	v_mfma_f32_16x16x32_bf16 v[108:111], v[146:149], v[198:201], v[108:111]
	v_mfma_f32_16x16x32_bf16 v[100:103], v[154:157], v[198:201], v[100:103]
	v_mfma_f32_16x16x32_bf16 v[92:95], v[146:149], v[206:209], v[92:95]
	v_mfma_f32_16x16x32_bf16 v[84:87], v[154:157], v[206:209], v[84:87]
	v_mfma_f32_16x16x32_bf16 v[76:79], v[146:149], v[214:217], v[76:79]
	v_mfma_f32_16x16x32_bf16 v[68:71], v[154:157], v[214:217], v[68:71]
	s_setprio 0
	s_setprio 1
	v_mfma_f32_16x16x32_bf16 v[116:119], v[158:161], v[174:177], v[116:119]
	v_mfma_f32_16x16x32_bf16 v[112:115], v[166:169], v[174:177], v[112:115]
	v_mfma_f32_16x16x32_bf16 v[104:107], v[158:161], v[182:185], v[104:107]
	v_mfma_f32_16x16x32_bf16 v[96:99], v[166:169], v[182:185], v[96:99]
	v_mfma_f32_16x16x32_bf16 v[88:91], v[158:161], v[202:205], v[88:91]
	v_mfma_f32_16x16x32_bf16 v[80:83], v[166:169], v[202:205], v[80:83]
	v_mfma_f32_16x16x32_bf16 v[72:75], v[158:161], v[210:213], v[72:75]
	v_mfma_f32_16x16x32_bf16 v[64:67], v[166:169], v[210:213], v[64:67]
	v_mfma_f32_16x16x32_bf16 v[116:119], v[162:165], v[178:181], v[116:119]
	v_mfma_f32_16x16x32_bf16 v[112:115], v[170:173], v[178:181], v[112:115]
	v_mfma_f32_16x16x32_bf16 v[104:107], v[162:165], v[198:201], v[104:107]
	v_mfma_f32_16x16x32_bf16 v[96:99], v[170:173], v[198:201], v[96:99]
	v_mfma_f32_16x16x32_bf16 v[88:91], v[162:165], v[206:209], v[88:91]
	v_mfma_f32_16x16x32_bf16 v[80:83], v[170:173], v[206:209], v[80:83]
	v_mfma_f32_16x16x32_bf16 v[72:75], v[162:165], v[214:217], v[72:75]
	v_mfma_f32_16x16x32_bf16 v[64:67], v[170:173], v[214:217], v[64:67]
	s_setprio 0
	s_barrier
; #define PG8_STAGE(bufoff, gbase, voff) do { _Pragma("unroll") for (int _i = 0; _i < 2; ++_i) \
;         __builtin_amdgcn_global_load_lds((const unsigned*)((const char*)(gbase) + (voff)[_i]), (LAS unsigned*)(lds + (bufoff) + ldsw + _i * 8192), 16, 0, 0); } while (0)
; #define PG8_LDA(dst, b, h) do { _Pragma("unroll") for (int m = 0; m < 4; ++m) _Pragma("unroll") for (int k = 0; k < 2; ++k) dst[m][k] = *(const LAS bf16x8*)(lds + PG8_SA(b, h) + aoff + m * 2048 + k * 1024); } while (0)
; #define PG8_MMA(ai, bj, At, Bt) do { __builtin_amdgcn_s_setprio(1); _Pragma("unroll") for (int m = 0; m < 4; ++m) _Pragma("unroll") for (int n = 0; n < 2; ++n) _Pragma("unroll") for (int k = 0; k < 2; ++k) \
;         acc[ai][bj][m][n] = __builtin_amdgcn_mfma_f32_16x16x32_bf16(Bt[n][k], At[m][k], acc[ai][bj][m][n], 0, 0, 0); __builtin_amdgcn_s_setprio(0); } while (0)
; #define PG8_WAIT_V(n) asm volatile("s_waitcnt vmcnt(" #n ")" ::: "memory")
; #define PG8_WAIT_L(n) asm volatile("s_waitcnt lgkmcnt(" #n ")" ::: "memory")
; #define PG8_BAR __builtin_amdgcn_s_barrier()
; #define PG8_SCHED __builtin_amdgcn_sched_barrier(0)
; template <class Epi, class Sched>
; __device__ __forceinline__ void gemm_phase(int wv, LAS unsigned char* lds, const Gemm g, const Sched& S, const Epi& E) {
;     ...
;             PG8_LDA(At, 1, 1); PG8_STAGE(PG8_SB(1, 0), b3, voffB); PG8_STAGE(PG8_SB(1, 1), b3 + hstepB, voffB); PG8_STAGE(PG8_SA(1, 0), a3, voffA);
;             PG8_WAIT_V(8); PG8_WAIT_L(0); PG8_BAR; PG8_MMA(1, 0, At, B0); PG8_MMA(1, 1, At, B1); PG8_BAR; PG8_SCHED;
;         }
;         if (wr == 0) PG8_BAR;
	s_add_i32 s22, s95, s28
	v_lshl_add_u64 v[186:187], v[186:187], 0, s[74:75]
	s_mov_b32 m0, s22
	ds_read_b128 v[174:177], v145 offset:49152
	ds_read_b128 v[178:181], v145 offset:50176
	ds_read_b128 v[182:185], v145 offset:51200
	ds_read_b128 v[198:201], v145 offset:52224
	ds_read_b128 v[202:205], v145 offset:53248
	ds_read_b128 v[206:209], v145 offset:54272
	ds_read_b128 v[210:213], v145 offset:55296
	ds_read_b128 v[214:217], v145 offset:56320
	global_load_lds_dwordx4 v[186:187], off
	s_add_i32 m0, s22, 0x2000
	s_add_u32 s20, s20, 0x40080
	v_lshl_add_u64 v[186:187], v[218:219], 0, s[74:75]
	s_addc_u32 s21, s21, 0
	s_add_i32 s22, s44, s28
	global_load_lds_dwordx4 v[186:187], off
	v_lshl_add_u64 v[186:187], s[20:21], 0, v[188:189]
	s_mov_b32 m0, s22
	s_nop 0
	global_load_lds_dwordx4 v[186:187], off
	v_lshl_add_u64 v[186:187], s[20:21], 0, v[128:129]
	s_add_i32 m0, s22, 0x2000
	s_nop 0
	global_load_lds_dwordx4 v[186:187], off
	v_lshl_add_u64 v[186:187], v[220:221], 0, s[74:75]
	s_mov_b32 m0, s35
	s_nop 0
	global_load_lds_dwordx4 v[186:187], off
	v_lshl_add_u64 v[186:187], v[222:223], 0, s[74:75]
	s_mov_b32 m0, s36
	s_nop 0
	global_load_lds_dwordx4 v[186:187], off
	s_waitcnt vmcnt(8)
	s_waitcnt lgkmcnt(0)
	s_barrier
	s_setprio 1
	s_waitcnt lgkmcnt(0)
	v_mfma_f32_16x16x32_bf16 v[60:63], v[138:141], v[174:177], v[60:63]
	v_mfma_f32_16x16x32_bf16 v[52:55], v[150:153], v[174:177], v[52:55]
	v_mfma_f32_16x16x32_bf16 v[44:47], v[138:141], v[182:185], v[44:47]
	v_mfma_f32_16x16x32_bf16 v[36:39], v[150:153], v[182:185], v[36:39]
	v_mfma_f32_16x16x32_bf16 v[28:31], v[138:141], v[202:205], v[28:31]
	v_mfma_f32_16x16x32_bf16 v[20:23], v[150:153], v[202:205], v[20:23]
	v_mfma_f32_16x16x32_bf16 v[12:15], v[138:141], v[210:213], v[12:15]
	v_mfma_f32_16x16x32_bf16 v[4:7], v[150:153], v[210:213], v[4:7]
	v_mfma_f32_16x16x32_bf16 v[60:63], v[146:149], v[178:181], v[60:63]
	v_mfma_f32_16x16x32_bf16 v[52:55], v[154:157], v[178:181], v[52:55]
	v_mfma_f32_16x16x32_bf16 v[44:47], v[146:149], v[198:201], v[44:47]
	v_mfma_f32_16x16x32_bf16 v[36:39], v[154:157], v[198:201], v[36:39]
	v_mfma_f32_16x16x32_bf16 v[28:31], v[146:149], v[206:209], v[28:31]
	v_mfma_f32_16x16x32_bf16 v[20:23], v[154:157], v[206:209], v[20:23]
	v_mfma_f32_16x16x32_bf16 v[12:15], v[146:149], v[214:217], v[12:15]
	v_mfma_f32_16x16x32_bf16 v[4:7], v[154:157], v[214:217], v[4:7]
	s_setprio 0
	s_setprio 1
	v_mfma_f32_16x16x32_bf16 v[56:59], v[158:161], v[174:177], v[56:59]
	v_mfma_f32_16x16x32_bf16 v[48:51], v[166:169], v[174:177], v[48:51]
	v_mfma_f32_16x16x32_bf16 v[40:43], v[158:161], v[182:185], v[40:43]
	v_mfma_f32_16x16x32_bf16 v[32:35], v[166:169], v[182:185], v[32:35]
	v_mfma_f32_16x16x32_bf16 v[24:27], v[158:161], v[202:205], v[24:27]
	v_mfma_f32_16x16x32_bf16 v[16:19], v[166:169], v[202:205], v[16:19]
	v_mfma_f32_16x16x32_bf16 v[8:11], v[158:161], v[210:213], v[8:11]
	v_mfma_f32_16x16x32_bf16 v[0:3], v[166:169], v[210:213], v[0:3]
	v_mfma_f32_16x16x32_bf16 v[56:59], v[162:165], v[178:181], v[56:59]
	v_mfma_f32_16x16x32_bf16 v[48:51], v[170:173], v[178:181], v[48:51]
	v_mfma_f32_16x16x32_bf16 v[40:43], v[162:165], v[198:201], v[40:43]
	v_mfma_f32_16x16x32_bf16 v[32:35], v[170:173], v[198:201], v[32:35]
	v_mfma_f32_16x16x32_bf16 v[24:27], v[162:165], v[206:209], v[24:27]
	v_mfma_f32_16x16x32_bf16 v[16:19], v[170:173], v[206:209], v[16:19]
	v_mfma_f32_16x16x32_bf16 v[8:11], v[162:165], v[214:217], v[8:11]
	v_mfma_f32_16x16x32_bf16 v[0:3], v[170:173], v[214:217], v[0:3]
	s_setprio 0
	s_barrier
	s_add_i32 s43, s43, 2
	s_add_u32 s18, s18, 0x100
	s_addc_u32 s19, s19, 0
	s_add_u32 s41, s41, 0x100
	s_addc_u32 s42, s42, 0
	s_cmp_gt_u32 s43, 13
	s_cbranch_scc0 .LBB0_978
	s_and_b64 vcc, exec, s[8:9]
	s_cbranch_vccz .LBB0_981
	s_barrier

; #define PG8_STAGE(bufoff, gbase, voff) do { _Pragma("unroll") for (int _i = 0; _i < 2; ++_i) \
;         __builtin_amdgcn_global_load_lds((const unsigned*)((const char*)(gbase) + (voff)[_i]), (LAS unsigned*)(lds + (bufoff) + ldsw + _i * 8192), 16, 0, 0); } while (0)
; #define PG8_LDA(dst, b, h) do { _Pragma("unroll") for (int m = 0; m < 4; ++m) _Pragma("unroll") for (int k = 0; k < 2; ++k) dst[m][k] = *(const LAS bf16x8*)(lds + PG8_SA(b, h) + aoff + m * 2048 + k * 1024); } while (0)
; #define PG8_LDB(dst, b, h) do { _Pragma("unroll") for (int n = 0; n < 2; ++n) _Pragma("unroll") for (int k = 0; k < 2; ++k) dst[n][k] = *(const LAS bf16x8*)(lds + PG8_SB(b, h) + boff + n * 2048 + k * 1024); } while (0)
; #define PG8_MMA(ai, bj, At, Bt) do { __builtin_amdgcn_s_setprio(1); _Pragma("unroll") for (int m = 0; m < 4; ++m) _Pragma("unroll") for (int n = 0; n < 2; ++n) _Pragma("unroll") for (int k = 0; k < 2; ++k) \
;         acc[ai][bj][m][n] = __builtin_amdgcn_mfma_f32_16x16x32_bf16(Bt[n][k], At[m][k], acc[ai][bj][m][n], 0, 0, 0); __builtin_amdgcn_s_setprio(0); } while (0)
; #define PG8_WAIT_V(n) asm volatile("s_waitcnt vmcnt(" #n ")" ::: "memory")
; #define PG8_WAIT_L(n) asm volatile("s_waitcnt lgkmcnt(" #n ")" ::: "memory")
; #define PG8_BAR __builtin_amdgcn_s_barrier()
; #define PG8_SCHED __builtin_amdgcn_sched_barrier(0)
; template <class Epi, class Sched>
; __device__ __forceinline__ void gemm_phase(int wv, LAS unsigned char* lds, const Gemm g, const Sched& S, const Epi& E) {
;     ...
;         for (int t = 0; t < nt; t += 2) {
;             const bool last = (t == nt - 2);
;             const char* a1 = cA + (size_t)(t + 1) * kstep;
;             const char* a2 = last ? nA : cA + (size_t)(t + 2) * kstep; const char* b2 = last ? nB : cB + (size_t)(t + 2) * kstep;
;             const char* a3 = a2 + kstep; const char* b3 = b2 + kstep;
;             PG8_LDB(B0, 0, 0); PG8_LDB(B1, 0, 1); PG8_SCHED; PG8_LDA(At, 0, 0); PG8_STAGE(PG8_SA(1, 1), a1 + hstep, voffA);
;             PG8_WAIT_V(8); PG8_WAIT_L(0); PG8_BAR; PG8_MMA(0, 0, At, B0); PG8_MMA(0, 1, At, B1); PG8_BAR; PG8_SCHED;
;             PG8_LDA(At, 0, 1); PG8_STAGE(PG8_SB(0, 0), b2, voffB); PG8_STAGE(PG8_SB(0, 1), b2 + hstepB, voffB); PG8_STAGE(PG8_SA(0, 0), a2, voffA);
;             PG8_WAIT_V(8); PG8_WAIT_L(0); PG8_BAR; PG8_MMA(1, 0, At, B0); PG8_MMA(1, 1, At, B1); PG8_BAR; PG8_SCHED;
.LBB0_1055:
	s_add_u32 s4, s22, 0x100
	s_addc_u32 s5, s23, 0
	s_add_i32 s48, 0, 0x10000
	s_cmp_eq_u32 s47, 40
	s_cselect_b32 s27, s19, s5
	s_cselect_b32 s26, s18, s4
	s_cselect_b32 s25, s21, s46
	s_cselect_b32 s24, s20, s45
	s_add_i32 s49, 0, 0x14000
	v_add_u32_e32 v136, s48, v213
	v_add_u32_e32 v156, s49, v213
	ds_read_b128 v[96:99], v136
	ds_read_b128 v[100:103], v136 offset:1024
	ds_read_b128 v[104:107], v136 offset:2048
	ds_read_b128 v[136:139], v136 offset:3072
	ds_read_b128 v[140:143], v156
	ds_read_b128 v[144:147], v156 offset:1024
	ds_read_b128 v[152:155], v156 offset:2048
	ds_read_b128 v[156:159], v156 offset:3072
	v_lshl_add_u64 v[186:187], s[22:23], 0, v[182:183]
	s_add_i32 m0, s35, 0xc000
	ds_read_b128 v[160:163], v217
	ds_read_b128 v[164:167], v217 offset:1024
	ds_read_b128 v[168:171], v217 offset:2048
	ds_read_b128 v[172:175], v217 offset:3072
	ds_read_b128 v[198:201], v217 offset:4096
	ds_read_b128 v[202:205], v217 offset:5120
	ds_read_b128 v[206:209], v217 offset:6144
	ds_read_b128 v[218:221], v217 offset:7168
	global_load_lds_dwordx4 v[186:187], off
	v_lshl_add_u64 v[186:187], s[22:23], 0, v[184:185]
	s_add_i32 m0, s35, 0xe000
	s_nop 0
	global_load_lds_dwordx4 v[186:187], off
	s_nop 0
	s_waitcnt vmcnt(8)
	s_waitcnt lgkmcnt(0)
	s_barrier
	s_setprio 1
	s_waitcnt lgkmcnt(0)
	v_mfma_f32_16x16x32_bf16 v[148:151], v[96:99], v[160:163], v[148:151]
	v_mfma_f32_16x16x32_bf16 v[124:127], v[104:107], v[160:163], v[124:127]
	v_mfma_f32_16x16x32_bf16 v[132:135], v[96:99], v[168:171], v[132:135]
	v_mfma_f32_16x16x32_bf16 v[128:131], v[104:107], v[168:171], v[128:131]
	v_mfma_f32_16x16x32_bf16 v[92:95], v[96:99], v[198:201], v[92:95]
	v_mfma_f32_16x16x32_bf16 v[88:91], v[104:107], v[198:201], v[88:91]
	v_mfma_f32_16x16x32_bf16 v[76:79], v[96:99], v[206:209], v[76:79]
	v_mfma_f32_16x16x32_bf16 v[72:75], v[104:107], v[206:209], v[72:75]
	v_mfma_f32_16x16x32_bf16 v[148:151], v[100:103], v[164:167], v[148:151]
	v_mfma_f32_16x16x32_bf16 v[124:127], v[136:139], v[164:167], v[124:127]
	v_mfma_f32_16x16x32_bf16 v[132:135], v[100:103], v[172:175], v[132:135]
	v_mfma_f32_16x16x32_bf16 v[128:131], v[136:139], v[172:175], v[128:131]
	v_mfma_f32_16x16x32_bf16 v[92:95], v[100:103], v[202:205], v[92:95]
	v_mfma_f32_16x16x32_bf16 v[88:91], v[136:139], v[202:205], v[88:91]
	v_mfma_f32_16x16x32_bf16 v[76:79], v[100:103], v[218:221], v[76:79]
	v_mfma_f32_16x16x32_bf16 v[72:75], v[136:139], v[218:221], v[72:75]
	s_setprio 0
	s_setprio 1
	v_mfma_f32_16x16x32_bf16 v[116:119], v[140:143], v[160:163], v[116:119]
	v_mfma_f32_16x16x32_bf16 v[108:111], v[152:155], v[160:163], v[108:111]
	v_mfma_f32_16x16x32_bf16 v[120:123], v[140:143], v[168:171], v[120:123]
	v_mfma_f32_16x16x32_bf16 v[112:115], v[152:155], v[168:171], v[112:115]
	v_mfma_f32_16x16x32_bf16 v[84:87], v[140:143], v[198:201], v[84:87]
	v_mfma_f32_16x16x32_bf16 v[80:83], v[152:155], v[198:201], v[80:83]
	v_mfma_f32_16x16x32_bf16 v[68:71], v[140:143], v[206:209], v[68:71]
	v_mfma_f32_16x16x32_bf16 v[64:67], v[152:155], v[206:209], v[64:67]
	v_mfma_f32_16x16x32_bf16 v[116:119], v[144:147], v[164:167], v[116:119]
	v_mfma_f32_16x16x32_bf16 v[108:111], v[156:159], v[164:167], v[108:111]
	v_mfma_f32_16x16x32_bf16 v[120:123], v[144:147], v[172:175], v[120:123]
	v_mfma_f32_16x16x32_bf16 v[112:115], v[156:159], v[172:175], v[112:115]
	v_mfma_f32_16x16x32_bf16 v[84:87], v[144:147], v[202:205], v[84:87]
	v_mfma_f32_16x16x32_bf16 v[80:83], v[156:159], v[202:205], v[80:83]
	v_mfma_f32_16x16x32_bf16 v[68:71], v[144:147], v[218:221], v[68:71]
	v_mfma_f32_16x16x32_bf16 v[64:67], v[156:159], v[218:221], v[64:67]
	s_setprio 0
	s_barrier
	s_add_i32 s22, s48, s34
	v_lshl_add_u64 v[186:187], s[24:25], 0, v[188:189]
	s_mov_b32 m0, s22
	ds_read_b128 v[160:163], v217 offset:16384
	ds_read_b128 v[164:167], v217 offset:17408
	ds_read_b128 v[168:171], v217 offset:18432
	ds_read_b128 v[172:175], v217 offset:19456
	ds_read_b128 v[198:201], v217 offset:20480
	ds_read_b128 v[202:205], v217 offset:21504
	ds_read_b128 v[206:209], v217 offset:22528
	ds_read_b128 v[218:221], v217 offset:23552
	global_load_lds_dwordx4 v[186:187], off
	s_add_i32 m0, s22, 0x2000
	s_add_u32 s22, s24, 0xb000
	v_lshl_add_u64 v[210:211], s[24:25], 0, v[176:177]
	s_addc_u32 s23, s25, 0
	s_add_i32 s48, s49, s34
	global_load_lds_dwordx4 v[210:211], off
	v_lshl_add_u64 v[222:223], s[22:23], 0, v[188:189]
	s_mov_b32 m0, s48
	v_lshl_add_u64 v[228:229], s[26:27], 0, v[178:179]
	global_load_lds_dwordx4 v[222:223], off
	v_lshl_add_u64 v[222:223], s[22:23], 0, v[176:177]
	s_add_i32 m0, s48, 0x2000
	s_nop 0
	global_load_lds_dwordx4 v[222:223], off
	v_lshl_add_u64 v[222:223], s[26:27], 0, v[180:181]
	s_mov_b32 m0, s35
	s_nop 0
	global_load_lds_dwordx4 v[222:223], off
	s_mov_b32 m0, s36
	s_nop 0
	global_load_lds_dwordx4 v[228:229], off
	s_nop 0
	s_waitcnt vmcnt(8)
	s_waitcnt lgkmcnt(0)
	s_barrier
; #define PG8_STAGE(bufoff, gbase, voff) do { _Pragma("unroll") for (int _i = 0; _i < 2; ++_i) \
;         __builtin_amdgcn_global_load_lds((const unsigned*)((const char*)(gbase) + (voff)[_i]), (LAS unsigned*)(lds + (bufoff) + ldsw + _i * 8192), 16, 0, 0); } while (0)
; #define PG8_LDA(dst, b, h) do { _Pragma("unroll") for (int m = 0; m < 4; ++m) _Pragma("unroll") for (int k = 0; k < 2; ++k) dst[m][k] = *(const LAS bf16x8*)(lds + PG8_SA(b, h) + aoff + m * 2048 + k * 1024); } while (0)
; #define PG8_LDB(dst, b, h) do { _Pragma("unroll") for (int n = 0; n < 2; ++n) _Pragma("unroll") for (int k = 0; k < 2; ++k) dst[n][k] = *(const LAS bf16x8*)(lds + PG8_SB(b, h) + boff + n * 2048 + k * 1024); } while (0)
; #define PG8_MMA(ai, bj, At, Bt) do { __builtin_amdgcn_s_setprio(1); _Pragma("unroll") for (int m = 0; m < 4; ++m) _Pragma("unroll") for (int n = 0; n < 2; ++n) _Pragma("unroll") for (int k = 0; k < 2; ++k) \
;         acc[ai][bj][m][n] = __builtin_amdgcn_mfma_f32_16x16x32_bf16(Bt[n][k], At[m][k], acc[ai][bj][m][n], 0, 0, 0); __builtin_amdgcn_s_setprio(0); } while (0)
; #define PG8_WAIT_V(n) asm volatile("s_waitcnt vmcnt(" #n ")" ::: "memory")
; #define PG8_WAIT_L(n) asm volatile("s_waitcnt lgkmcnt(" #n ")" ::: "memory")
; #define PG8_BAR __builtin_amdgcn_s_barrier()
; #define PG8_SCHED __builtin_amdgcn_sched_barrier(0)
; template <class Epi, class Sched>
; __device__ __forceinline__ void gemm_phase(int wv, LAS unsigned char* lds, const Gemm g, const Sched& S, const Epi& E) {
;     ...
;             PG8_WAIT_V(8); PG8_WAIT_L(0); PG8_BAR; PG8_MMA(1, 0, At, B0); PG8_MMA(1, 1, At, B1); PG8_BAR; PG8_SCHED;
;             PG8_LDB(B0, 1, 0); PG8_LDB(B1, 1, 1); PG8_SCHED; PG8_LDA(At, 1, 0); PG8_STAGE(PG8_SA(0, 1), a2 + hstep, voffA);
;             PG8_WAIT_V(8); PG8_WAIT_L(0); PG8_BAR; PG8_MMA(0, 0, At, B0); PG8_MMA(0, 1, At, B1); PG8_BAR; PG8_SCHED;
	s_setprio 1
	s_waitcnt lgkmcnt(0)
	v_mfma_f32_16x16x32_bf16 v[60:63], v[96:99], v[160:163], v[60:63]
	v_mfma_f32_16x16x32_bf16 v[56:59], v[104:107], v[160:163], v[56:59]
	v_mfma_f32_16x16x32_bf16 v[44:47], v[96:99], v[168:171], v[44:47]
	v_mfma_f32_16x16x32_bf16 v[40:43], v[104:107], v[168:171], v[40:43]
	v_mfma_f32_16x16x32_bf16 v[28:31], v[96:99], v[198:201], v[28:31]
	v_mfma_f32_16x16x32_bf16 v[24:27], v[104:107], v[198:201], v[24:27]
	v_mfma_f32_16x16x32_bf16 v[12:15], v[96:99], v[206:209], v[12:15]
	v_mfma_f32_16x16x32_bf16 v[8:11], v[104:107], v[206:209], v[8:11]
	v_mfma_f32_16x16x32_bf16 v[60:63], v[100:103], v[164:167], v[60:63]
	v_mfma_f32_16x16x32_bf16 v[56:59], v[136:139], v[164:167], v[56:59]
	v_mfma_f32_16x16x32_bf16 v[44:47], v[100:103], v[172:175], v[44:47]
	v_mfma_f32_16x16x32_bf16 v[40:43], v[136:139], v[172:175], v[40:43]
	v_mfma_f32_16x16x32_bf16 v[28:31], v[100:103], v[202:205], v[28:31]
	v_mfma_f32_16x16x32_bf16 v[24:27], v[136:139], v[202:205], v[24:27]
	v_mfma_f32_16x16x32_bf16 v[12:15], v[100:103], v[218:221], v[12:15]
	v_mfma_f32_16x16x32_bf16 v[8:11], v[136:139], v[218:221], v[8:11]
	s_setprio 0
	s_setprio 1
	v_mfma_f32_16x16x32_bf16 v[52:55], v[140:143], v[160:163], v[52:55]
	v_mfma_f32_16x16x32_bf16 v[48:51], v[152:155], v[160:163], v[48:51]
	v_mfma_f32_16x16x32_bf16 v[36:39], v[140:143], v[168:171], v[36:39]
	v_mfma_f32_16x16x32_bf16 v[32:35], v[152:155], v[168:171], v[32:35]
	v_mfma_f32_16x16x32_bf16 v[20:23], v[140:143], v[198:201], v[20:23]
	v_mfma_f32_16x16x32_bf16 v[16:19], v[152:155], v[198:201], v[16:19]
	v_mfma_f32_16x16x32_bf16 v[4:7], v[140:143], v[206:209], v[4:7]
	v_mfma_f32_16x16x32_bf16 v[0:3], v[152:155], v[206:209], v[0:3]
	v_mfma_f32_16x16x32_bf16 v[52:55], v[144:147], v[164:167], v[52:55]
	v_mfma_f32_16x16x32_bf16 v[48:51], v[156:159], v[164:167], v[48:51]
	v_mfma_f32_16x16x32_bf16 v[36:39], v[144:147], v[172:175], v[36:39]
	v_mfma_f32_16x16x32_bf16 v[32:35], v[156:159], v[172:175], v[32:35]
	v_mfma_f32_16x16x32_bf16 v[20:23], v[144:147], v[202:205], v[20:23]
	v_mfma_f32_16x16x32_bf16 v[16:19], v[156:159], v[202:205], v[16:19]
	v_mfma_f32_16x16x32_bf16 v[4:7], v[144:147], v[218:221], v[4:7]
	v_mfma_f32_16x16x32_bf16 v[0:3], v[156:159], v[218:221], v[0:3]
	s_setprio 0
	s_barrier
	s_add_i32 s48, 0, 0x1c000
	v_add_u32_e32 v136, s95, v213
	v_add_u32_e32 v156, s48, v213
	ds_read_b128 v[96:99], v136
	ds_read_b128 v[100:103], v136 offset:1024
	ds_read_b128 v[104:107], v136 offset:2048
	ds_read_b128 v[136:139], v136 offset:3072
	ds_read_b128 v[140:143], v156
	ds_read_b128 v[144:147], v156 offset:1024
	ds_read_b128 v[152:155], v156 offset:2048
	ds_read_b128 v[156:159], v156 offset:3072
	s_add_u32 s22, s26, 0xb0000
	s_addc_u32 s23, s27, 0
	s_mov_b32 m0, s37
	v_lshl_add_u64 v[230:231], s[22:23], 0, v[180:181]
	ds_read_b128 v[160:163], v217 offset:32768
	ds_read_b128 v[164:167], v217 offset:33792
	ds_read_b128 v[168:171], v217 offset:34816
	ds_read_b128 v[172:175], v217 offset:35840
	ds_read_b128 v[198:201], v217 offset:36864
	ds_read_b128 v[202:205], v217 offset:37888
	ds_read_b128 v[206:209], v217 offset:38912
	ds_read_b128 v[218:221], v217 offset:39936
	global_load_lds_dwordx4 v[230:231], off
	v_lshl_add_u64 v[230:231], s[22:23], 0, v[178:179]
	s_mov_b32 m0, s38
	s_nop 0
	global_load_lds_dwordx4 v[230:231], off
	s_nop 0
	s_waitcnt vmcnt(8)
	s_waitcnt lgkmcnt(0)
	s_barrier
	s_setprio 1
	s_waitcnt lgkmcnt(0)
	v_mfma_f32_16x16x32_bf16 v[148:151], v[96:99], v[160:163], v[148:151]
	v_mfma_f32_16x16x32_bf16 v[124:127], v[104:107], v[160:163], v[124:127]
	v_mfma_f32_16x16x32_bf16 v[132:135], v[96:99], v[168:171], v[132:135]
	v_mfma_f32_16x16x32_bf16 v[128:131], v[104:107], v[168:171], v[128:131]
	v_mfma_f32_16x16x32_bf16 v[92:95], v[96:99], v[198:201], v[92:95]
	v_mfma_f32_16x16x32_bf16 v[88:91], v[104:107], v[198:201], v[88:91]
	v_mfma_f32_16x16x32_bf16 v[76:79], v[96:99], v[206:209], v[76:79]
	v_mfma_f32_16x16x32_bf16 v[72:75], v[104:107], v[206:209], v[72:75]
	v_mfma_f32_16x16x32_bf16 v[148:151], v[100:103], v[164:167], v[148:151]
	v_mfma_f32_16x16x32_bf16 v[124:127], v[136:139], v[164:167], v[124:127]
	v_mfma_f32_16x16x32_bf16 v[132:135], v[100:103], v[172:175], v[132:135]
	v_mfma_f32_16x16x32_bf16 v[128:131], v[136:139], v[172:175], v[128:131]
	v_mfma_f32_16x16x32_bf16 v[92:95], v[100:103], v[202:205], v[92:95]
	v_mfma_f32_16x16x32_bf16 v[88:91], v[136:139], v[202:205], v[88:91]
	v_mfma_f32_16x16x32_bf16 v[76:79], v[100:103], v[218:221], v[76:79]
	v_mfma_f32_16x16x32_bf16 v[72:75], v[136:139], v[218:221], v[72:75]
	s_setprio 0
	s_setprio 1
	v_mfma_f32_16x16x32_bf16 v[116:119], v[140:143], v[160:163], v[116:119]
	v_mfma_f32_16x16x32_bf16 v[108:111], v[152:155], v[160:163], v[108:111]
	v_mfma_f32_16x16x32_bf16 v[120:123], v[140:143], v[168:171], v[120:123]
	v_mfma_f32_16x16x32_bf16 v[112:115], v[152:155], v[168:171], v[112:115]
	v_mfma_f32_16x16x32_bf16 v[84:87], v[140:143], v[198:201], v[84:87]
	v_mfma_f32_16x16x32_bf16 v[80:83], v[152:155], v[198:201], v[80:83]
	v_mfma_f32_16x16x32_bf16 v[68:71], v[140:143], v[206:209], v[68:71]
	v_mfma_f32_16x16x32_bf16 v[64:67], v[152:155], v[206:209], v[64:67]
	v_mfma_f32_16x16x32_bf16 v[116:119], v[144:147], v[164:167], v[116:119]
	v_mfma_f32_16x16x32_bf16 v[108:111], v[156:159], v[164:167], v[108:111]
	v_mfma_f32_16x16x32_bf16 v[120:123], v[144:147], v[172:175], v[120:123]
	v_mfma_f32_16x16x32_bf16 v[112:115], v[156:159], v[172:175], v[112:115]
	v_mfma_f32_16x16x32_bf16 v[84:87], v[144:147], v[202:205], v[84:87]
	v_mfma_f32_16x16x32_bf16 v[80:83], v[156:159], v[202:205], v[80:83]
	v_mfma_f32_16x16x32_bf16 v[68:71], v[144:147], v[218:221], v[68:71]
	v_mfma_f32_16x16x32_bf16 v[64:67], v[156:159], v[218:221], v[64:67]
	s_setprio 0
	s_barrier
; #define PG8_STAGE(bufoff, gbase, voff) do { _Pragma("unroll") for (int _i = 0; _i < 2; ++_i) \
;         __builtin_amdgcn_global_load_lds((const unsigned*)((const char*)(gbase) + (voff)[_i]), (LAS unsigned*)(lds + (bufoff) + ldsw + _i * 8192), 16, 0, 0); } while (0)
; #define PG8_LDA(dst, b, h) do { _Pragma("unroll") for (int m = 0; m < 4; ++m) _Pragma("unroll") for (int k = 0; k < 2; ++k) dst[m][k] = *(const LAS bf16x8*)(lds + PG8_SA(b, h) + aoff + m * 2048 + k * 1024); } while (0)
; #define PG8_MMA(ai, bj, At, Bt) do { __builtin_amdgcn_s_setprio(1); _Pragma("unroll") for (int m = 0; m < 4; ++m) _Pragma("unroll") for (int n = 0; n < 2; ++n) _Pragma("unroll") for (int k = 0; k < 2; ++k) \
;         acc[ai][bj][m][n] = __builtin_amdgcn_mfma_f32_16x16x32_bf16(Bt[n][k], At[m][k], acc[ai][bj][m][n], 0, 0, 0); __builtin_amdgcn_s_setprio(0); } while (0)
; #define PG8_WAIT_V(n) asm volatile("s_waitcnt vmcnt(" #n ")" ::: "memory")
; #define PG8_WAIT_L(n) asm volatile("s_waitcnt lgkmcnt(" #n ")" ::: "memory")
; #define PG8_BAR __builtin_amdgcn_s_barrier()
; #define PG8_SCHED __builtin_amdgcn_sched_barrier(0)
; template <class Epi, class Sched>
; __device__ __forceinline__ void gemm_phase(int wv, LAS unsigned char* lds, const Gemm g, const Sched& S, const Epi& E) {
;     ...
;             PG8_LDA(At, 1, 1); PG8_STAGE(PG8_SB(1, 0), b3, voffB); PG8_STAGE(PG8_SB(1, 1), b3 + hstepB, voffB); PG8_STAGE(PG8_SA(1, 0), a3, voffA);
;             PG8_WAIT_V(8); PG8_WAIT_L(0); PG8_BAR; PG8_MMA(1, 0, At, B0); PG8_MMA(1, 1, At, B1); PG8_BAR; PG8_SCHED;
;         }
;         if (wr == 0) PG8_BAR;
	s_add_i32 s22, s95, s34
	v_lshl_add_u64 v[186:187], v[186:187], 0, s[74:75]
	s_mov_b32 m0, s22
	ds_read_b128 v[160:163], v217 offset:49152
	ds_read_b128 v[164:167], v217 offset:50176
	ds_read_b128 v[168:171], v217 offset:51200
	ds_read_b128 v[172:175], v217 offset:52224
	ds_read_b128 v[198:201], v217 offset:53248
	ds_read_b128 v[202:205], v217 offset:54272
	ds_read_b128 v[206:209], v217 offset:55296
	ds_read_b128 v[218:221], v217 offset:56320
	global_load_lds_dwordx4 v[186:187], off
	s_add_i32 m0, s22, 0x2000
	s_add_u32 s22, s24, 0xb080
	v_lshl_add_u64 v[186:187], v[210:211], 0, s[74:75]
	s_addc_u32 s23, s25, 0
	s_add_i32 s24, s48, s34
	global_load_lds_dwordx4 v[186:187], off
	v_lshl_add_u64 v[186:187], s[22:23], 0, v[188:189]
	s_mov_b32 m0, s24
	s_nop 0
	global_load_lds_dwordx4 v[186:187], off
	v_lshl_add_u64 v[186:187], s[22:23], 0, v[176:177]
	s_add_i32 m0, s24, 0x2000
	s_nop 0
	global_load_lds_dwordx4 v[186:187], off
	v_lshl_add_u64 v[186:187], v[222:223], 0, s[74:75]
	s_mov_b32 m0, s39
	s_nop 0
	global_load_lds_dwordx4 v[186:187], off
	v_lshl_add_u64 v[186:187], v[228:229], 0, s[74:75]
	s_mov_b32 m0, s40
	s_nop 0
	global_load_lds_dwordx4 v[186:187], off
	s_waitcnt vmcnt(8)
	s_waitcnt lgkmcnt(0)
	s_barrier
	s_setprio 1
	s_waitcnt lgkmcnt(0)
	v_mfma_f32_16x16x32_bf16 v[60:63], v[96:99], v[160:163], v[60:63]
	v_mfma_f32_16x16x32_bf16 v[56:59], v[104:107], v[160:163], v[56:59]
	v_mfma_f32_16x16x32_bf16 v[44:47], v[96:99], v[168:171], v[44:47]
	v_mfma_f32_16x16x32_bf16 v[40:43], v[104:107], v[168:171], v[40:43]
	v_mfma_f32_16x16x32_bf16 v[28:31], v[96:99], v[198:201], v[28:31]
	v_mfma_f32_16x16x32_bf16 v[24:27], v[104:107], v[198:201], v[24:27]
	v_mfma_f32_16x16x32_bf16 v[12:15], v[96:99], v[206:209], v[12:15]
	v_mfma_f32_16x16x32_bf16 v[8:11], v[104:107], v[206:209], v[8:11]
	v_mfma_f32_16x16x32_bf16 v[60:63], v[100:103], v[164:167], v[60:63]
	v_mfma_f32_16x16x32_bf16 v[56:59], v[136:139], v[164:167], v[56:59]
	v_mfma_f32_16x16x32_bf16 v[44:47], v[100:103], v[172:175], v[44:47]
	v_mfma_f32_16x16x32_bf16 v[40:43], v[136:139], v[172:175], v[40:43]
	v_mfma_f32_16x16x32_bf16 v[28:31], v[100:103], v[202:205], v[28:31]
	v_mfma_f32_16x16x32_bf16 v[24:27], v[136:139], v[202:205], v[24:27]
	v_mfma_f32_16x16x32_bf16 v[12:15], v[100:103], v[218:221], v[12:15]
	v_mfma_f32_16x16x32_bf16 v[8:11], v[136:139], v[218:221], v[8:11]
	s_setprio 0
	s_setprio 1
	v_mfma_f32_16x16x32_bf16 v[52:55], v[140:143], v[160:163], v[52:55]
	v_mfma_f32_16x16x32_bf16 v[48:51], v[152:155], v[160:163], v[48:51]
	v_mfma_f32_16x16x32_bf16 v[36:39], v[140:143], v[168:171], v[36:39]
	v_mfma_f32_16x16x32_bf16 v[32:35], v[152:155], v[168:171], v[32:35]
	v_mfma_f32_16x16x32_bf16 v[20:23], v[140:143], v[198:201], v[20:23]
	v_mfma_f32_16x16x32_bf16 v[16:19], v[152:155], v[198:201], v[16:19]
	v_mfma_f32_16x16x32_bf16 v[4:7], v[140:143], v[206:209], v[4:7]
	v_mfma_f32_16x16x32_bf16 v[0:3], v[152:155], v[206:209], v[0:3]
	v_mfma_f32_16x16x32_bf16 v[52:55], v[144:147], v[164:167], v[52:55]
	v_mfma_f32_16x16x32_bf16 v[48:51], v[156:159], v[164:167], v[48:51]
	v_mfma_f32_16x16x32_bf16 v[36:39], v[144:147], v[172:175], v[36:39]
	v_mfma_f32_16x16x32_bf16 v[32:35], v[156:159], v[172:175], v[32:35]
	v_mfma_f32_16x16x32_bf16 v[20:23], v[144:147], v[202:205], v[20:23]
	v_mfma_f32_16x16x32_bf16 v[16:19], v[156:159], v[202:205], v[16:19]
	v_mfma_f32_16x16x32_bf16 v[4:7], v[144:147], v[218:221], v[4:7]
	v_mfma_f32_16x16x32_bf16 v[0:3], v[156:159], v[218:221], v[0:3]
	s_setprio 0
	s_barrier
	s_add_i32 s47, s47, 2
	s_add_u32 s45, s45, 0x100
	s_addc_u32 s46, s46, 0
	s_cmp_gt_u32 s47, 41
	s_mov_b64 s[22:23], s[4:5]
	s_cbranch_scc0 .LBB0_1055
	s_and_b64 vcc, exec, s[16:17]
	s_cbranch_vccz .LBB0_1058
	s_barrier
